# GEMM mainloops: the two K-halves of each accumulator issued back to back (D->SrcC forwarding chain) instead of 8 MFMAs apart
# speedup vs baseline: 1.0186x; 1.0186x over previous
; #define PG8_STAGE(bufoff, gbase, voff) do { _Pragma("unroll") for (int _i = 0; _i < 2; ++_i) \
;         __builtin_amdgcn_global_load_lds((const unsigned*)((const char*)(gbase) + (voff)[_i]), (LAS unsigned*)(lds + (bufoff) + ldsw + _i * 8192), 16, 0, 0); } while (0)
; #define PG8_LDA(dst, b, h) do { _Pragma("unroll") for (int m = 0; m < 4; ++m) _Pragma("unroll") for (int k = 0; k < 2; ++k) dst[m][k] = *(const LAS bf16x8*)(lds + PG8_SA(b, h) + aoff + m * 2048 + k * 1024); } while (0)
; #define PG8_LDB(dst, b, h) do { _Pragma("unroll") for (int n = 0; n < 2; ++n) _Pragma("unroll") for (int k = 0; k < 2; ++k) dst[n][k] = *(const LAS bf16x8*)(lds + PG8_SB(b, h) + boff + n * 2048 + k * 1024); } while (0)
; #define PG8_MMA(ai, bj, At, Bt) do { __builtin_amdgcn_s_setprio(1); _Pragma("unroll") for (int m = 0; m < 4; ++m) _Pragma("unroll") for (int n = 0; n < 2; ++n) _Pragma("unroll") for (int k = 0; k < 2; ++k) \
;         acc[ai][bj][m][n] = __builtin_amdgcn_mfma_f32_16x16x32_bf16(Bt[n][k], At[m][k], acc[ai][bj][m][n], 0, 0, 0); __builtin_amdgcn_s_setprio(0); } while (0)
; #define PG8_WAIT_V(n) asm volatile("s_waitcnt vmcnt(" #n ")" ::: "memory")
; #define PG8_WAIT_L(n) asm volatile("s_waitcnt lgkmcnt(" #n ")" ::: "memory")
; #define PG8_BAR __builtin_amdgcn_s_barrier()
; #define PG8_SCHED __builtin_amdgcn_sched_barrier(0)
; template <class EpiT>
; __device__ __forceinline__ void gemm_phase(LAS unsigned char* lds, const Gemm g, const StaticOrder& S, const EpiT& E) {
;     ...
;         for (int t = 0; t < nt; t += 2) {
;             const bool last = (t == nt - 2);
;             const char* a1 = cA + (size_t)(t + 1) * kstep;
;             const char* a2 = last ? nA : cA + (size_t)(t + 2) * kstep; const char* b2 = last ? nB : cB + (size_t)(t + 2) * kstep;
;             const char* a3 = a2 + kstep; const char* b3 = b2 + kstep;
;             PG8_LDB(B0, 0, 0); PG8_LDB(B1, 0, 1); PG8_SCHED; PG8_LDA(At, 0, 0); PG8_STAGE(PG8_SA(1, 1), a1 + hstepA, voffA);
;             PG8_WAIT_V(8); PG8_WAIT_L(0); PG8_BAR; PG8_MMA(0, 0, At, B0); PG8_MMA(0, 1, At, B1); PG8_BAR; PG8_SCHED;
;             PG8_LDA(At, 0, 1); PG8_STAGE(PG8_SB(0, 0), b2, voffB); PG8_STAGE(PG8_SB(0, 1), b2 + hstepB, voffB); PG8_STAGE(PG8_SA(0, 0), a2, voffA);
.LBB0_100:
	ds_read_b128 v[128:131], v160
	ds_read_b128 v[170:173], v160 offset:1024
	ds_read_b128 v[174:177], v160 offset:2048
	ds_read_b128 v[178:181], v160 offset:3072
	ds_read_b128 v[182:185], v161
	ds_read_b128 v[186:189], v161 offset:1024
	ds_read_b128 v[190:193], v161 offset:2048
	ds_read_b128 v[194:197], v161 offset:3072
	s_add_u32 s18, s16, 0xfff7c080
	s_addc_u32 s19, s17, -1
	s_cmp_eq_u32 s53, 28
	s_cselect_b32 s21, s3, s19
	s_cselect_b32 s20, s2, s18
	s_cselect_b32 s19, s15, s52
	s_cselect_b32 s18, s14, s51
	v_lshl_add_u64 v[158:159], s[16:17], 0, v[150:151]
	s_add_i32 m0, s35, 0xc000
	ds_read_b128 v[198:201], v162
	ds_read_b128 v[202:205], v162 offset:1024
	ds_read_b128 v[206:209], v162 offset:2048
	ds_read_b128 v[210:213], v162 offset:3072
	ds_read_b128 v[214:217], v162 offset:4096
	ds_read_b128 v[218:221], v162 offset:5120
	ds_read_b128 v[222:225], v162 offset:6144
	ds_read_b128 v[226:229], v162 offset:7168
	global_load_lds_dwordx4 v[158:159], off
	v_lshl_add_u64 v[158:159], s[16:17], 0, v[152:153]
	s_add_i32 m0, s35, 0xe000
	s_nop 0
	global_load_lds_dwordx4 v[158:159], off
	s_waitcnt vmcnt(8)
	s_waitcnt lgkmcnt(0)
	s_barrier
	s_setprio 1
	s_waitcnt lgkmcnt(0)
	v_mfma_f32_16x16x32_bf16 v[124:127], v[128:131], v[198:201], v[124:127]
	v_mfma_f32_16x16x32_bf16 v[124:127], v[170:173], v[202:205], v[124:127]
	v_mfma_f32_16x16x32_bf16 v[120:123], v[174:177], v[198:201], v[120:123]
	v_mfma_f32_16x16x32_bf16 v[120:123], v[178:181], v[202:205], v[120:123]
	v_mfma_f32_16x16x32_bf16 v[108:111], v[128:131], v[206:209], v[108:111]
	v_mfma_f32_16x16x32_bf16 v[108:111], v[170:173], v[210:213], v[108:111]
	v_mfma_f32_16x16x32_bf16 v[104:107], v[174:177], v[206:209], v[104:107]
	v_mfma_f32_16x16x32_bf16 v[104:107], v[178:181], v[210:213], v[104:107]
	v_mfma_f32_16x16x32_bf16 v[92:95], v[128:131], v[214:217], v[92:95]
	v_mfma_f32_16x16x32_bf16 v[92:95], v[170:173], v[218:221], v[92:95]
	v_mfma_f32_16x16x32_bf16 v[88:91], v[174:177], v[214:217], v[88:91]
	v_mfma_f32_16x16x32_bf16 v[88:91], v[178:181], v[218:221], v[88:91]
	v_mfma_f32_16x16x32_bf16 v[76:79], v[128:131], v[222:225], v[76:79]
	v_mfma_f32_16x16x32_bf16 v[76:79], v[170:173], v[226:229], v[76:79]
	v_mfma_f32_16x16x32_bf16 v[72:75], v[174:177], v[222:225], v[72:75]
	v_mfma_f32_16x16x32_bf16 v[72:75], v[178:181], v[226:229], v[72:75]
	s_setprio 0
	s_setprio 1
	v_mfma_f32_16x16x32_bf16 v[116:119], v[182:185], v[198:201], v[116:119]
	v_mfma_f32_16x16x32_bf16 v[116:119], v[186:189], v[202:205], v[116:119]
	v_mfma_f32_16x16x32_bf16 v[112:115], v[190:193], v[198:201], v[112:115]
	v_mfma_f32_16x16x32_bf16 v[112:115], v[194:197], v[202:205], v[112:115]
	v_mfma_f32_16x16x32_bf16 v[100:103], v[182:185], v[206:209], v[100:103]
	v_mfma_f32_16x16x32_bf16 v[100:103], v[186:189], v[210:213], v[100:103]
	v_mfma_f32_16x16x32_bf16 v[96:99], v[190:193], v[206:209], v[96:99]
	v_mfma_f32_16x16x32_bf16 v[96:99], v[194:197], v[210:213], v[96:99]
	v_mfma_f32_16x16x32_bf16 v[84:87], v[182:185], v[214:217], v[84:87]
	v_mfma_f32_16x16x32_bf16 v[84:87], v[186:189], v[218:221], v[84:87]
	v_mfma_f32_16x16x32_bf16 v[80:83], v[190:193], v[214:217], v[80:83]
	v_mfma_f32_16x16x32_bf16 v[80:83], v[194:197], v[218:221], v[80:83]
	v_mfma_f32_16x16x32_bf16 v[68:71], v[182:185], v[222:225], v[68:71]
	v_mfma_f32_16x16x32_bf16 v[68:71], v[186:189], v[226:229], v[68:71]
	v_mfma_f32_16x16x32_bf16 v[64:67], v[190:193], v[222:225], v[64:67]
	v_mfma_f32_16x16x32_bf16 v[64:67], v[194:197], v[226:229], v[64:67]
	s_setprio 0
	s_barrier
	s_add_i32 s54, s43, s25
	v_lshl_add_u64 v[158:159], s[18:19], 0, v[136:137]
	s_mov_b32 m0, s54
	ds_read_b128 v[198:201], v162 offset:16384
	ds_read_b128 v[202:205], v162 offset:17408
	ds_read_b128 v[206:209], v162 offset:18432
	ds_read_b128 v[210:213], v162 offset:19456
	ds_read_b128 v[214:217], v162 offset:20480
	ds_read_b128 v[218:221], v162 offset:21504
	ds_read_b128 v[222:225], v162 offset:22528
	ds_read_b128 v[226:229], v162 offset:23552
	global_load_lds_dwordx4 v[158:159], off
	s_add_i32 m0, s54, 0x2000
	s_add_u32 s54, s18, 0x84000
	v_lshl_add_u64 v[166:167], s[18:19], 0, v[132:133]
	s_addc_u32 s55, s19, 0
	s_add_i32 s56, s44, s25
	global_load_lds_dwordx4 v[166:167], off
	v_lshl_add_u64 v[230:231], s[54:55], 0, v[136:137]
	s_mov_b32 m0, s56
	v_lshl_add_u64 v[232:233], s[20:21], 0, v[134:135]
	global_load_lds_dwordx4 v[230:231], off
	v_lshl_add_u64 v[230:231], s[54:55], 0, v[132:133]
	s_add_i32 m0, s56, 0x2000
	s_nop 0
	global_load_lds_dwordx4 v[230:231], off
	v_lshl_add_u64 v[230:231], s[20:21], 0, v[138:139]
	s_mov_b32 m0, s35
	s_nop 0
	global_load_lds_dwordx4 v[230:231], off
	s_mov_b32 m0, s36
	s_nop 0
	global_load_lds_dwordx4 v[232:233], off
	s_waitcnt vmcnt(8)
	s_waitcnt lgkmcnt(0)
	s_barrier
; #define PG8_STAGE(bufoff, gbase, voff) do { _Pragma("unroll") for (int _i = 0; _i < 2; ++_i) \
;         __builtin_amdgcn_global_load_lds((const unsigned*)((const char*)(gbase) + (voff)[_i]), (LAS unsigned*)(lds + (bufoff) + ldsw + _i * 8192), 16, 0, 0); } while (0)
; #define PG8_LDA(dst, b, h) do { _Pragma("unroll") for (int m = 0; m < 4; ++m) _Pragma("unroll") for (int k = 0; k < 2; ++k) dst[m][k] = *(const LAS bf16x8*)(lds + PG8_SA(b, h) + aoff + m * 2048 + k * 1024); } while (0)
; #define PG8_LDB(dst, b, h) do { _Pragma("unroll") for (int n = 0; n < 2; ++n) _Pragma("unroll") for (int k = 0; k < 2; ++k) dst[n][k] = *(const LAS bf16x8*)(lds + PG8_SB(b, h) + boff + n * 2048 + k * 1024); } while (0)
; #define PG8_MMA(ai, bj, At, Bt) do { __builtin_amdgcn_s_setprio(1); _Pragma("unroll") for (int m = 0; m < 4; ++m) _Pragma("unroll") for (int n = 0; n < 2; ++n) _Pragma("unroll") for (int k = 0; k < 2; ++k) \
;         acc[ai][bj][m][n] = __builtin_amdgcn_mfma_f32_16x16x32_bf16(Bt[n][k], At[m][k], acc[ai][bj][m][n], 0, 0, 0); __builtin_amdgcn_s_setprio(0); } while (0)
; #define PG8_WAIT_V(n) asm volatile("s_waitcnt vmcnt(" #n ")" ::: "memory")
; #define PG8_WAIT_L(n) asm volatile("s_waitcnt lgkmcnt(" #n ")" ::: "memory")
; #define PG8_BAR __builtin_amdgcn_s_barrier()
; #define PG8_SCHED __builtin_amdgcn_sched_barrier(0)
; template <class EpiT>
; __device__ __forceinline__ void gemm_phase(LAS unsigned char* lds, const Gemm g, const StaticOrder& S, const EpiT& E) {
;     ...
;             PG8_WAIT_V(8); PG8_WAIT_L(0); PG8_BAR; PG8_MMA(1, 0, At, B0); PG8_MMA(1, 1, At, B1); PG8_BAR; PG8_SCHED;
;             PG8_LDB(B0, 1, 0); PG8_LDB(B1, 1, 1); PG8_SCHED; PG8_LDA(At, 1, 0); PG8_STAGE(PG8_SA(0, 1), a2 + hstepA, voffA);
;             PG8_WAIT_V(8); PG8_WAIT_L(0); PG8_BAR; PG8_MMA(0, 0, At, B0); PG8_MMA(0, 1, At, B1); PG8_BAR; PG8_SCHED;
	s_setprio 1
	s_waitcnt lgkmcnt(0)
	v_mfma_f32_16x16x32_bf16 v[60:63], v[128:131], v[198:201], v[60:63]
	v_mfma_f32_16x16x32_bf16 v[60:63], v[170:173], v[202:205], v[60:63]
	v_mfma_f32_16x16x32_bf16 v[56:59], v[174:177], v[198:201], v[56:59]
	v_mfma_f32_16x16x32_bf16 v[56:59], v[178:181], v[202:205], v[56:59]
	v_mfma_f32_16x16x32_bf16 v[44:47], v[128:131], v[206:209], v[44:47]
	v_mfma_f32_16x16x32_bf16 v[44:47], v[170:173], v[210:213], v[44:47]
	v_mfma_f32_16x16x32_bf16 v[40:43], v[174:177], v[206:209], v[40:43]
	v_mfma_f32_16x16x32_bf16 v[40:43], v[178:181], v[210:213], v[40:43]
	v_mfma_f32_16x16x32_bf16 v[28:31], v[128:131], v[214:217], v[28:31]
	v_mfma_f32_16x16x32_bf16 v[28:31], v[170:173], v[218:221], v[28:31]
	v_mfma_f32_16x16x32_bf16 v[24:27], v[174:177], v[214:217], v[24:27]
	v_mfma_f32_16x16x32_bf16 v[24:27], v[178:181], v[218:221], v[24:27]
	v_mfma_f32_16x16x32_bf16 v[12:15], v[128:131], v[222:225], v[12:15]
	v_mfma_f32_16x16x32_bf16 v[12:15], v[170:173], v[226:229], v[12:15]
	v_mfma_f32_16x16x32_bf16 v[8:11], v[174:177], v[222:225], v[8:11]
	v_mfma_f32_16x16x32_bf16 v[8:11], v[178:181], v[226:229], v[8:11]
	s_setprio 0
	s_setprio 1
	v_mfma_f32_16x16x32_bf16 v[52:55], v[182:185], v[198:201], v[52:55]
	v_mfma_f32_16x16x32_bf16 v[52:55], v[186:189], v[202:205], v[52:55]
	v_mfma_f32_16x16x32_bf16 v[48:51], v[190:193], v[198:201], v[48:51]
	v_mfma_f32_16x16x32_bf16 v[48:51], v[194:197], v[202:205], v[48:51]
	v_mfma_f32_16x16x32_bf16 v[36:39], v[182:185], v[206:209], v[36:39]
	v_mfma_f32_16x16x32_bf16 v[36:39], v[186:189], v[210:213], v[36:39]
	v_mfma_f32_16x16x32_bf16 v[32:35], v[190:193], v[206:209], v[32:35]
	v_mfma_f32_16x16x32_bf16 v[32:35], v[194:197], v[210:213], v[32:35]
	v_mfma_f32_16x16x32_bf16 v[20:23], v[182:185], v[214:217], v[20:23]
	v_mfma_f32_16x16x32_bf16 v[20:23], v[186:189], v[218:221], v[20:23]
	v_mfma_f32_16x16x32_bf16 v[16:19], v[190:193], v[214:217], v[16:19]
	v_mfma_f32_16x16x32_bf16 v[16:19], v[194:197], v[218:221], v[16:19]
	v_mfma_f32_16x16x32_bf16 v[4:7], v[182:185], v[222:225], v[4:7]
	v_mfma_f32_16x16x32_bf16 v[4:7], v[186:189], v[226:229], v[4:7]
	v_mfma_f32_16x16x32_bf16 v[0:3], v[190:193], v[222:225], v[0:3]
	v_mfma_f32_16x16x32_bf16 v[0:3], v[194:197], v[226:229], v[0:3]
	s_setprio 0
	s_barrier
	s_add_i32 s54, 0, 0x18000
	v_add_u32_e32 v140, s54, v145
	s_add_i32 s55, 0, 0x1c000
	ds_read_b128 v[128:131], v140
	ds_read_b128 v[170:173], v140 offset:1024
	ds_read_b128 v[174:177], v140 offset:2048
	ds_read_b128 v[178:181], v140 offset:3072
	v_add_u32_e32 v140, s55, v145
	ds_read_b128 v[182:185], v140
	ds_read_b128 v[186:189], v140 offset:1024
	ds_read_b128 v[190:193], v140 offset:2048
	ds_read_b128 v[194:197], v140 offset:3072
	s_add_u32 s20, s20, 0x84000
	s_addc_u32 s21, s21, 0
	s_mov_b32 m0, s37
	v_lshl_add_u64 v[234:235], s[20:21], 0, v[138:139]
	ds_read_b128 v[198:201], v162 offset:32768
	ds_read_b128 v[202:205], v162 offset:33792
	ds_read_b128 v[206:209], v162 offset:34816
	ds_read_b128 v[210:213], v162 offset:35840
	ds_read_b128 v[214:217], v162 offset:36864
	ds_read_b128 v[218:221], v162 offset:37888
	ds_read_b128 v[222:225], v162 offset:38912
	ds_read_b128 v[226:229], v162 offset:39936
	global_load_lds_dwordx4 v[234:235], off
	v_lshl_add_u64 v[234:235], s[20:21], 0, v[134:135]
	s_mov_b32 m0, s38
	s_nop 0
	global_load_lds_dwordx4 v[234:235], off
	s_waitcnt vmcnt(8)
	s_waitcnt lgkmcnt(0)
	s_barrier
	s_setprio 1
	s_waitcnt lgkmcnt(0)
	v_mfma_f32_16x16x32_bf16 v[124:127], v[128:131], v[198:201], v[124:127]
	v_mfma_f32_16x16x32_bf16 v[124:127], v[170:173], v[202:205], v[124:127]
	v_mfma_f32_16x16x32_bf16 v[120:123], v[174:177], v[198:201], v[120:123]
	v_mfma_f32_16x16x32_bf16 v[120:123], v[178:181], v[202:205], v[120:123]
	v_mfma_f32_16x16x32_bf16 v[108:111], v[128:131], v[206:209], v[108:111]
	v_mfma_f32_16x16x32_bf16 v[108:111], v[170:173], v[210:213], v[108:111]
	v_mfma_f32_16x16x32_bf16 v[104:107], v[174:177], v[206:209], v[104:107]
	v_mfma_f32_16x16x32_bf16 v[104:107], v[178:181], v[210:213], v[104:107]
	v_mfma_f32_16x16x32_bf16 v[92:95], v[128:131], v[214:217], v[92:95]
	v_mfma_f32_16x16x32_bf16 v[92:95], v[170:173], v[218:221], v[92:95]
	v_mfma_f32_16x16x32_bf16 v[88:91], v[174:177], v[214:217], v[88:91]
	v_mfma_f32_16x16x32_bf16 v[88:91], v[178:181], v[218:221], v[88:91]
	v_mfma_f32_16x16x32_bf16 v[76:79], v[128:131], v[222:225], v[76:79]
	v_mfma_f32_16x16x32_bf16 v[76:79], v[170:173], v[226:229], v[76:79]
	v_mfma_f32_16x16x32_bf16 v[72:75], v[174:177], v[222:225], v[72:75]
	v_mfma_f32_16x16x32_bf16 v[72:75], v[178:181], v[226:229], v[72:75]
	s_setprio 0
	s_setprio 1
	v_mfma_f32_16x16x32_bf16 v[116:119], v[182:185], v[198:201], v[116:119]
	v_mfma_f32_16x16x32_bf16 v[116:119], v[186:189], v[202:205], v[116:119]
	v_mfma_f32_16x16x32_bf16 v[112:115], v[190:193], v[198:201], v[112:115]
	v_mfma_f32_16x16x32_bf16 v[112:115], v[194:197], v[202:205], v[112:115]
	v_mfma_f32_16x16x32_bf16 v[100:103], v[182:185], v[206:209], v[100:103]
	v_mfma_f32_16x16x32_bf16 v[100:103], v[186:189], v[210:213], v[100:103]
	v_mfma_f32_16x16x32_bf16 v[96:99], v[190:193], v[206:209], v[96:99]
	v_mfma_f32_16x16x32_bf16 v[96:99], v[194:197], v[210:213], v[96:99]
	v_mfma_f32_16x16x32_bf16 v[84:87], v[182:185], v[214:217], v[84:87]
	v_mfma_f32_16x16x32_bf16 v[84:87], v[186:189], v[218:221], v[84:87]
	v_mfma_f32_16x16x32_bf16 v[80:83], v[190:193], v[214:217], v[80:83]
	v_mfma_f32_16x16x32_bf16 v[80:83], v[194:197], v[218:221], v[80:83]
	v_mfma_f32_16x16x32_bf16 v[68:71], v[182:185], v[222:225], v[68:71]
	v_mfma_f32_16x16x32_bf16 v[68:71], v[186:189], v[226:229], v[68:71]
	v_mfma_f32_16x16x32_bf16 v[64:67], v[190:193], v[222:225], v[64:67]
	v_mfma_f32_16x16x32_bf16 v[64:67], v[194:197], v[226:229], v[64:67]
	s_setprio 0
	s_barrier
; #define PG8_STAGE(bufoff, gbase, voff) do { _Pragma("unroll") for (int _i = 0; _i < 2; ++_i) \
;         __builtin_amdgcn_global_load_lds((const unsigned*)((const char*)(gbase) + (voff)[_i]), (LAS unsigned*)(lds + (bufoff) + ldsw + _i * 8192), 16, 0, 0); } while (0)
; #define PG8_LDA(dst, b, h) do { _Pragma("unroll") for (int m = 0; m < 4; ++m) _Pragma("unroll") for (int k = 0; k < 2; ++k) dst[m][k] = *(const LAS bf16x8*)(lds + PG8_SA(b, h) + aoff + m * 2048 + k * 1024); } while (0)
; #define PG8_MMA(ai, bj, At, Bt) do { __builtin_amdgcn_s_setprio(1); _Pragma("unroll") for (int m = 0; m < 4; ++m) _Pragma("unroll") for (int n = 0; n < 2; ++n) _Pragma("unroll") for (int k = 0; k < 2; ++k) \
;         acc[ai][bj][m][n] = __builtin_amdgcn_mfma_f32_16x16x32_bf16(Bt[n][k], At[m][k], acc[ai][bj][m][n], 0, 0, 0); __builtin_amdgcn_s_setprio(0); } while (0)
; #define PG8_WAIT_V(n) asm volatile("s_waitcnt vmcnt(" #n ")" ::: "memory")
; #define PG8_WAIT_L(n) asm volatile("s_waitcnt lgkmcnt(" #n ")" ::: "memory")
; #define PG8_BAR __builtin_amdgcn_s_barrier()
; #define PG8_SCHED __builtin_amdgcn_sched_barrier(0)
; template <class EpiT>
; __device__ __forceinline__ void gemm_phase(LAS unsigned char* lds, const Gemm g, const StaticOrder& S, const EpiT& E) {
;     ...
;             PG8_LDA(At, 1, 1); PG8_STAGE(PG8_SB(1, 0), b3, voffB); PG8_STAGE(PG8_SB(1, 1), b3 + hstepB, voffB); PG8_STAGE(PG8_SA(1, 0), a3, voffA);
;             PG8_WAIT_V(8); PG8_WAIT_L(0); PG8_BAR; PG8_MMA(1, 0, At, B0); PG8_MMA(1, 1, At, B1); PG8_BAR; PG8_SCHED;
;         }
;         if (wr == 0) PG8_BAR;
	s_add_i32 s20, s54, s25
	v_lshl_add_u64 v[158:159], v[158:159], 0, s[10:11]
	s_mov_b32 m0, s20
	ds_read_b128 v[198:201], v162 offset:49152
	ds_read_b128 v[202:205], v162 offset:50176
	ds_read_b128 v[206:209], v162 offset:51200
	ds_read_b128 v[210:213], v162 offset:52224
	ds_read_b128 v[214:217], v162 offset:53248
	ds_read_b128 v[218:221], v162 offset:54272
	ds_read_b128 v[222:225], v162 offset:55296
	ds_read_b128 v[226:229], v162 offset:56320
	global_load_lds_dwordx4 v[158:159], off
	s_add_i32 m0, s20, 0x2000
	s_add_u32 s18, s18, 0x84080
	v_lshl_add_u64 v[158:159], v[166:167], 0, s[10:11]
	s_addc_u32 s19, s19, 0
	s_add_i32 s20, s55, s25
	global_load_lds_dwordx4 v[158:159], off
	v_lshl_add_u64 v[158:159], s[18:19], 0, v[136:137]
	s_mov_b32 m0, s20
	s_nop 0
	global_load_lds_dwordx4 v[158:159], off
	v_lshl_add_u64 v[158:159], s[18:19], 0, v[132:133]
	s_add_i32 m0, s20, 0x2000
	s_nop 0
	global_load_lds_dwordx4 v[158:159], off
	v_lshl_add_u64 v[158:159], v[230:231], 0, s[10:11]
	s_mov_b32 m0, s40
	s_nop 0
	global_load_lds_dwordx4 v[158:159], off
	v_lshl_add_u64 v[158:159], v[232:233], 0, s[10:11]
	s_mov_b32 m0, s41
	s_nop 0
	global_load_lds_dwordx4 v[158:159], off
	s_waitcnt vmcnt(8)
	s_waitcnt lgkmcnt(0)
	s_barrier
	s_setprio 1
	s_waitcnt lgkmcnt(0)
	v_mfma_f32_16x16x32_bf16 v[60:63], v[128:131], v[198:201], v[60:63]
	v_mfma_f32_16x16x32_bf16 v[60:63], v[170:173], v[202:205], v[60:63]
	v_mfma_f32_16x16x32_bf16 v[56:59], v[174:177], v[198:201], v[56:59]
	v_mfma_f32_16x16x32_bf16 v[56:59], v[178:181], v[202:205], v[56:59]
	v_mfma_f32_16x16x32_bf16 v[44:47], v[128:131], v[206:209], v[44:47]
	v_mfma_f32_16x16x32_bf16 v[44:47], v[170:173], v[210:213], v[44:47]
	v_mfma_f32_16x16x32_bf16 v[40:43], v[174:177], v[206:209], v[40:43]
	v_mfma_f32_16x16x32_bf16 v[40:43], v[178:181], v[210:213], v[40:43]
	v_mfma_f32_16x16x32_bf16 v[28:31], v[128:131], v[214:217], v[28:31]
	v_mfma_f32_16x16x32_bf16 v[28:31], v[170:173], v[218:221], v[28:31]
	v_mfma_f32_16x16x32_bf16 v[24:27], v[174:177], v[214:217], v[24:27]
	v_mfma_f32_16x16x32_bf16 v[24:27], v[178:181], v[218:221], v[24:27]
	v_mfma_f32_16x16x32_bf16 v[12:15], v[128:131], v[222:225], v[12:15]
	v_mfma_f32_16x16x32_bf16 v[12:15], v[170:173], v[226:229], v[12:15]
	v_mfma_f32_16x16x32_bf16 v[8:11], v[174:177], v[222:225], v[8:11]
	v_mfma_f32_16x16x32_bf16 v[8:11], v[178:181], v[226:229], v[8:11]
	s_setprio 0
	s_setprio 1
	v_mfma_f32_16x16x32_bf16 v[52:55], v[182:185], v[198:201], v[52:55]
	v_mfma_f32_16x16x32_bf16 v[52:55], v[186:189], v[202:205], v[52:55]
	v_mfma_f32_16x16x32_bf16 v[48:51], v[190:193], v[198:201], v[48:51]
	v_mfma_f32_16x16x32_bf16 v[48:51], v[194:197], v[202:205], v[48:51]
	v_mfma_f32_16x16x32_bf16 v[36:39], v[182:185], v[206:209], v[36:39]
	v_mfma_f32_16x16x32_bf16 v[36:39], v[186:189], v[210:213], v[36:39]
	v_mfma_f32_16x16x32_bf16 v[32:35], v[190:193], v[206:209], v[32:35]
	v_mfma_f32_16x16x32_bf16 v[32:35], v[194:197], v[210:213], v[32:35]
	v_mfma_f32_16x16x32_bf16 v[20:23], v[182:185], v[214:217], v[20:23]
	v_mfma_f32_16x16x32_bf16 v[20:23], v[186:189], v[218:221], v[20:23]
	v_mfma_f32_16x16x32_bf16 v[16:19], v[190:193], v[214:217], v[16:19]
	v_mfma_f32_16x16x32_bf16 v[16:19], v[194:197], v[218:221], v[16:19]
	v_mfma_f32_16x16x32_bf16 v[4:7], v[182:185], v[222:225], v[4:7]
	v_mfma_f32_16x16x32_bf16 v[4:7], v[186:189], v[226:229], v[4:7]
	v_mfma_f32_16x16x32_bf16 v[0:3], v[190:193], v[222:225], v[0:3]
	v_mfma_f32_16x16x32_bf16 v[0:3], v[194:197], v[226:229], v[0:3]
	s_setprio 0
	s_barrier
	s_add_i32 s53, s53, 2
	s_add_u32 s16, s16, 0x100
	s_addc_u32 s17, s17, 0
	s_add_u32 s51, s51, 0x100
	s_addc_u32 s52, s52, 0
	s_cmp_gt_u32 s53, 29
	s_cbranch_scc0 .LBB0_100
	s_and_b64 vcc, exec, s[12:13]
	s_cbranch_vccz .LBB0_103
	s_barrier

; #define PG8_STAGE(bufoff, gbase, voff) do { _Pragma("unroll") for (int _i = 0; _i < 2; ++_i) \
;         __builtin_amdgcn_global_load_lds((const unsigned*)((const char*)(gbase) + (voff)[_i]), (LAS unsigned*)(lds + (bufoff) + ldsw + _i * 8192), 16, 0, 0); } while (0)
; #define PG8_LDA(dst, b, h) do { _Pragma("unroll") for (int m = 0; m < 4; ++m) _Pragma("unroll") for (int k = 0; k < 2; ++k) dst[m][k] = *(const LAS bf16x8*)(lds + PG8_SA(b, h) + aoff + m * 2048 + k * 1024); } while (0)
; #define PG8_LDB(dst, b, h) do { _Pragma("unroll") for (int n = 0; n < 2; ++n) _Pragma("unroll") for (int k = 0; k < 2; ++k) dst[n][k] = *(const LAS bf16x8*)(lds + PG8_SB(b, h) + boff + n * 2048 + k * 1024); } while (0)
; #define PG8_MMA(ai, bj, At, Bt) do { __builtin_amdgcn_s_setprio(1); _Pragma("unroll") for (int m = 0; m < 4; ++m) _Pragma("unroll") for (int n = 0; n < 2; ++n) _Pragma("unroll") for (int k = 0; k < 2; ++k) \
;         acc[ai][bj][m][n] = __builtin_amdgcn_mfma_f32_16x16x32_bf16(Bt[n][k], At[m][k], acc[ai][bj][m][n], 0, 0, 0); __builtin_amdgcn_s_setprio(0); } while (0)
; #define PG8_WAIT_V(n) asm volatile("s_waitcnt vmcnt(" #n ")" ::: "memory")
; #define PG8_WAIT_L(n) asm volatile("s_waitcnt lgkmcnt(" #n ")" ::: "memory")
; #define PG8_BAR __builtin_amdgcn_s_barrier()
; #define PG8_SCHED __builtin_amdgcn_sched_barrier(0)
; template <class EpiT>
; __device__ __forceinline__ void gemm_phase(LAS unsigned char* lds, const Gemm g, const StaticOrder& S, const EpiT& E) {
;     ...
;         for (int t = 0; t < nt; t += 2) {
;             const bool last = (t == nt - 2);
;             const char* a1 = cA + (size_t)(t + 1) * kstep;
;             const char* a2 = last ? nA : cA + (size_t)(t + 2) * kstep; const char* b2 = last ? nB : cB + (size_t)(t + 2) * kstep;
;             const char* a3 = a2 + kstep; const char* b3 = b2 + kstep;
;             PG8_LDB(B0, 0, 0); PG8_LDB(B1, 0, 1); PG8_SCHED; PG8_LDA(At, 0, 0); PG8_STAGE(PG8_SA(1, 1), a1 + hstepA, voffA);
;             PG8_WAIT_V(8); PG8_WAIT_L(0); PG8_BAR; PG8_MMA(0, 0, At, B0); PG8_MMA(0, 1, At, B1); PG8_BAR; PG8_SCHED;
;             PG8_LDA(At, 0, 1); PG8_STAGE(PG8_SB(0, 0), b2, voffB); PG8_STAGE(PG8_SB(0, 1), b2 + hstepB, voffB); PG8_STAGE(PG8_SA(0, 0), a2, voffA);
.LBB0_392:
	ds_read_b128 v[154:157], v149
	ds_read_b128 v[158:161], v149 offset:1024
	ds_read_b128 v[170:173], v149 offset:2048
	ds_read_b128 v[174:177], v149 offset:3072
	ds_read_b128 v[178:181], v150
	ds_read_b128 v[182:185], v150 offset:1024
	ds_read_b128 v[186:189], v150 offset:2048
	ds_read_b128 v[190:193], v150 offset:3072
	s_add_u32 s20, s18, 0xfff7c080
	s_addc_u32 s21, s19, -1
	s_cmp_eq_u32 s53, 28
	s_cselect_b32 s23, s5, s21
	s_cselect_b32 s22, s4, s20
	s_cselect_b32 s21, s17, s52
	s_cselect_b32 s20, s16, s51
	v_lshl_add_u64 v[162:163], s[18:19], 0, v[138:139]
	s_add_i32 m0, s35, 0xc000
	ds_read_b128 v[194:197], v151
	ds_read_b128 v[198:201], v151 offset:1024
	ds_read_b128 v[202:205], v151 offset:2048
	ds_read_b128 v[206:209], v151 offset:3072
	ds_read_b128 v[210:213], v151 offset:4096
	ds_read_b128 v[214:217], v151 offset:5120
	ds_read_b128 v[218:221], v151 offset:6144
	ds_read_b128 v[222:225], v151 offset:7168
	global_load_lds_dwordx4 v[162:163], off
	v_lshl_add_u64 v[162:163], s[18:19], 0, v[140:141]
	s_add_i32 m0, s35, 0xe000
	s_nop 0
	global_load_lds_dwordx4 v[162:163], off
	s_waitcnt vmcnt(8)
	s_waitcnt lgkmcnt(0)
	s_barrier
	s_setprio 1
	s_waitcnt lgkmcnt(0)
	v_mfma_f32_16x16x32_bf16 v[124:127], v[154:157], v[194:197], v[124:127]
	v_mfma_f32_16x16x32_bf16 v[124:127], v[158:161], v[198:201], v[124:127]
	v_mfma_f32_16x16x32_bf16 v[120:123], v[170:173], v[194:197], v[120:123]
	v_mfma_f32_16x16x32_bf16 v[120:123], v[174:177], v[198:201], v[120:123]
	v_mfma_f32_16x16x32_bf16 v[108:111], v[154:157], v[202:205], v[108:111]
	v_mfma_f32_16x16x32_bf16 v[108:111], v[158:161], v[206:209], v[108:111]
	v_mfma_f32_16x16x32_bf16 v[104:107], v[170:173], v[202:205], v[104:107]
	v_mfma_f32_16x16x32_bf16 v[104:107], v[174:177], v[206:209], v[104:107]
	v_mfma_f32_16x16x32_bf16 v[92:95], v[154:157], v[210:213], v[92:95]
	v_mfma_f32_16x16x32_bf16 v[92:95], v[158:161], v[214:217], v[92:95]
	v_mfma_f32_16x16x32_bf16 v[88:91], v[170:173], v[210:213], v[88:91]
	v_mfma_f32_16x16x32_bf16 v[88:91], v[174:177], v[214:217], v[88:91]
	v_mfma_f32_16x16x32_bf16 v[76:79], v[154:157], v[218:221], v[76:79]
	v_mfma_f32_16x16x32_bf16 v[76:79], v[158:161], v[222:225], v[76:79]
	v_mfma_f32_16x16x32_bf16 v[72:75], v[170:173], v[218:221], v[72:75]
	v_mfma_f32_16x16x32_bf16 v[72:75], v[174:177], v[222:225], v[72:75]
	s_setprio 0
	s_setprio 1
	v_mfma_f32_16x16x32_bf16 v[116:119], v[178:181], v[194:197], v[116:119]
	v_mfma_f32_16x16x32_bf16 v[116:119], v[182:185], v[198:201], v[116:119]
	v_mfma_f32_16x16x32_bf16 v[112:115], v[186:189], v[194:197], v[112:115]
	v_mfma_f32_16x16x32_bf16 v[112:115], v[190:193], v[198:201], v[112:115]
	v_mfma_f32_16x16x32_bf16 v[100:103], v[178:181], v[202:205], v[100:103]
	v_mfma_f32_16x16x32_bf16 v[100:103], v[182:185], v[206:209], v[100:103]
	v_mfma_f32_16x16x32_bf16 v[96:99], v[186:189], v[202:205], v[96:99]
	v_mfma_f32_16x16x32_bf16 v[96:99], v[190:193], v[206:209], v[96:99]
	v_mfma_f32_16x16x32_bf16 v[84:87], v[178:181], v[210:213], v[84:87]
	v_mfma_f32_16x16x32_bf16 v[84:87], v[182:185], v[214:217], v[84:87]
	v_mfma_f32_16x16x32_bf16 v[80:83], v[186:189], v[210:213], v[80:83]
	v_mfma_f32_16x16x32_bf16 v[80:83], v[190:193], v[214:217], v[80:83]
	v_mfma_f32_16x16x32_bf16 v[68:71], v[178:181], v[218:221], v[68:71]
	v_mfma_f32_16x16x32_bf16 v[68:71], v[182:185], v[222:225], v[68:71]
	v_mfma_f32_16x16x32_bf16 v[64:67], v[186:189], v[218:221], v[64:67]
	v_mfma_f32_16x16x32_bf16 v[64:67], v[190:193], v[222:225], v[64:67]
	s_setprio 0
	s_barrier
	s_add_i32 s54, s44, s33
	v_lshl_add_u64 v[162:163], s[20:21], 0, v[130:131]
	s_mov_b32 m0, s54
	ds_read_b128 v[194:197], v151 offset:16384
	ds_read_b128 v[198:201], v151 offset:17408
	ds_read_b128 v[202:205], v151 offset:18432
	ds_read_b128 v[206:209], v151 offset:19456
	ds_read_b128 v[210:213], v151 offset:20480
	ds_read_b128 v[214:217], v151 offset:21504
	ds_read_b128 v[218:221], v151 offset:22528
	ds_read_b128 v[222:225], v151 offset:23552
	global_load_lds_dwordx4 v[162:163], off
	s_add_i32 m0, s54, 0x2000
	s_add_u32 s54, s20, 0x84000
	v_lshl_add_u64 v[166:167], s[20:21], 0, v[134:135]
	s_addc_u32 s55, s21, 0
	s_add_i32 s56, s45, s33
	global_load_lds_dwordx4 v[166:167], off
	v_lshl_add_u64 v[226:227], s[54:55], 0, v[130:131]
	s_mov_b32 m0, s56
	v_lshl_add_u64 v[228:229], s[22:23], 0, v[132:133]
	global_load_lds_dwordx4 v[226:227], off
	v_lshl_add_u64 v[226:227], s[54:55], 0, v[134:135]
	s_add_i32 m0, s56, 0x2000
	s_nop 0
	global_load_lds_dwordx4 v[226:227], off
	v_lshl_add_u64 v[226:227], s[22:23], 0, v[128:129]
	s_mov_b32 m0, s35
	s_nop 0
	global_load_lds_dwordx4 v[226:227], off
	s_mov_b32 m0, s36
	s_nop 0
	global_load_lds_dwordx4 v[228:229], off
	s_waitcnt vmcnt(8)
	s_waitcnt lgkmcnt(0)
	s_barrier
; #define PG8_STAGE(bufoff, gbase, voff) do { _Pragma("unroll") for (int _i = 0; _i < 2; ++_i) \
;         __builtin_amdgcn_global_load_lds((const unsigned*)((const char*)(gbase) + (voff)[_i]), (LAS unsigned*)(lds + (bufoff) + ldsw + _i * 8192), 16, 0, 0); } while (0)
; #define PG8_LDA(dst, b, h) do { _Pragma("unroll") for (int m = 0; m < 4; ++m) _Pragma("unroll") for (int k = 0; k < 2; ++k) dst[m][k] = *(const LAS bf16x8*)(lds + PG8_SA(b, h) + aoff + m * 2048 + k * 1024); } while (0)
; #define PG8_LDB(dst, b, h) do { _Pragma("unroll") for (int n = 0; n < 2; ++n) _Pragma("unroll") for (int k = 0; k < 2; ++k) dst[n][k] = *(const LAS bf16x8*)(lds + PG8_SB(b, h) + boff + n * 2048 + k * 1024); } while (0)
; #define PG8_MMA(ai, bj, At, Bt) do { __builtin_amdgcn_s_setprio(1); _Pragma("unroll") for (int m = 0; m < 4; ++m) _Pragma("unroll") for (int n = 0; n < 2; ++n) _Pragma("unroll") for (int k = 0; k < 2; ++k) \
;         acc[ai][bj][m][n] = __builtin_amdgcn_mfma_f32_16x16x32_bf16(Bt[n][k], At[m][k], acc[ai][bj][m][n], 0, 0, 0); __builtin_amdgcn_s_setprio(0); } while (0)
; #define PG8_WAIT_V(n) asm volatile("s_waitcnt vmcnt(" #n ")" ::: "memory")
; #define PG8_WAIT_L(n) asm volatile("s_waitcnt lgkmcnt(" #n ")" ::: "memory")
; #define PG8_BAR __builtin_amdgcn_s_barrier()
; #define PG8_SCHED __builtin_amdgcn_sched_barrier(0)
; template <class EpiT>
; __device__ __forceinline__ void gemm_phase(LAS unsigned char* lds, const Gemm g, const StaticOrder& S, const EpiT& E) {
;     ...
;             PG8_WAIT_V(8); PG8_WAIT_L(0); PG8_BAR; PG8_MMA(1, 0, At, B0); PG8_MMA(1, 1, At, B1); PG8_BAR; PG8_SCHED;
;             PG8_LDB(B0, 1, 0); PG8_LDB(B1, 1, 1); PG8_SCHED; PG8_LDA(At, 1, 0); PG8_STAGE(PG8_SA(0, 1), a2 + hstepA, voffA);
;             PG8_WAIT_V(8); PG8_WAIT_L(0); PG8_BAR; PG8_MMA(0, 0, At, B0); PG8_MMA(0, 1, At, B1); PG8_BAR; PG8_SCHED;
	s_setprio 1
	s_waitcnt lgkmcnt(0)
	v_mfma_f32_16x16x32_bf16 v[60:63], v[154:157], v[194:197], v[60:63]
	v_mfma_f32_16x16x32_bf16 v[60:63], v[158:161], v[198:201], v[60:63]
	v_mfma_f32_16x16x32_bf16 v[56:59], v[170:173], v[194:197], v[56:59]
	v_mfma_f32_16x16x32_bf16 v[56:59], v[174:177], v[198:201], v[56:59]
	v_mfma_f32_16x16x32_bf16 v[44:47], v[154:157], v[202:205], v[44:47]
	v_mfma_f32_16x16x32_bf16 v[44:47], v[158:161], v[206:209], v[44:47]
	v_mfma_f32_16x16x32_bf16 v[40:43], v[170:173], v[202:205], v[40:43]
	v_mfma_f32_16x16x32_bf16 v[40:43], v[174:177], v[206:209], v[40:43]
	v_mfma_f32_16x16x32_bf16 v[28:31], v[154:157], v[210:213], v[28:31]
	v_mfma_f32_16x16x32_bf16 v[28:31], v[158:161], v[214:217], v[28:31]
	v_mfma_f32_16x16x32_bf16 v[24:27], v[170:173], v[210:213], v[24:27]
	v_mfma_f32_16x16x32_bf16 v[24:27], v[174:177], v[214:217], v[24:27]
	v_mfma_f32_16x16x32_bf16 v[12:15], v[154:157], v[218:221], v[12:15]
	v_mfma_f32_16x16x32_bf16 v[12:15], v[158:161], v[222:225], v[12:15]
	v_mfma_f32_16x16x32_bf16 v[8:11], v[170:173], v[218:221], v[8:11]
	v_mfma_f32_16x16x32_bf16 v[8:11], v[174:177], v[222:225], v[8:11]
	s_setprio 0
	s_setprio 1
	v_mfma_f32_16x16x32_bf16 v[52:55], v[178:181], v[194:197], v[52:55]
	v_mfma_f32_16x16x32_bf16 v[52:55], v[182:185], v[198:201], v[52:55]
	v_mfma_f32_16x16x32_bf16 v[48:51], v[186:189], v[194:197], v[48:51]
	v_mfma_f32_16x16x32_bf16 v[48:51], v[190:193], v[198:201], v[48:51]
	v_mfma_f32_16x16x32_bf16 v[36:39], v[178:181], v[202:205], v[36:39]
	v_mfma_f32_16x16x32_bf16 v[36:39], v[182:185], v[206:209], v[36:39]
	v_mfma_f32_16x16x32_bf16 v[32:35], v[186:189], v[202:205], v[32:35]
	v_mfma_f32_16x16x32_bf16 v[32:35], v[190:193], v[206:209], v[32:35]
	v_mfma_f32_16x16x32_bf16 v[20:23], v[178:181], v[210:213], v[20:23]
	v_mfma_f32_16x16x32_bf16 v[20:23], v[182:185], v[214:217], v[20:23]
	v_mfma_f32_16x16x32_bf16 v[16:19], v[186:189], v[210:213], v[16:19]
	v_mfma_f32_16x16x32_bf16 v[16:19], v[190:193], v[214:217], v[16:19]
	v_mfma_f32_16x16x32_bf16 v[4:7], v[178:181], v[218:221], v[4:7]
	v_mfma_f32_16x16x32_bf16 v[4:7], v[182:185], v[222:225], v[4:7]
	v_mfma_f32_16x16x32_bf16 v[0:3], v[186:189], v[218:221], v[0:3]
	v_mfma_f32_16x16x32_bf16 v[0:3], v[190:193], v[222:225], v[0:3]
	s_setprio 0
	s_barrier
	s_add_i32 s54, 0, 0x18000
	v_add_u32_e32 v153, s54, v146
	s_add_i32 s55, 0, 0x1c000
	ds_read_b128 v[154:157], v153
	ds_read_b128 v[158:161], v153 offset:1024
	ds_read_b128 v[170:173], v153 offset:2048
	ds_read_b128 v[174:177], v153 offset:3072
	v_add_u32_e32 v153, s55, v146
	ds_read_b128 v[178:181], v153
	ds_read_b128 v[182:185], v153 offset:1024
	ds_read_b128 v[186:189], v153 offset:2048
	ds_read_b128 v[190:193], v153 offset:3072
	s_add_u32 s22, s22, 0x84000
	s_addc_u32 s23, s23, 0
	s_mov_b32 m0, s37
	v_lshl_add_u64 v[230:231], s[22:23], 0, v[128:129]
	ds_read_b128 v[194:197], v151 offset:32768
	ds_read_b128 v[198:201], v151 offset:33792
	ds_read_b128 v[202:205], v151 offset:34816
	ds_read_b128 v[206:209], v151 offset:35840
	ds_read_b128 v[210:213], v151 offset:36864
	ds_read_b128 v[214:217], v151 offset:37888
	ds_read_b128 v[218:221], v151 offset:38912
	ds_read_b128 v[222:225], v151 offset:39936
	global_load_lds_dwordx4 v[230:231], off
	v_lshl_add_u64 v[230:231], s[22:23], 0, v[132:133]
	s_mov_b32 m0, s38
	s_nop 0
	global_load_lds_dwordx4 v[230:231], off
	s_waitcnt vmcnt(8)
	s_waitcnt lgkmcnt(0)
	s_barrier
	s_setprio 1
	s_waitcnt lgkmcnt(0)
	v_mfma_f32_16x16x32_bf16 v[124:127], v[154:157], v[194:197], v[124:127]
	v_mfma_f32_16x16x32_bf16 v[124:127], v[158:161], v[198:201], v[124:127]
	v_mfma_f32_16x16x32_bf16 v[120:123], v[170:173], v[194:197], v[120:123]
	v_mfma_f32_16x16x32_bf16 v[120:123], v[174:177], v[198:201], v[120:123]
	v_mfma_f32_16x16x32_bf16 v[108:111], v[154:157], v[202:205], v[108:111]
	v_mfma_f32_16x16x32_bf16 v[108:111], v[158:161], v[206:209], v[108:111]
	v_mfma_f32_16x16x32_bf16 v[104:107], v[170:173], v[202:205], v[104:107]
	v_mfma_f32_16x16x32_bf16 v[104:107], v[174:177], v[206:209], v[104:107]
	v_mfma_f32_16x16x32_bf16 v[92:95], v[154:157], v[210:213], v[92:95]
	v_mfma_f32_16x16x32_bf16 v[92:95], v[158:161], v[214:217], v[92:95]
	v_mfma_f32_16x16x32_bf16 v[88:91], v[170:173], v[210:213], v[88:91]
	v_mfma_f32_16x16x32_bf16 v[88:91], v[174:177], v[214:217], v[88:91]
	v_mfma_f32_16x16x32_bf16 v[76:79], v[154:157], v[218:221], v[76:79]
	v_mfma_f32_16x16x32_bf16 v[76:79], v[158:161], v[222:225], v[76:79]
	v_mfma_f32_16x16x32_bf16 v[72:75], v[170:173], v[218:221], v[72:75]
	v_mfma_f32_16x16x32_bf16 v[72:75], v[174:177], v[222:225], v[72:75]
	s_setprio 0
	s_setprio 1
	v_mfma_f32_16x16x32_bf16 v[116:119], v[178:181], v[194:197], v[116:119]
	v_mfma_f32_16x16x32_bf16 v[116:119], v[182:185], v[198:201], v[116:119]
	v_mfma_f32_16x16x32_bf16 v[112:115], v[186:189], v[194:197], v[112:115]
	v_mfma_f32_16x16x32_bf16 v[112:115], v[190:193], v[198:201], v[112:115]
	v_mfma_f32_16x16x32_bf16 v[100:103], v[178:181], v[202:205], v[100:103]
	v_mfma_f32_16x16x32_bf16 v[100:103], v[182:185], v[206:209], v[100:103]
	v_mfma_f32_16x16x32_bf16 v[96:99], v[186:189], v[202:205], v[96:99]
	v_mfma_f32_16x16x32_bf16 v[96:99], v[190:193], v[206:209], v[96:99]
	v_mfma_f32_16x16x32_bf16 v[84:87], v[178:181], v[210:213], v[84:87]
	v_mfma_f32_16x16x32_bf16 v[84:87], v[182:185], v[214:217], v[84:87]
	v_mfma_f32_16x16x32_bf16 v[80:83], v[186:189], v[210:213], v[80:83]
	v_mfma_f32_16x16x32_bf16 v[80:83], v[190:193], v[214:217], v[80:83]
	v_mfma_f32_16x16x32_bf16 v[68:71], v[178:181], v[218:221], v[68:71]
	v_mfma_f32_16x16x32_bf16 v[68:71], v[182:185], v[222:225], v[68:71]
	v_mfma_f32_16x16x32_bf16 v[64:67], v[186:189], v[218:221], v[64:67]
	v_mfma_f32_16x16x32_bf16 v[64:67], v[190:193], v[222:225], v[64:67]
	s_setprio 0
	s_barrier
; #define PG8_STAGE(bufoff, gbase, voff) do { _Pragma("unroll") for (int _i = 0; _i < 2; ++_i) \
;         __builtin_amdgcn_global_load_lds((const unsigned*)((const char*)(gbase) + (voff)[_i]), (LAS unsigned*)(lds + (bufoff) + ldsw + _i * 8192), 16, 0, 0); } while (0)
; #define PG8_LDA(dst, b, h) do { _Pragma("unroll") for (int m = 0; m < 4; ++m) _Pragma("unroll") for (int k = 0; k < 2; ++k) dst[m][k] = *(const LAS bf16x8*)(lds + PG8_SA(b, h) + aoff + m * 2048 + k * 1024); } while (0)
; #define PG8_MMA(ai, bj, At, Bt) do { __builtin_amdgcn_s_setprio(1); _Pragma("unroll") for (int m = 0; m < 4; ++m) _Pragma("unroll") for (int n = 0; n < 2; ++n) _Pragma("unroll") for (int k = 0; k < 2; ++k) \
;         acc[ai][bj][m][n] = __builtin_amdgcn_mfma_f32_16x16x32_bf16(Bt[n][k], At[m][k], acc[ai][bj][m][n], 0, 0, 0); __builtin_amdgcn_s_setprio(0); } while (0)
; #define PG8_WAIT_V(n) asm volatile("s_waitcnt vmcnt(" #n ")" ::: "memory")
; #define PG8_WAIT_L(n) asm volatile("s_waitcnt lgkmcnt(" #n ")" ::: "memory")
; #define PG8_BAR __builtin_amdgcn_s_barrier()
; #define PG8_SCHED __builtin_amdgcn_sched_barrier(0)
; template <class EpiT>
; __device__ __forceinline__ void gemm_phase(LAS unsigned char* lds, const Gemm g, const StaticOrder& S, const EpiT& E) {
;     ...
;             PG8_LDA(At, 1, 1); PG8_STAGE(PG8_SB(1, 0), b3, voffB); PG8_STAGE(PG8_SB(1, 1), b3 + hstepB, voffB); PG8_STAGE(PG8_SA(1, 0), a3, voffA);
;             PG8_WAIT_V(8); PG8_WAIT_L(0); PG8_BAR; PG8_MMA(1, 0, At, B0); PG8_MMA(1, 1, At, B1); PG8_BAR; PG8_SCHED;
;         }
;         if (wr == 0) PG8_BAR;
	s_add_i32 s22, s54, s33
	v_lshl_add_u64 v[162:163], v[162:163], 0, s[12:13]
	s_mov_b32 m0, s22
	ds_read_b128 v[194:197], v151 offset:49152
	ds_read_b128 v[198:201], v151 offset:50176
	ds_read_b128 v[202:205], v151 offset:51200
	ds_read_b128 v[206:209], v151 offset:52224
	ds_read_b128 v[210:213], v151 offset:53248
	ds_read_b128 v[214:217], v151 offset:54272
	ds_read_b128 v[218:221], v151 offset:55296
	ds_read_b128 v[222:225], v151 offset:56320
	global_load_lds_dwordx4 v[162:163], off
	s_add_i32 m0, s22, 0x2000
	s_add_u32 s20, s20, 0x84080
	v_lshl_add_u64 v[162:163], v[166:167], 0, s[12:13]
	s_addc_u32 s21, s21, 0
	s_add_i32 s22, s55, s33
	global_load_lds_dwordx4 v[162:163], off
	v_lshl_add_u64 v[162:163], s[20:21], 0, v[130:131]
	s_mov_b32 m0, s22
	s_nop 0
	global_load_lds_dwordx4 v[162:163], off
	v_lshl_add_u64 v[162:163], s[20:21], 0, v[134:135]
	s_add_i32 m0, s22, 0x2000
	s_nop 0
	global_load_lds_dwordx4 v[162:163], off
	v_lshl_add_u64 v[162:163], v[226:227], 0, s[12:13]
	s_mov_b32 m0, s40
	s_nop 0
	global_load_lds_dwordx4 v[162:163], off
	v_lshl_add_u64 v[162:163], v[228:229], 0, s[12:13]
	s_mov_b32 m0, s41
	s_nop 0
	global_load_lds_dwordx4 v[162:163], off
	s_waitcnt vmcnt(8)
	s_waitcnt lgkmcnt(0)
	s_barrier
	s_setprio 1
	s_waitcnt lgkmcnt(0)
	v_mfma_f32_16x16x32_bf16 v[60:63], v[154:157], v[194:197], v[60:63]
	v_mfma_f32_16x16x32_bf16 v[60:63], v[158:161], v[198:201], v[60:63]
	v_mfma_f32_16x16x32_bf16 v[56:59], v[170:173], v[194:197], v[56:59]
	v_mfma_f32_16x16x32_bf16 v[56:59], v[174:177], v[198:201], v[56:59]
	v_mfma_f32_16x16x32_bf16 v[44:47], v[154:157], v[202:205], v[44:47]
	v_mfma_f32_16x16x32_bf16 v[44:47], v[158:161], v[206:209], v[44:47]
	v_mfma_f32_16x16x32_bf16 v[40:43], v[170:173], v[202:205], v[40:43]
	v_mfma_f32_16x16x32_bf16 v[40:43], v[174:177], v[206:209], v[40:43]
	v_mfma_f32_16x16x32_bf16 v[28:31], v[154:157], v[210:213], v[28:31]
	v_mfma_f32_16x16x32_bf16 v[28:31], v[158:161], v[214:217], v[28:31]
	v_mfma_f32_16x16x32_bf16 v[24:27], v[170:173], v[210:213], v[24:27]
	v_mfma_f32_16x16x32_bf16 v[24:27], v[174:177], v[214:217], v[24:27]
	v_mfma_f32_16x16x32_bf16 v[12:15], v[154:157], v[218:221], v[12:15]
	v_mfma_f32_16x16x32_bf16 v[12:15], v[158:161], v[222:225], v[12:15]
	v_mfma_f32_16x16x32_bf16 v[8:11], v[170:173], v[218:221], v[8:11]
	v_mfma_f32_16x16x32_bf16 v[8:11], v[174:177], v[222:225], v[8:11]
	s_setprio 0
	s_setprio 1
	v_mfma_f32_16x16x32_bf16 v[52:55], v[178:181], v[194:197], v[52:55]
	v_mfma_f32_16x16x32_bf16 v[52:55], v[182:185], v[198:201], v[52:55]
	v_mfma_f32_16x16x32_bf16 v[48:51], v[186:189], v[194:197], v[48:51]
	v_mfma_f32_16x16x32_bf16 v[48:51], v[190:193], v[198:201], v[48:51]
	v_mfma_f32_16x16x32_bf16 v[36:39], v[178:181], v[202:205], v[36:39]
	v_mfma_f32_16x16x32_bf16 v[36:39], v[182:185], v[206:209], v[36:39]
	v_mfma_f32_16x16x32_bf16 v[32:35], v[186:189], v[202:205], v[32:35]
	v_mfma_f32_16x16x32_bf16 v[32:35], v[190:193], v[206:209], v[32:35]
	v_mfma_f32_16x16x32_bf16 v[20:23], v[178:181], v[210:213], v[20:23]
	v_mfma_f32_16x16x32_bf16 v[20:23], v[182:185], v[214:217], v[20:23]
	v_mfma_f32_16x16x32_bf16 v[16:19], v[186:189], v[210:213], v[16:19]
	v_mfma_f32_16x16x32_bf16 v[16:19], v[190:193], v[214:217], v[16:19]
	v_mfma_f32_16x16x32_bf16 v[4:7], v[178:181], v[218:221], v[4:7]
	v_mfma_f32_16x16x32_bf16 v[4:7], v[182:185], v[222:225], v[4:7]
	v_mfma_f32_16x16x32_bf16 v[0:3], v[186:189], v[218:221], v[0:3]
	v_mfma_f32_16x16x32_bf16 v[0:3], v[190:193], v[222:225], v[0:3]
	s_setprio 0
	s_barrier
	s_add_i32 s53, s53, 2
	s_add_u32 s18, s18, 0x100
	s_addc_u32 s19, s19, 0
	s_add_u32 s51, s51, 0x100
	s_addc_u32 s52, s52, 0
	s_cmp_gt_u32 s53, 29
	s_cbranch_scc0 .LBB0_392
	s_and_b64 vcc, exec, s[14:15]
	s_cbranch_vccz .LBB0_395
	s_barrier

; #define PG8_STAGE(bufoff, gbase, voff) do { _Pragma("unroll") for (int _i = 0; _i < 2; ++_i) \
;         __builtin_amdgcn_global_load_lds((const unsigned*)((const char*)(gbase) + (voff)[_i]), (LAS unsigned*)(lds + (bufoff) + ldsw + _i * 8192), 16, 0, 0); } while (0)
; #define PG8_LDA(dst, b, h) do { _Pragma("unroll") for (int m = 0; m < 4; ++m) _Pragma("unroll") for (int k = 0; k < 2; ++k) dst[m][k] = *(const LAS bf16x8*)(lds + PG8_SA(b, h) + aoff + m * 2048 + k * 1024); } while (0)
; #define PG8_LDB(dst, b, h) do { _Pragma("unroll") for (int n = 0; n < 2; ++n) _Pragma("unroll") for (int k = 0; k < 2; ++k) dst[n][k] = *(const LAS bf16x8*)(lds + PG8_SB(b, h) + boff + n * 2048 + k * 1024); } while (0)
; #define PG8_MMA(ai, bj, At, Bt) do { __builtin_amdgcn_s_setprio(1); _Pragma("unroll") for (int m = 0; m < 4; ++m) _Pragma("unroll") for (int n = 0; n < 2; ++n) _Pragma("unroll") for (int k = 0; k < 2; ++k) \
;         acc[ai][bj][m][n] = __builtin_amdgcn_mfma_f32_16x16x32_bf16(Bt[n][k], At[m][k], acc[ai][bj][m][n], 0, 0, 0); __builtin_amdgcn_s_setprio(0); } while (0)
; #define PG8_WAIT_V(n) asm volatile("s_waitcnt vmcnt(" #n ")" ::: "memory")
; #define PG8_WAIT_L(n) asm volatile("s_waitcnt lgkmcnt(" #n ")" ::: "memory")
; #define PG8_BAR __builtin_amdgcn_s_barrier()
; #define PG8_SCHED __builtin_amdgcn_sched_barrier(0)
; template <class EpiT>
; __device__ __forceinline__ void gemm_phase(LAS unsigned char* lds, const Gemm g, const StaticOrder& S, const EpiT& E) {
;     ...
;         for (int t = 0; t < nt; t += 2) {
;             const bool last = (t == nt - 2);
;             const char* a1 = cA + (size_t)(t + 1) * kstep;
;             const char* a2 = last ? nA : cA + (size_t)(t + 2) * kstep; const char* b2 = last ? nB : cB + (size_t)(t + 2) * kstep;
;             const char* a3 = a2 + kstep; const char* b3 = b2 + kstep;
;             PG8_LDB(B0, 0, 0); PG8_LDB(B1, 0, 1); PG8_SCHED; PG8_LDA(At, 0, 0); PG8_STAGE(PG8_SA(1, 1), a1 + hstepA, voffA);
;             PG8_WAIT_V(8); PG8_WAIT_L(0); PG8_BAR; PG8_MMA(0, 0, At, B0); PG8_MMA(0, 1, At, B1); PG8_BAR; PG8_SCHED;
;             PG8_LDA(At, 0, 1); PG8_STAGE(PG8_SB(0, 0), b2, voffB); PG8_STAGE(PG8_SB(0, 1), b2 + hstepB, voffB); PG8_STAGE(PG8_SA(0, 0), a2, voffA);
.LBB0_516:
	ds_read_b128 v[154:157], v150
	ds_read_b128 v[158:161], v150 offset:1024
	ds_read_b128 v[170:173], v150 offset:2048
	ds_read_b128 v[174:177], v150 offset:3072
	ds_read_b128 v[178:181], v151
	ds_read_b128 v[182:185], v151 offset:1024
	ds_read_b128 v[186:189], v151 offset:2048
	ds_read_b128 v[190:193], v151 offset:3072
	s_add_u32 s18, s16, 0xfff7c080
	s_addc_u32 s19, s17, -1
	s_cmp_eq_u32 s53, 28
	s_cselect_b32 s21, s3, s19
	s_cselect_b32 s20, s2, s18
	s_cselect_b32 s19, s15, s52
	s_cselect_b32 s18, s14, s51
	v_lshl_add_u64 v[144:145], s[16:17], 0, v[136:137]
	s_add_i32 m0, s36, 0xc000
	ds_read_b128 v[194:197], v152
	ds_read_b128 v[198:201], v152 offset:1024
	ds_read_b128 v[202:205], v152 offset:2048
	ds_read_b128 v[206:209], v152 offset:3072
	ds_read_b128 v[210:213], v152 offset:4096
	ds_read_b128 v[214:217], v152 offset:5120
	ds_read_b128 v[218:221], v152 offset:6144
	ds_read_b128 v[222:225], v152 offset:7168
	global_load_lds_dwordx4 v[144:145], off
	v_lshl_add_u64 v[144:145], s[16:17], 0, v[138:139]
	s_add_i32 m0, s36, 0xe000
	s_nop 0
	global_load_lds_dwordx4 v[144:145], off
	s_waitcnt vmcnt(8)
	s_waitcnt lgkmcnt(0)
	s_barrier
	s_setprio 1
	s_waitcnt lgkmcnt(0)
	v_mfma_f32_16x16x32_bf16 v[124:127], v[154:157], v[194:197], v[124:127]
	v_mfma_f32_16x16x32_bf16 v[124:127], v[158:161], v[198:201], v[124:127]
	v_mfma_f32_16x16x32_bf16 v[120:123], v[170:173], v[194:197], v[120:123]
	v_mfma_f32_16x16x32_bf16 v[120:123], v[174:177], v[198:201], v[120:123]
	v_mfma_f32_16x16x32_bf16 v[108:111], v[154:157], v[202:205], v[108:111]
	v_mfma_f32_16x16x32_bf16 v[108:111], v[158:161], v[206:209], v[108:111]
	v_mfma_f32_16x16x32_bf16 v[104:107], v[170:173], v[202:205], v[104:107]
	v_mfma_f32_16x16x32_bf16 v[104:107], v[174:177], v[206:209], v[104:107]
	v_mfma_f32_16x16x32_bf16 v[92:95], v[154:157], v[210:213], v[92:95]
	v_mfma_f32_16x16x32_bf16 v[92:95], v[158:161], v[214:217], v[92:95]
	v_mfma_f32_16x16x32_bf16 v[88:91], v[170:173], v[210:213], v[88:91]
	v_mfma_f32_16x16x32_bf16 v[88:91], v[174:177], v[214:217], v[88:91]
	v_mfma_f32_16x16x32_bf16 v[76:79], v[154:157], v[218:221], v[76:79]
	v_mfma_f32_16x16x32_bf16 v[76:79], v[158:161], v[222:225], v[76:79]
	v_mfma_f32_16x16x32_bf16 v[72:75], v[170:173], v[218:221], v[72:75]
	v_mfma_f32_16x16x32_bf16 v[72:75], v[174:177], v[222:225], v[72:75]
	s_setprio 0
	s_setprio 1
	v_mfma_f32_16x16x32_bf16 v[116:119], v[178:181], v[194:197], v[116:119]
	v_mfma_f32_16x16x32_bf16 v[116:119], v[182:185], v[198:201], v[116:119]
	v_mfma_f32_16x16x32_bf16 v[112:115], v[186:189], v[194:197], v[112:115]
	v_mfma_f32_16x16x32_bf16 v[112:115], v[190:193], v[198:201], v[112:115]
	v_mfma_f32_16x16x32_bf16 v[100:103], v[178:181], v[202:205], v[100:103]
	v_mfma_f32_16x16x32_bf16 v[100:103], v[182:185], v[206:209], v[100:103]
	v_mfma_f32_16x16x32_bf16 v[96:99], v[186:189], v[202:205], v[96:99]
	v_mfma_f32_16x16x32_bf16 v[96:99], v[190:193], v[206:209], v[96:99]
	v_mfma_f32_16x16x32_bf16 v[84:87], v[178:181], v[210:213], v[84:87]
	v_mfma_f32_16x16x32_bf16 v[84:87], v[182:185], v[214:217], v[84:87]
	v_mfma_f32_16x16x32_bf16 v[80:83], v[186:189], v[210:213], v[80:83]
	v_mfma_f32_16x16x32_bf16 v[80:83], v[190:193], v[214:217], v[80:83]
	v_mfma_f32_16x16x32_bf16 v[68:71], v[178:181], v[218:221], v[68:71]
	v_mfma_f32_16x16x32_bf16 v[68:71], v[182:185], v[222:225], v[68:71]
	v_mfma_f32_16x16x32_bf16 v[64:67], v[186:189], v[218:221], v[64:67]
	v_mfma_f32_16x16x32_bf16 v[64:67], v[190:193], v[222:225], v[64:67]
	s_setprio 0
	s_barrier
	s_add_i32 s54, s44, s27
	v_lshl_add_u64 v[144:145], s[18:19], 0, v[132:133]
	s_mov_b32 m0, s54
	ds_read_b128 v[194:197], v152 offset:16384
	ds_read_b128 v[198:201], v152 offset:17408
	ds_read_b128 v[202:205], v152 offset:18432
	ds_read_b128 v[206:209], v152 offset:19456
	ds_read_b128 v[210:213], v152 offset:20480
	ds_read_b128 v[214:217], v152 offset:21504
	ds_read_b128 v[218:221], v152 offset:22528
	ds_read_b128 v[222:225], v152 offset:23552
	global_load_lds_dwordx4 v[144:145], off
	s_add_i32 m0, s54, 0x2000
	s_add_u32 s54, s18, 0x84000
	v_lshl_add_u64 v[162:163], s[18:19], 0, v[128:129]
	s_addc_u32 s55, s19, 0
	s_add_i32 s56, s45, s27
	global_load_lds_dwordx4 v[162:163], off
	v_lshl_add_u64 v[166:167], s[54:55], 0, v[132:133]
	s_mov_b32 m0, s56
	v_lshl_add_u64 v[226:227], s[20:21], 0, v[130:131]
	global_load_lds_dwordx4 v[166:167], off
	v_lshl_add_u64 v[166:167], s[54:55], 0, v[128:129]
	s_add_i32 m0, s56, 0x2000
	s_nop 0
	global_load_lds_dwordx4 v[166:167], off
	v_lshl_add_u64 v[166:167], s[20:21], 0, v[134:135]
	s_mov_b32 m0, s36
	s_nop 0
	global_load_lds_dwordx4 v[166:167], off
	s_mov_b32 m0, s37
	s_nop 0
	global_load_lds_dwordx4 v[226:227], off
	s_waitcnt vmcnt(8)
	s_waitcnt lgkmcnt(0)
	s_barrier
; #define PG8_STAGE(bufoff, gbase, voff) do { _Pragma("unroll") for (int _i = 0; _i < 2; ++_i) \
;         __builtin_amdgcn_global_load_lds((const unsigned*)((const char*)(gbase) + (voff)[_i]), (LAS unsigned*)(lds + (bufoff) + ldsw + _i * 8192), 16, 0, 0); } while (0)
; #define PG8_LDA(dst, b, h) do { _Pragma("unroll") for (int m = 0; m < 4; ++m) _Pragma("unroll") for (int k = 0; k < 2; ++k) dst[m][k] = *(const LAS bf16x8*)(lds + PG8_SA(b, h) + aoff + m * 2048 + k * 1024); } while (0)
; #define PG8_LDB(dst, b, h) do { _Pragma("unroll") for (int n = 0; n < 2; ++n) _Pragma("unroll") for (int k = 0; k < 2; ++k) dst[n][k] = *(const LAS bf16x8*)(lds + PG8_SB(b, h) + boff + n * 2048 + k * 1024); } while (0)
; #define PG8_MMA(ai, bj, At, Bt) do { __builtin_amdgcn_s_setprio(1); _Pragma("unroll") for (int m = 0; m < 4; ++m) _Pragma("unroll") for (int n = 0; n < 2; ++n) _Pragma("unroll") for (int k = 0; k < 2; ++k) \
;         acc[ai][bj][m][n] = __builtin_amdgcn_mfma_f32_16x16x32_bf16(Bt[n][k], At[m][k], acc[ai][bj][m][n], 0, 0, 0); __builtin_amdgcn_s_setprio(0); } while (0)
; #define PG8_WAIT_V(n) asm volatile("s_waitcnt vmcnt(" #n ")" ::: "memory")
; #define PG8_WAIT_L(n) asm volatile("s_waitcnt lgkmcnt(" #n ")" ::: "memory")
; #define PG8_BAR __builtin_amdgcn_s_barrier()
; #define PG8_SCHED __builtin_amdgcn_sched_barrier(0)
; template <class EpiT>
; __device__ __forceinline__ void gemm_phase(LAS unsigned char* lds, const Gemm g, const StaticOrder& S, const EpiT& E) {
;     ...
;             PG8_WAIT_V(8); PG8_WAIT_L(0); PG8_BAR; PG8_MMA(1, 0, At, B0); PG8_MMA(1, 1, At, B1); PG8_BAR; PG8_SCHED;
;             PG8_LDB(B0, 1, 0); PG8_LDB(B1, 1, 1); PG8_SCHED; PG8_LDA(At, 1, 0); PG8_STAGE(PG8_SA(0, 1), a2 + hstepA, voffA);
;             PG8_WAIT_V(8); PG8_WAIT_L(0); PG8_BAR; PG8_MMA(0, 0, At, B0); PG8_MMA(0, 1, At, B1); PG8_BAR; PG8_SCHED;
	s_setprio 1
	s_waitcnt lgkmcnt(0)
	v_mfma_f32_16x16x32_bf16 v[60:63], v[154:157], v[194:197], v[60:63]
	v_mfma_f32_16x16x32_bf16 v[60:63], v[158:161], v[198:201], v[60:63]
	v_mfma_f32_16x16x32_bf16 v[56:59], v[170:173], v[194:197], v[56:59]
	v_mfma_f32_16x16x32_bf16 v[56:59], v[174:177], v[198:201], v[56:59]
	v_mfma_f32_16x16x32_bf16 v[44:47], v[154:157], v[202:205], v[44:47]
	v_mfma_f32_16x16x32_bf16 v[44:47], v[158:161], v[206:209], v[44:47]
	v_mfma_f32_16x16x32_bf16 v[40:43], v[170:173], v[202:205], v[40:43]
	v_mfma_f32_16x16x32_bf16 v[40:43], v[174:177], v[206:209], v[40:43]
	v_mfma_f32_16x16x32_bf16 v[28:31], v[154:157], v[210:213], v[28:31]
	v_mfma_f32_16x16x32_bf16 v[28:31], v[158:161], v[214:217], v[28:31]
	v_mfma_f32_16x16x32_bf16 v[24:27], v[170:173], v[210:213], v[24:27]
	v_mfma_f32_16x16x32_bf16 v[24:27], v[174:177], v[214:217], v[24:27]
	v_mfma_f32_16x16x32_bf16 v[12:15], v[154:157], v[218:221], v[12:15]
	v_mfma_f32_16x16x32_bf16 v[12:15], v[158:161], v[222:225], v[12:15]
	v_mfma_f32_16x16x32_bf16 v[8:11], v[170:173], v[218:221], v[8:11]
	v_mfma_f32_16x16x32_bf16 v[8:11], v[174:177], v[222:225], v[8:11]
	s_setprio 0
	s_setprio 1
	v_mfma_f32_16x16x32_bf16 v[52:55], v[178:181], v[194:197], v[52:55]
	v_mfma_f32_16x16x32_bf16 v[52:55], v[182:185], v[198:201], v[52:55]
	v_mfma_f32_16x16x32_bf16 v[48:51], v[186:189], v[194:197], v[48:51]
	v_mfma_f32_16x16x32_bf16 v[48:51], v[190:193], v[198:201], v[48:51]
	v_mfma_f32_16x16x32_bf16 v[36:39], v[178:181], v[202:205], v[36:39]
	v_mfma_f32_16x16x32_bf16 v[36:39], v[182:185], v[206:209], v[36:39]
	v_mfma_f32_16x16x32_bf16 v[32:35], v[186:189], v[202:205], v[32:35]
	v_mfma_f32_16x16x32_bf16 v[32:35], v[190:193], v[206:209], v[32:35]
	v_mfma_f32_16x16x32_bf16 v[20:23], v[178:181], v[210:213], v[20:23]
	v_mfma_f32_16x16x32_bf16 v[20:23], v[182:185], v[214:217], v[20:23]
	v_mfma_f32_16x16x32_bf16 v[16:19], v[186:189], v[210:213], v[16:19]
	v_mfma_f32_16x16x32_bf16 v[16:19], v[190:193], v[214:217], v[16:19]
	v_mfma_f32_16x16x32_bf16 v[4:7], v[178:181], v[218:221], v[4:7]
	v_mfma_f32_16x16x32_bf16 v[4:7], v[182:185], v[222:225], v[4:7]
	v_mfma_f32_16x16x32_bf16 v[0:3], v[186:189], v[218:221], v[0:3]
	v_mfma_f32_16x16x32_bf16 v[0:3], v[190:193], v[222:225], v[0:3]
	s_setprio 0
	s_barrier
	s_add_i32 s54, 0, 0x18000
	v_add_u32_e32 v153, s54, v147
	s_add_i32 s55, 0, 0x1c000
	ds_read_b128 v[154:157], v153
	ds_read_b128 v[158:161], v153 offset:1024
	ds_read_b128 v[170:173], v153 offset:2048
	ds_read_b128 v[174:177], v153 offset:3072
	v_add_u32_e32 v153, s55, v147
	ds_read_b128 v[178:181], v153
	ds_read_b128 v[182:185], v153 offset:1024
	ds_read_b128 v[186:189], v153 offset:2048
	ds_read_b128 v[190:193], v153 offset:3072
	s_add_u32 s20, s20, 0x84000
	s_addc_u32 s21, s21, 0
	s_mov_b32 m0, s38
	v_lshl_add_u64 v[228:229], s[20:21], 0, v[134:135]
	ds_read_b128 v[194:197], v152 offset:32768
	ds_read_b128 v[198:201], v152 offset:33792
	ds_read_b128 v[202:205], v152 offset:34816
	ds_read_b128 v[206:209], v152 offset:35840
	ds_read_b128 v[210:213], v152 offset:36864
	ds_read_b128 v[214:217], v152 offset:37888
	ds_read_b128 v[218:221], v152 offset:38912
	ds_read_b128 v[222:225], v152 offset:39936
	global_load_lds_dwordx4 v[228:229], off
	v_lshl_add_u64 v[228:229], s[20:21], 0, v[130:131]
	s_mov_b32 m0, s39
	s_nop 0
	global_load_lds_dwordx4 v[228:229], off
	s_waitcnt vmcnt(8)
	s_waitcnt lgkmcnt(0)
	s_barrier
	s_setprio 1
	s_waitcnt lgkmcnt(0)
	v_mfma_f32_16x16x32_bf16 v[124:127], v[154:157], v[194:197], v[124:127]
	v_mfma_f32_16x16x32_bf16 v[124:127], v[158:161], v[198:201], v[124:127]
	v_mfma_f32_16x16x32_bf16 v[120:123], v[170:173], v[194:197], v[120:123]
	v_mfma_f32_16x16x32_bf16 v[120:123], v[174:177], v[198:201], v[120:123]
	v_mfma_f32_16x16x32_bf16 v[108:111], v[154:157], v[202:205], v[108:111]
	v_mfma_f32_16x16x32_bf16 v[108:111], v[158:161], v[206:209], v[108:111]
	v_mfma_f32_16x16x32_bf16 v[104:107], v[170:173], v[202:205], v[104:107]
	v_mfma_f32_16x16x32_bf16 v[104:107], v[174:177], v[206:209], v[104:107]
	v_mfma_f32_16x16x32_bf16 v[92:95], v[154:157], v[210:213], v[92:95]
	v_mfma_f32_16x16x32_bf16 v[92:95], v[158:161], v[214:217], v[92:95]
	v_mfma_f32_16x16x32_bf16 v[88:91], v[170:173], v[210:213], v[88:91]
	v_mfma_f32_16x16x32_bf16 v[88:91], v[174:177], v[214:217], v[88:91]
	v_mfma_f32_16x16x32_bf16 v[76:79], v[154:157], v[218:221], v[76:79]
	v_mfma_f32_16x16x32_bf16 v[76:79], v[158:161], v[222:225], v[76:79]
	v_mfma_f32_16x16x32_bf16 v[72:75], v[170:173], v[218:221], v[72:75]
	v_mfma_f32_16x16x32_bf16 v[72:75], v[174:177], v[222:225], v[72:75]
	s_setprio 0
	s_setprio 1
	v_mfma_f32_16x16x32_bf16 v[116:119], v[178:181], v[194:197], v[116:119]
	v_mfma_f32_16x16x32_bf16 v[116:119], v[182:185], v[198:201], v[116:119]
	v_mfma_f32_16x16x32_bf16 v[112:115], v[186:189], v[194:197], v[112:115]
	v_mfma_f32_16x16x32_bf16 v[112:115], v[190:193], v[198:201], v[112:115]
	v_mfma_f32_16x16x32_bf16 v[100:103], v[178:181], v[202:205], v[100:103]
	v_mfma_f32_16x16x32_bf16 v[100:103], v[182:185], v[206:209], v[100:103]
	v_mfma_f32_16x16x32_bf16 v[96:99], v[186:189], v[202:205], v[96:99]
	v_mfma_f32_16x16x32_bf16 v[96:99], v[190:193], v[206:209], v[96:99]
	v_mfma_f32_16x16x32_bf16 v[84:87], v[178:181], v[210:213], v[84:87]
	v_mfma_f32_16x16x32_bf16 v[84:87], v[182:185], v[214:217], v[84:87]
	v_mfma_f32_16x16x32_bf16 v[80:83], v[186:189], v[210:213], v[80:83]
	v_mfma_f32_16x16x32_bf16 v[80:83], v[190:193], v[214:217], v[80:83]
	v_mfma_f32_16x16x32_bf16 v[68:71], v[178:181], v[218:221], v[68:71]
	v_mfma_f32_16x16x32_bf16 v[68:71], v[182:185], v[222:225], v[68:71]
	v_mfma_f32_16x16x32_bf16 v[64:67], v[186:189], v[218:221], v[64:67]
	v_mfma_f32_16x16x32_bf16 v[64:67], v[190:193], v[222:225], v[64:67]
	s_setprio 0
	s_barrier
; #define PG8_STAGE(bufoff, gbase, voff) do { _Pragma("unroll") for (int _i = 0; _i < 2; ++_i) \
;         __builtin_amdgcn_global_load_lds((const unsigned*)((const char*)(gbase) + (voff)[_i]), (LAS unsigned*)(lds + (bufoff) + ldsw + _i * 8192), 16, 0, 0); } while (0)
; #define PG8_LDA(dst, b, h) do { _Pragma("unroll") for (int m = 0; m < 4; ++m) _Pragma("unroll") for (int k = 0; k < 2; ++k) dst[m][k] = *(const LAS bf16x8*)(lds + PG8_SA(b, h) + aoff + m * 2048 + k * 1024); } while (0)
; #define PG8_MMA(ai, bj, At, Bt) do { __builtin_amdgcn_s_setprio(1); _Pragma("unroll") for (int m = 0; m < 4; ++m) _Pragma("unroll") for (int n = 0; n < 2; ++n) _Pragma("unroll") for (int k = 0; k < 2; ++k) \
;         acc[ai][bj][m][n] = __builtin_amdgcn_mfma_f32_16x16x32_bf16(Bt[n][k], At[m][k], acc[ai][bj][m][n], 0, 0, 0); __builtin_amdgcn_s_setprio(0); } while (0)
; #define PG8_WAIT_V(n) asm volatile("s_waitcnt vmcnt(" #n ")" ::: "memory")
; #define PG8_WAIT_L(n) asm volatile("s_waitcnt lgkmcnt(" #n ")" ::: "memory")
; #define PG8_BAR __builtin_amdgcn_s_barrier()
; #define PG8_SCHED __builtin_amdgcn_sched_barrier(0)
; template <class EpiT>
; __device__ __forceinline__ void gemm_phase(LAS unsigned char* lds, const Gemm g, const StaticOrder& S, const EpiT& E) {
;     ...
;             PG8_LDA(At, 1, 1); PG8_STAGE(PG8_SB(1, 0), b3, voffB); PG8_STAGE(PG8_SB(1, 1), b3 + hstepB, voffB); PG8_STAGE(PG8_SA(1, 0), a3, voffA);
;             PG8_WAIT_V(8); PG8_WAIT_L(0); PG8_BAR; PG8_MMA(1, 0, At, B0); PG8_MMA(1, 1, At, B1); PG8_BAR; PG8_SCHED;
;         }
;         if (wr == 0) PG8_BAR;
	s_add_i32 s20, s54, s27
	v_lshl_add_u64 v[144:145], v[144:145], 0, s[10:11]
	s_mov_b32 m0, s20
	ds_read_b128 v[194:197], v152 offset:49152
	ds_read_b128 v[198:201], v152 offset:50176
	ds_read_b128 v[202:205], v152 offset:51200
	ds_read_b128 v[206:209], v152 offset:52224
	ds_read_b128 v[210:213], v152 offset:53248
	ds_read_b128 v[214:217], v152 offset:54272
	ds_read_b128 v[218:221], v152 offset:55296
	ds_read_b128 v[222:225], v152 offset:56320
	global_load_lds_dwordx4 v[144:145], off
	s_add_i32 m0, s20, 0x2000
	s_add_u32 s18, s18, 0x84080
	v_lshl_add_u64 v[144:145], v[162:163], 0, s[10:11]
	s_addc_u32 s19, s19, 0
	s_add_i32 s20, s55, s27
	global_load_lds_dwordx4 v[144:145], off
	v_lshl_add_u64 v[144:145], s[18:19], 0, v[132:133]
	s_mov_b32 m0, s20
	s_nop 0
	global_load_lds_dwordx4 v[144:145], off
	v_lshl_add_u64 v[144:145], s[18:19], 0, v[128:129]
	s_add_i32 m0, s20, 0x2000
	s_nop 0
	global_load_lds_dwordx4 v[144:145], off
	v_lshl_add_u64 v[144:145], v[166:167], 0, s[10:11]
	s_mov_b32 m0, s41
	s_nop 0
	global_load_lds_dwordx4 v[144:145], off
	v_lshl_add_u64 v[144:145], v[226:227], 0, s[10:11]
	s_mov_b32 m0, s42
	s_nop 0
	global_load_lds_dwordx4 v[144:145], off
	s_waitcnt vmcnt(8)
	s_waitcnt lgkmcnt(0)
	s_barrier
	s_setprio 1
	s_waitcnt lgkmcnt(0)
	v_mfma_f32_16x16x32_bf16 v[60:63], v[154:157], v[194:197], v[60:63]
	v_mfma_f32_16x16x32_bf16 v[60:63], v[158:161], v[198:201], v[60:63]
	v_mfma_f32_16x16x32_bf16 v[56:59], v[170:173], v[194:197], v[56:59]
	v_mfma_f32_16x16x32_bf16 v[56:59], v[174:177], v[198:201], v[56:59]
	v_mfma_f32_16x16x32_bf16 v[44:47], v[154:157], v[202:205], v[44:47]
	v_mfma_f32_16x16x32_bf16 v[44:47], v[158:161], v[206:209], v[44:47]
	v_mfma_f32_16x16x32_bf16 v[40:43], v[170:173], v[202:205], v[40:43]
	v_mfma_f32_16x16x32_bf16 v[40:43], v[174:177], v[206:209], v[40:43]
	v_mfma_f32_16x16x32_bf16 v[28:31], v[154:157], v[210:213], v[28:31]
	v_mfma_f32_16x16x32_bf16 v[28:31], v[158:161], v[214:217], v[28:31]
	v_mfma_f32_16x16x32_bf16 v[24:27], v[170:173], v[210:213], v[24:27]
	v_mfma_f32_16x16x32_bf16 v[24:27], v[174:177], v[214:217], v[24:27]
	v_mfma_f32_16x16x32_bf16 v[12:15], v[154:157], v[218:221], v[12:15]
	v_mfma_f32_16x16x32_bf16 v[12:15], v[158:161], v[222:225], v[12:15]
	v_mfma_f32_16x16x32_bf16 v[8:11], v[170:173], v[218:221], v[8:11]
	v_mfma_f32_16x16x32_bf16 v[8:11], v[174:177], v[222:225], v[8:11]
	s_setprio 0
	s_setprio 1
	v_mfma_f32_16x16x32_bf16 v[52:55], v[178:181], v[194:197], v[52:55]
	v_mfma_f32_16x16x32_bf16 v[52:55], v[182:185], v[198:201], v[52:55]
	v_mfma_f32_16x16x32_bf16 v[48:51], v[186:189], v[194:197], v[48:51]
	v_mfma_f32_16x16x32_bf16 v[48:51], v[190:193], v[198:201], v[48:51]
	v_mfma_f32_16x16x32_bf16 v[36:39], v[178:181], v[202:205], v[36:39]
	v_mfma_f32_16x16x32_bf16 v[36:39], v[182:185], v[206:209], v[36:39]
	v_mfma_f32_16x16x32_bf16 v[32:35], v[186:189], v[202:205], v[32:35]
	v_mfma_f32_16x16x32_bf16 v[32:35], v[190:193], v[206:209], v[32:35]
	v_mfma_f32_16x16x32_bf16 v[20:23], v[178:181], v[210:213], v[20:23]
	v_mfma_f32_16x16x32_bf16 v[20:23], v[182:185], v[214:217], v[20:23]
	v_mfma_f32_16x16x32_bf16 v[16:19], v[186:189], v[210:213], v[16:19]
	v_mfma_f32_16x16x32_bf16 v[16:19], v[190:193], v[214:217], v[16:19]
	v_mfma_f32_16x16x32_bf16 v[4:7], v[178:181], v[218:221], v[4:7]
	v_mfma_f32_16x16x32_bf16 v[4:7], v[182:185], v[222:225], v[4:7]
	v_mfma_f32_16x16x32_bf16 v[0:3], v[186:189], v[218:221], v[0:3]
	v_mfma_f32_16x16x32_bf16 v[0:3], v[190:193], v[222:225], v[0:3]
	s_setprio 0
	s_barrier
	s_add_i32 s53, s53, 2
	s_add_u32 s16, s16, 0x100
	s_addc_u32 s17, s17, 0
	s_add_u32 s51, s51, 0x100
	s_addc_u32 s52, s52, 0
	s_cmp_gt_u32 s53, 29
	s_cbranch_scc0 .LBB0_516
	s_and_b64 vcc, exec, s[12:13]
	s_cbranch_vccz .LBB0_519
	s_barrier

; #define PG8_STAGE(bufoff, gbase, voff) do { _Pragma("unroll") for (int _i = 0; _i < 2; ++_i) \
;         __builtin_amdgcn_global_load_lds((const unsigned*)((const char*)(gbase) + (voff)[_i]), (LAS unsigned*)(lds + (bufoff) + ldsw + _i * 8192), 16, 0, 0); } while (0)
; #define PG8_LDA(dst, b, h) do { _Pragma("unroll") for (int m = 0; m < 4; ++m) _Pragma("unroll") for (int k = 0; k < 2; ++k) dst[m][k] = *(const LAS bf16x8*)(lds + PG8_SA(b, h) + aoff + m * 2048 + k * 1024); } while (0)
; #define PG8_LDB(dst, b, h) do { _Pragma("unroll") for (int n = 0; n < 2; ++n) _Pragma("unroll") for (int k = 0; k < 2; ++k) dst[n][k] = *(const LAS bf16x8*)(lds + PG8_SB(b, h) + boff + n * 2048 + k * 1024); } while (0)
; #define PG8_MMA(ai, bj, At, Bt) do { __builtin_amdgcn_s_setprio(1); _Pragma("unroll") for (int m = 0; m < 4; ++m) _Pragma("unroll") for (int n = 0; n < 2; ++n) _Pragma("unroll") for (int k = 0; k < 2; ++k) \
;         acc[ai][bj][m][n] = __builtin_amdgcn_mfma_f32_16x16x32_bf16(Bt[n][k], At[m][k], acc[ai][bj][m][n], 0, 0, 0); __builtin_amdgcn_s_setprio(0); } while (0)
; #define PG8_WAIT_V(n) asm volatile("s_waitcnt vmcnt(" #n ")" ::: "memory")
; #define PG8_WAIT_L(n) asm volatile("s_waitcnt lgkmcnt(" #n ")" ::: "memory")
; #define PG8_BAR __builtin_amdgcn_s_barrier()
; #define PG8_SCHED __builtin_amdgcn_sched_barrier(0)
; template <class EpiT>
; __device__ __forceinline__ void gemm_phase(LAS unsigned char* lds, const Gemm g, const StaticOrder& S, const EpiT& E) {
;     ...
;         for (int t = 0; t < nt; t += 2) {
;             const bool last = (t == nt - 2);
;             const char* a1 = cA + (size_t)(t + 1) * kstep;
;             const char* a2 = last ? nA : cA + (size_t)(t + 2) * kstep; const char* b2 = last ? nB : cB + (size_t)(t + 2) * kstep;
;             const char* a3 = a2 + kstep; const char* b3 = b2 + kstep;
;             PG8_LDB(B0, 0, 0); PG8_LDB(B1, 0, 1); PG8_SCHED; PG8_LDA(At, 0, 0); PG8_STAGE(PG8_SA(1, 1), a1 + hstepA, voffA);
;             PG8_WAIT_V(8); PG8_WAIT_L(0); PG8_BAR; PG8_MMA(0, 0, At, B0); PG8_MMA(0, 1, At, B1); PG8_BAR; PG8_SCHED;
;             PG8_LDA(At, 0, 1); PG8_STAGE(PG8_SB(0, 0), b2, voffB); PG8_STAGE(PG8_SB(0, 1), b2 + hstepB, voffB); PG8_STAGE(PG8_SA(0, 0), a2, voffA);
.LBB0_595:
	ds_read_b128 v[154:157], v150
	ds_read_b128 v[158:161], v150 offset:1024
	ds_read_b128 v[170:173], v150 offset:2048
	ds_read_b128 v[174:177], v150 offset:3072
	ds_read_b128 v[178:181], v151
	ds_read_b128 v[182:185], v151 offset:1024
	ds_read_b128 v[186:189], v151 offset:2048
	ds_read_b128 v[190:193], v151 offset:3072
	s_add_u32 s20, s18, 0xffe9c080
	s_addc_u32 s21, s19, -1
	s_cmpk_eq_i32 s55, 0x54
	s_cselect_b32 s23, s5, s21
	s_cselect_b32 s22, s4, s20
	s_cselect_b32 s21, s17, s54
	s_cselect_b32 s20, s16, s53
	v_lshl_add_u64 v[162:163], s[18:19], 0, v[138:139]
	s_add_i32 m0, s37, 0xc000
	ds_read_b128 v[194:197], v152
	ds_read_b128 v[198:201], v152 offset:1024
	ds_read_b128 v[202:205], v152 offset:2048
	ds_read_b128 v[206:209], v152 offset:3072
	ds_read_b128 v[210:213], v152 offset:4096
	ds_read_b128 v[214:217], v152 offset:5120
	ds_read_b128 v[218:221], v152 offset:6144
	ds_read_b128 v[222:225], v152 offset:7168
	global_load_lds_dwordx4 v[162:163], off
	v_lshl_add_u64 v[162:163], s[18:19], 0, v[140:141]
	s_add_i32 m0, s37, 0xe000
	s_nop 0
	global_load_lds_dwordx4 v[162:163], off
	s_waitcnt vmcnt(8)
	s_waitcnt lgkmcnt(0)
	s_barrier
	s_setprio 1
	s_waitcnt lgkmcnt(0)
	v_mfma_f32_16x16x32_bf16 v[124:127], v[154:157], v[194:197], v[124:127]
	v_mfma_f32_16x16x32_bf16 v[124:127], v[158:161], v[198:201], v[124:127]
	v_mfma_f32_16x16x32_bf16 v[120:123], v[170:173], v[194:197], v[120:123]
	v_mfma_f32_16x16x32_bf16 v[120:123], v[174:177], v[198:201], v[120:123]
	v_mfma_f32_16x16x32_bf16 v[108:111], v[154:157], v[202:205], v[108:111]
	v_mfma_f32_16x16x32_bf16 v[108:111], v[158:161], v[206:209], v[108:111]
	v_mfma_f32_16x16x32_bf16 v[104:107], v[170:173], v[202:205], v[104:107]
	v_mfma_f32_16x16x32_bf16 v[104:107], v[174:177], v[206:209], v[104:107]
	v_mfma_f32_16x16x32_bf16 v[92:95], v[154:157], v[210:213], v[92:95]
	v_mfma_f32_16x16x32_bf16 v[92:95], v[158:161], v[214:217], v[92:95]
	v_mfma_f32_16x16x32_bf16 v[88:91], v[170:173], v[210:213], v[88:91]
	v_mfma_f32_16x16x32_bf16 v[88:91], v[174:177], v[214:217], v[88:91]
	v_mfma_f32_16x16x32_bf16 v[76:79], v[154:157], v[218:221], v[76:79]
	v_mfma_f32_16x16x32_bf16 v[76:79], v[158:161], v[222:225], v[76:79]
	v_mfma_f32_16x16x32_bf16 v[72:75], v[170:173], v[218:221], v[72:75]
	v_mfma_f32_16x16x32_bf16 v[72:75], v[174:177], v[222:225], v[72:75]
	s_setprio 0
	s_setprio 1
	v_mfma_f32_16x16x32_bf16 v[116:119], v[178:181], v[194:197], v[116:119]
	v_mfma_f32_16x16x32_bf16 v[116:119], v[182:185], v[198:201], v[116:119]
	v_mfma_f32_16x16x32_bf16 v[112:115], v[186:189], v[194:197], v[112:115]
	v_mfma_f32_16x16x32_bf16 v[112:115], v[190:193], v[198:201], v[112:115]
	v_mfma_f32_16x16x32_bf16 v[100:103], v[178:181], v[202:205], v[100:103]
	v_mfma_f32_16x16x32_bf16 v[100:103], v[182:185], v[206:209], v[100:103]
	v_mfma_f32_16x16x32_bf16 v[96:99], v[186:189], v[202:205], v[96:99]
	v_mfma_f32_16x16x32_bf16 v[96:99], v[190:193], v[206:209], v[96:99]
	v_mfma_f32_16x16x32_bf16 v[84:87], v[178:181], v[210:213], v[84:87]
	v_mfma_f32_16x16x32_bf16 v[84:87], v[182:185], v[214:217], v[84:87]
	v_mfma_f32_16x16x32_bf16 v[80:83], v[186:189], v[210:213], v[80:83]
	v_mfma_f32_16x16x32_bf16 v[80:83], v[190:193], v[214:217], v[80:83]
	v_mfma_f32_16x16x32_bf16 v[68:71], v[178:181], v[218:221], v[68:71]
	v_mfma_f32_16x16x32_bf16 v[68:71], v[182:185], v[222:225], v[68:71]
	v_mfma_f32_16x16x32_bf16 v[64:67], v[186:189], v[218:221], v[64:67]
	v_mfma_f32_16x16x32_bf16 v[64:67], v[190:193], v[222:225], v[64:67]
	s_setprio 0
	s_barrier
	s_add_i32 s56, s46, s36
	v_lshl_add_u64 v[162:163], s[20:21], 0, v[130:131]
	s_mov_b32 m0, s56
	ds_read_b128 v[194:197], v152 offset:16384
	ds_read_b128 v[198:201], v152 offset:17408
	ds_read_b128 v[202:205], v152 offset:18432
	ds_read_b128 v[206:209], v152 offset:19456
	ds_read_b128 v[210:213], v152 offset:20480
	ds_read_b128 v[214:217], v152 offset:21504
	ds_read_b128 v[218:221], v152 offset:22528
	ds_read_b128 v[222:225], v152 offset:23552
	global_load_lds_dwordx4 v[162:163], off
	s_add_i32 m0, s56, 0x2000
	s_add_u32 s56, s20, 0x164000
	v_lshl_add_u64 v[166:167], s[20:21], 0, v[134:135]
	s_addc_u32 s57, s21, 0
	s_add_i32 s58, s47, s36
	global_load_lds_dwordx4 v[166:167], off
	v_lshl_add_u64 v[226:227], s[56:57], 0, v[130:131]
	s_mov_b32 m0, s58
	v_lshl_add_u64 v[228:229], s[22:23], 0, v[132:133]
	global_load_lds_dwordx4 v[226:227], off
	v_lshl_add_u64 v[226:227], s[56:57], 0, v[134:135]
	s_add_i32 m0, s58, 0x2000
	s_nop 0
	global_load_lds_dwordx4 v[226:227], off
	v_lshl_add_u64 v[226:227], s[22:23], 0, v[128:129]
	s_mov_b32 m0, s37
	s_nop 0
	global_load_lds_dwordx4 v[226:227], off
	s_mov_b32 m0, s38
	s_nop 0
	global_load_lds_dwordx4 v[228:229], off
	s_waitcnt vmcnt(8)
	s_waitcnt lgkmcnt(0)
	s_barrier
; #define PG8_STAGE(bufoff, gbase, voff) do { _Pragma("unroll") for (int _i = 0; _i < 2; ++_i) \
;         __builtin_amdgcn_global_load_lds((const unsigned*)((const char*)(gbase) + (voff)[_i]), (LAS unsigned*)(lds + (bufoff) + ldsw + _i * 8192), 16, 0, 0); } while (0)
; #define PG8_LDA(dst, b, h) do { _Pragma("unroll") for (int m = 0; m < 4; ++m) _Pragma("unroll") for (int k = 0; k < 2; ++k) dst[m][k] = *(const LAS bf16x8*)(lds + PG8_SA(b, h) + aoff + m * 2048 + k * 1024); } while (0)
; #define PG8_LDB(dst, b, h) do { _Pragma("unroll") for (int n = 0; n < 2; ++n) _Pragma("unroll") for (int k = 0; k < 2; ++k) dst[n][k] = *(const LAS bf16x8*)(lds + PG8_SB(b, h) + boff + n * 2048 + k * 1024); } while (0)
; #define PG8_MMA(ai, bj, At, Bt) do { __builtin_amdgcn_s_setprio(1); _Pragma("unroll") for (int m = 0; m < 4; ++m) _Pragma("unroll") for (int n = 0; n < 2; ++n) _Pragma("unroll") for (int k = 0; k < 2; ++k) \
;         acc[ai][bj][m][n] = __builtin_amdgcn_mfma_f32_16x16x32_bf16(Bt[n][k], At[m][k], acc[ai][bj][m][n], 0, 0, 0); __builtin_amdgcn_s_setprio(0); } while (0)
; #define PG8_WAIT_V(n) asm volatile("s_waitcnt vmcnt(" #n ")" ::: "memory")
; #define PG8_WAIT_L(n) asm volatile("s_waitcnt lgkmcnt(" #n ")" ::: "memory")
; #define PG8_BAR __builtin_amdgcn_s_barrier()
; #define PG8_SCHED __builtin_amdgcn_sched_barrier(0)
; template <class EpiT>
; __device__ __forceinline__ void gemm_phase(LAS unsigned char* lds, const Gemm g, const StaticOrder& S, const EpiT& E) {
;     ...
;             PG8_WAIT_V(8); PG8_WAIT_L(0); PG8_BAR; PG8_MMA(1, 0, At, B0); PG8_MMA(1, 1, At, B1); PG8_BAR; PG8_SCHED;
;             PG8_LDB(B0, 1, 0); PG8_LDB(B1, 1, 1); PG8_SCHED; PG8_LDA(At, 1, 0); PG8_STAGE(PG8_SA(0, 1), a2 + hstepA, voffA);
;             PG8_WAIT_V(8); PG8_WAIT_L(0); PG8_BAR; PG8_MMA(0, 0, At, B0); PG8_MMA(0, 1, At, B1); PG8_BAR; PG8_SCHED;
	s_setprio 1
	s_waitcnt lgkmcnt(0)
	v_mfma_f32_16x16x32_bf16 v[60:63], v[154:157], v[194:197], v[60:63]
	v_mfma_f32_16x16x32_bf16 v[60:63], v[158:161], v[198:201], v[60:63]
	v_mfma_f32_16x16x32_bf16 v[56:59], v[170:173], v[194:197], v[56:59]
	v_mfma_f32_16x16x32_bf16 v[56:59], v[174:177], v[198:201], v[56:59]
	v_mfma_f32_16x16x32_bf16 v[44:47], v[154:157], v[202:205], v[44:47]
	v_mfma_f32_16x16x32_bf16 v[44:47], v[158:161], v[206:209], v[44:47]
	v_mfma_f32_16x16x32_bf16 v[40:43], v[170:173], v[202:205], v[40:43]
	v_mfma_f32_16x16x32_bf16 v[40:43], v[174:177], v[206:209], v[40:43]
	v_mfma_f32_16x16x32_bf16 v[28:31], v[154:157], v[210:213], v[28:31]
	v_mfma_f32_16x16x32_bf16 v[28:31], v[158:161], v[214:217], v[28:31]
	v_mfma_f32_16x16x32_bf16 v[24:27], v[170:173], v[210:213], v[24:27]
	v_mfma_f32_16x16x32_bf16 v[24:27], v[174:177], v[214:217], v[24:27]
	v_mfma_f32_16x16x32_bf16 v[12:15], v[154:157], v[218:221], v[12:15]
	v_mfma_f32_16x16x32_bf16 v[12:15], v[158:161], v[222:225], v[12:15]
	v_mfma_f32_16x16x32_bf16 v[8:11], v[170:173], v[218:221], v[8:11]
	v_mfma_f32_16x16x32_bf16 v[8:11], v[174:177], v[222:225], v[8:11]
	s_setprio 0
	s_setprio 1
	v_mfma_f32_16x16x32_bf16 v[52:55], v[178:181], v[194:197], v[52:55]
	v_mfma_f32_16x16x32_bf16 v[52:55], v[182:185], v[198:201], v[52:55]
	v_mfma_f32_16x16x32_bf16 v[48:51], v[186:189], v[194:197], v[48:51]
	v_mfma_f32_16x16x32_bf16 v[48:51], v[190:193], v[198:201], v[48:51]
	v_mfma_f32_16x16x32_bf16 v[36:39], v[178:181], v[202:205], v[36:39]
	v_mfma_f32_16x16x32_bf16 v[36:39], v[182:185], v[206:209], v[36:39]
	v_mfma_f32_16x16x32_bf16 v[32:35], v[186:189], v[202:205], v[32:35]
	v_mfma_f32_16x16x32_bf16 v[32:35], v[190:193], v[206:209], v[32:35]
	v_mfma_f32_16x16x32_bf16 v[20:23], v[178:181], v[210:213], v[20:23]
	v_mfma_f32_16x16x32_bf16 v[20:23], v[182:185], v[214:217], v[20:23]
	v_mfma_f32_16x16x32_bf16 v[16:19], v[186:189], v[210:213], v[16:19]
	v_mfma_f32_16x16x32_bf16 v[16:19], v[190:193], v[214:217], v[16:19]
	v_mfma_f32_16x16x32_bf16 v[4:7], v[178:181], v[218:221], v[4:7]
	v_mfma_f32_16x16x32_bf16 v[4:7], v[182:185], v[222:225], v[4:7]
	v_mfma_f32_16x16x32_bf16 v[0:3], v[186:189], v[218:221], v[0:3]
	v_mfma_f32_16x16x32_bf16 v[0:3], v[190:193], v[222:225], v[0:3]
	s_setprio 0
	s_barrier
	s_add_i32 s56, 0, 0x18000
	v_add_u32_e32 v165, s56, v146
	s_add_i32 s57, 0, 0x1c000
	ds_read_b128 v[154:157], v165
	ds_read_b128 v[158:161], v165 offset:1024
	ds_read_b128 v[170:173], v165 offset:2048
	ds_read_b128 v[174:177], v165 offset:3072
	v_add_u32_e32 v165, s57, v146
	ds_read_b128 v[178:181], v165
	ds_read_b128 v[182:185], v165 offset:1024
	ds_read_b128 v[186:189], v165 offset:2048
	ds_read_b128 v[190:193], v165 offset:3072
	s_add_u32 s22, s22, 0x164000
	s_addc_u32 s23, s23, 0
	s_mov_b32 m0, s39
	v_lshl_add_u64 v[230:231], s[22:23], 0, v[128:129]
	ds_read_b128 v[194:197], v152 offset:32768
	ds_read_b128 v[198:201], v152 offset:33792
	ds_read_b128 v[202:205], v152 offset:34816
	ds_read_b128 v[206:209], v152 offset:35840
	ds_read_b128 v[210:213], v152 offset:36864
	ds_read_b128 v[214:217], v152 offset:37888
	ds_read_b128 v[218:221], v152 offset:38912
	ds_read_b128 v[222:225], v152 offset:39936
	global_load_lds_dwordx4 v[230:231], off
	v_lshl_add_u64 v[230:231], s[22:23], 0, v[132:133]
	s_mov_b32 m0, s40
	s_nop 0
	global_load_lds_dwordx4 v[230:231], off
	s_waitcnt vmcnt(8)
	s_waitcnt lgkmcnt(0)
	s_barrier
	s_setprio 1
	s_waitcnt lgkmcnt(0)
	v_mfma_f32_16x16x32_bf16 v[124:127], v[154:157], v[194:197], v[124:127]
	v_mfma_f32_16x16x32_bf16 v[124:127], v[158:161], v[198:201], v[124:127]
	v_mfma_f32_16x16x32_bf16 v[120:123], v[170:173], v[194:197], v[120:123]
	v_mfma_f32_16x16x32_bf16 v[120:123], v[174:177], v[198:201], v[120:123]
	v_mfma_f32_16x16x32_bf16 v[108:111], v[154:157], v[202:205], v[108:111]
	v_mfma_f32_16x16x32_bf16 v[108:111], v[158:161], v[206:209], v[108:111]
	v_mfma_f32_16x16x32_bf16 v[104:107], v[170:173], v[202:205], v[104:107]
	v_mfma_f32_16x16x32_bf16 v[104:107], v[174:177], v[206:209], v[104:107]
	v_mfma_f32_16x16x32_bf16 v[92:95], v[154:157], v[210:213], v[92:95]
	v_mfma_f32_16x16x32_bf16 v[92:95], v[158:161], v[214:217], v[92:95]
	v_mfma_f32_16x16x32_bf16 v[88:91], v[170:173], v[210:213], v[88:91]
	v_mfma_f32_16x16x32_bf16 v[88:91], v[174:177], v[214:217], v[88:91]
	v_mfma_f32_16x16x32_bf16 v[76:79], v[154:157], v[218:221], v[76:79]
	v_mfma_f32_16x16x32_bf16 v[76:79], v[158:161], v[222:225], v[76:79]
	v_mfma_f32_16x16x32_bf16 v[72:75], v[170:173], v[218:221], v[72:75]
	v_mfma_f32_16x16x32_bf16 v[72:75], v[174:177], v[222:225], v[72:75]
	s_setprio 0
	s_setprio 1
	v_mfma_f32_16x16x32_bf16 v[116:119], v[178:181], v[194:197], v[116:119]
	v_mfma_f32_16x16x32_bf16 v[116:119], v[182:185], v[198:201], v[116:119]
	v_mfma_f32_16x16x32_bf16 v[112:115], v[186:189], v[194:197], v[112:115]
	v_mfma_f32_16x16x32_bf16 v[112:115], v[190:193], v[198:201], v[112:115]
	v_mfma_f32_16x16x32_bf16 v[100:103], v[178:181], v[202:205], v[100:103]
	v_mfma_f32_16x16x32_bf16 v[100:103], v[182:185], v[206:209], v[100:103]
	v_mfma_f32_16x16x32_bf16 v[96:99], v[186:189], v[202:205], v[96:99]
	v_mfma_f32_16x16x32_bf16 v[96:99], v[190:193], v[206:209], v[96:99]
	v_mfma_f32_16x16x32_bf16 v[84:87], v[178:181], v[210:213], v[84:87]
	v_mfma_f32_16x16x32_bf16 v[84:87], v[182:185], v[214:217], v[84:87]
	v_mfma_f32_16x16x32_bf16 v[80:83], v[186:189], v[210:213], v[80:83]
	v_mfma_f32_16x16x32_bf16 v[80:83], v[190:193], v[214:217], v[80:83]
	v_mfma_f32_16x16x32_bf16 v[68:71], v[178:181], v[218:221], v[68:71]
	v_mfma_f32_16x16x32_bf16 v[68:71], v[182:185], v[222:225], v[68:71]
	v_mfma_f32_16x16x32_bf16 v[64:67], v[186:189], v[218:221], v[64:67]
	v_mfma_f32_16x16x32_bf16 v[64:67], v[190:193], v[222:225], v[64:67]
	s_setprio 0
	s_barrier
; #define PG8_STAGE(bufoff, gbase, voff) do { _Pragma("unroll") for (int _i = 0; _i < 2; ++_i) \
;         __builtin_amdgcn_global_load_lds((const unsigned*)((const char*)(gbase) + (voff)[_i]), (LAS unsigned*)(lds + (bufoff) + ldsw + _i * 8192), 16, 0, 0); } while (0)
; #define PG8_LDA(dst, b, h) do { _Pragma("unroll") for (int m = 0; m < 4; ++m) _Pragma("unroll") for (int k = 0; k < 2; ++k) dst[m][k] = *(const LAS bf16x8*)(lds + PG8_SA(b, h) + aoff + m * 2048 + k * 1024); } while (0)
; #define PG8_MMA(ai, bj, At, Bt) do { __builtin_amdgcn_s_setprio(1); _Pragma("unroll") for (int m = 0; m < 4; ++m) _Pragma("unroll") for (int n = 0; n < 2; ++n) _Pragma("unroll") for (int k = 0; k < 2; ++k) \
;         acc[ai][bj][m][n] = __builtin_amdgcn_mfma_f32_16x16x32_bf16(Bt[n][k], At[m][k], acc[ai][bj][m][n], 0, 0, 0); __builtin_amdgcn_s_setprio(0); } while (0)
; #define PG8_WAIT_V(n) asm volatile("s_waitcnt vmcnt(" #n ")" ::: "memory")
; #define PG8_WAIT_L(n) asm volatile("s_waitcnt lgkmcnt(" #n ")" ::: "memory")
; #define PG8_BAR __builtin_amdgcn_s_barrier()
; #define PG8_SCHED __builtin_amdgcn_sched_barrier(0)
; template <class EpiT>
; __device__ __forceinline__ void gemm_phase(LAS unsigned char* lds, const Gemm g, const StaticOrder& S, const EpiT& E) {
;     ...
;             PG8_LDA(At, 1, 1); PG8_STAGE(PG8_SB(1, 0), b3, voffB); PG8_STAGE(PG8_SB(1, 1), b3 + hstepB, voffB); PG8_STAGE(PG8_SA(1, 0), a3, voffA);
;             PG8_WAIT_V(8); PG8_WAIT_L(0); PG8_BAR; PG8_MMA(1, 0, At, B0); PG8_MMA(1, 1, At, B1); PG8_BAR; PG8_SCHED;
;         }
;         if (wr == 0) PG8_BAR;
	s_add_i32 s22, s56, s36
	v_lshl_add_u64 v[162:163], v[162:163], 0, s[12:13]
	s_mov_b32 m0, s22
	ds_read_b128 v[194:197], v152 offset:49152
	ds_read_b128 v[198:201], v152 offset:50176
	ds_read_b128 v[202:205], v152 offset:51200
	ds_read_b128 v[206:209], v152 offset:52224
	ds_read_b128 v[210:213], v152 offset:53248
	ds_read_b128 v[214:217], v152 offset:54272
	ds_read_b128 v[218:221], v152 offset:55296
	ds_read_b128 v[222:225], v152 offset:56320
	global_load_lds_dwordx4 v[162:163], off
	s_add_i32 m0, s22, 0x2000
	s_add_u32 s20, s20, 0x164080
	v_lshl_add_u64 v[162:163], v[166:167], 0, s[12:13]
	s_addc_u32 s21, s21, 0
	s_add_i32 s22, s57, s36
	global_load_lds_dwordx4 v[162:163], off
	v_lshl_add_u64 v[162:163], s[20:21], 0, v[130:131]
	s_mov_b32 m0, s22
	s_nop 0
	global_load_lds_dwordx4 v[162:163], off
	v_lshl_add_u64 v[162:163], s[20:21], 0, v[134:135]
	s_add_i32 m0, s22, 0x2000
	s_nop 0
	global_load_lds_dwordx4 v[162:163], off
	v_lshl_add_u64 v[162:163], v[226:227], 0, s[12:13]
	s_mov_b32 m0, s42
	s_nop 0
	global_load_lds_dwordx4 v[162:163], off
	v_lshl_add_u64 v[162:163], v[228:229], 0, s[12:13]
	s_mov_b32 m0, s43
	s_nop 0
	global_load_lds_dwordx4 v[162:163], off
	s_waitcnt vmcnt(8)
	s_waitcnt lgkmcnt(0)
	s_barrier
	s_setprio 1
	s_waitcnt lgkmcnt(0)
	v_mfma_f32_16x16x32_bf16 v[60:63], v[154:157], v[194:197], v[60:63]
	v_mfma_f32_16x16x32_bf16 v[60:63], v[158:161], v[198:201], v[60:63]
	v_mfma_f32_16x16x32_bf16 v[56:59], v[170:173], v[194:197], v[56:59]
	v_mfma_f32_16x16x32_bf16 v[56:59], v[174:177], v[198:201], v[56:59]
	v_mfma_f32_16x16x32_bf16 v[44:47], v[154:157], v[202:205], v[44:47]
	v_mfma_f32_16x16x32_bf16 v[44:47], v[158:161], v[206:209], v[44:47]
	v_mfma_f32_16x16x32_bf16 v[40:43], v[170:173], v[202:205], v[40:43]
	v_mfma_f32_16x16x32_bf16 v[40:43], v[174:177], v[206:209], v[40:43]
	v_mfma_f32_16x16x32_bf16 v[28:31], v[154:157], v[210:213], v[28:31]
	v_mfma_f32_16x16x32_bf16 v[28:31], v[158:161], v[214:217], v[28:31]
	v_mfma_f32_16x16x32_bf16 v[24:27], v[170:173], v[210:213], v[24:27]
	v_mfma_f32_16x16x32_bf16 v[24:27], v[174:177], v[214:217], v[24:27]
	v_mfma_f32_16x16x32_bf16 v[12:15], v[154:157], v[218:221], v[12:15]
	v_mfma_f32_16x16x32_bf16 v[12:15], v[158:161], v[222:225], v[12:15]
	v_mfma_f32_16x16x32_bf16 v[8:11], v[170:173], v[218:221], v[8:11]
	v_mfma_f32_16x16x32_bf16 v[8:11], v[174:177], v[222:225], v[8:11]
	s_setprio 0
	s_setprio 1
	v_mfma_f32_16x16x32_bf16 v[52:55], v[178:181], v[194:197], v[52:55]
	v_mfma_f32_16x16x32_bf16 v[52:55], v[182:185], v[198:201], v[52:55]
	v_mfma_f32_16x16x32_bf16 v[48:51], v[186:189], v[194:197], v[48:51]
	v_mfma_f32_16x16x32_bf16 v[48:51], v[190:193], v[198:201], v[48:51]
	v_mfma_f32_16x16x32_bf16 v[36:39], v[178:181], v[202:205], v[36:39]
	v_mfma_f32_16x16x32_bf16 v[36:39], v[182:185], v[206:209], v[36:39]
	v_mfma_f32_16x16x32_bf16 v[32:35], v[186:189], v[202:205], v[32:35]
	v_mfma_f32_16x16x32_bf16 v[32:35], v[190:193], v[206:209], v[32:35]
	v_mfma_f32_16x16x32_bf16 v[20:23], v[178:181], v[210:213], v[20:23]
	v_mfma_f32_16x16x32_bf16 v[20:23], v[182:185], v[214:217], v[20:23]
	v_mfma_f32_16x16x32_bf16 v[16:19], v[186:189], v[210:213], v[16:19]
	v_mfma_f32_16x16x32_bf16 v[16:19], v[190:193], v[214:217], v[16:19]
	v_mfma_f32_16x16x32_bf16 v[4:7], v[178:181], v[218:221], v[4:7]
	v_mfma_f32_16x16x32_bf16 v[4:7], v[182:185], v[222:225], v[4:7]
	v_mfma_f32_16x16x32_bf16 v[0:3], v[186:189], v[218:221], v[0:3]
	v_mfma_f32_16x16x32_bf16 v[0:3], v[190:193], v[222:225], v[0:3]
	s_setprio 0
	s_barrier
	s_add_i32 s55, s55, 2
	s_add_u32 s18, s18, 0x100
	s_addc_u32 s19, s19, 0
	s_add_u32 s53, s53, 0x100
	s_addc_u32 s54, s54, 0
	s_cmpk_gt_u32 s55, 0x55
	s_cbranch_scc0 .LBB0_595
	s_and_b64 vcc, exec, s[14:15]
	s_cbranch_vccz .LBB0_598
	s_barrier

; #define PG8_STAGE(bufoff, gbase, voff) do { _Pragma("unroll") for (int _i = 0; _i < 2; ++_i) \
;         __builtin_amdgcn_global_load_lds((const unsigned*)((const char*)(gbase) + (voff)[_i]), (LAS unsigned*)(lds + (bufoff) + ldsw + _i * 8192), 16, 0, 0); } while (0)
; #define PG8_LDA(dst, b, h) do { _Pragma("unroll") for (int m = 0; m < 4; ++m) _Pragma("unroll") for (int k = 0; k < 2; ++k) dst[m][k] = *(const LAS bf16x8*)(lds + PG8_SA(b, h) + aoff + m * 2048 + k * 1024); } while (0)
; #define PG8_LDB(dst, b, h) do { _Pragma("unroll") for (int n = 0; n < 2; ++n) _Pragma("unroll") for (int k = 0; k < 2; ++k) dst[n][k] = *(const LAS bf16x8*)(lds + PG8_SB(b, h) + boff + n * 2048 + k * 1024); } while (0)
; #define PG8_MMA(ai, bj, At, Bt) do { __builtin_amdgcn_s_setprio(1); _Pragma("unroll") for (int m = 0; m < 4; ++m) _Pragma("unroll") for (int n = 0; n < 2; ++n) _Pragma("unroll") for (int k = 0; k < 2; ++k) \
;         acc[ai][bj][m][n] = __builtin_amdgcn_mfma_f32_16x16x32_bf16(Bt[n][k], At[m][k], acc[ai][bj][m][n], 0, 0, 0); __builtin_amdgcn_s_setprio(0); } while (0)
; #define PG8_WAIT_V(n) asm volatile("s_waitcnt vmcnt(" #n ")" ::: "memory")
; template <class EpiT>
; __device__ __forceinline__ void gemm_phase(LAS unsigned char* lds, const Gemm g, const StaticOrder& S, const EpiT& E) {
;     ...
;         const char* nA = has_next ? (const char*)g.A + (size_t)nxt.pm * tstepA + (size_t)nxt.pn * g.a_koff * 2 : cA; const char* nB = has_next ? (const char*)g.Bt + (size_t)nxt.pn * tstepB : cB;
;         for (int t = 0; t < nt; t += 2) {
;             const bool last = (t == nt - 2);
;             const char* a1 = cA + (size_t)(t + 1) * kstep;
;             const char* a2 = last ? nA : cA + (size_t)(t + 2) * kstep; const char* b2 = last ? nB : cB + (size_t)(t + 2) * kstep;
;             const char* a3 = a2 + kstep; const char* b3 = b2 + kstep;
;             PG8_LDB(B0, 0, 0); PG8_LDB(B1, 0, 1); PG8_SCHED; PG8_LDA(At, 0, 0); PG8_STAGE(PG8_SA(1, 1), a1 + hstepA, voffA);
;             PG8_WAIT_V(8); PG8_WAIT_L(0); PG8_BAR; PG8_MMA(0, 0, At, B0); PG8_MMA(0, 1, At, B1); PG8_BAR; PG8_SCHED;
;             PG8_LDA(At, 0, 1); PG8_STAGE(PG8_SB(0, 0), b2, voffB); PG8_STAGE(PG8_SB(0, 1), b2 + hstepB, voffB); PG8_STAGE(PG8_SA(0, 0), a2, voffA);
;             PG8_WAIT_V(8); PG8_WAIT_L(0); PG8_BAR; PG8_MMA(1, 0, At, B0); PG8_MMA(1, 1, At, B1); PG8_BAR; PG8_SCHED;
.LBB0_761:
	ds_read_b128 v[156:159], v160
	ds_read_b128 v[164:167], v160 offset:1024
	ds_read_b128 v[170:173], v160 offset:2048
	ds_read_b128 v[174:177], v160 offset:3072
	ds_read_b128 v[178:181], v161
	ds_read_b128 v[182:185], v161 offset:1024
	ds_read_b128 v[186:189], v161 offset:2048
	ds_read_b128 v[190:193], v161 offset:3072
	s_add_u32 s22, s20, 0xfff7c080
	s_addc_u32 s23, s21, -1
	s_cmp_eq_u32 s56, 28
	s_cselect_b32 s25, s5, s23
	s_cselect_b32 s24, s4, s22
	s_cselect_b32 s23, s19, s39
	s_cselect_b32 s22, s18, s8
	v_lshl_add_u64 v[226:227], s[20:21], 0, v[146:147]
	s_add_i32 m0, s40, 0xc000
	ds_read_b128 v[194:197], v162
	ds_read_b128 v[198:201], v162 offset:1024
	ds_read_b128 v[202:205], v162 offset:2048
	ds_read_b128 v[206:209], v162 offset:3072
	ds_read_b128 v[210:213], v162 offset:4096
	ds_read_b128 v[214:217], v162 offset:5120
	ds_read_b128 v[218:221], v162 offset:6144
	ds_read_b128 v[222:225], v162 offset:7168
	global_load_lds_dwordx4 v[226:227], off
	v_lshl_add_u64 v[226:227], s[20:21], 0, v[150:151]
	s_add_i32 m0, s40, 0xe000
	s_nop 0
	global_load_lds_dwordx4 v[226:227], off
	s_waitcnt vmcnt(8)
	s_waitcnt lgkmcnt(0)
	s_barrier
	s_setprio 1
	s_waitcnt lgkmcnt(0)
	v_mfma_f32_16x16x32_bf16 v[124:127], v[156:159], v[194:197], v[124:127]
	v_mfma_f32_16x16x32_bf16 v[124:127], v[164:167], v[198:201], v[124:127]
	v_mfma_f32_16x16x32_bf16 v[120:123], v[170:173], v[194:197], v[120:123]
	v_mfma_f32_16x16x32_bf16 v[120:123], v[174:177], v[198:201], v[120:123]
	v_mfma_f32_16x16x32_bf16 v[108:111], v[156:159], v[202:205], v[108:111]
	v_mfma_f32_16x16x32_bf16 v[108:111], v[164:167], v[206:209], v[108:111]
	v_mfma_f32_16x16x32_bf16 v[104:107], v[170:173], v[202:205], v[104:107]
	v_mfma_f32_16x16x32_bf16 v[104:107], v[174:177], v[206:209], v[104:107]
	v_mfma_f32_16x16x32_bf16 v[92:95], v[156:159], v[210:213], v[92:95]
	v_mfma_f32_16x16x32_bf16 v[92:95], v[164:167], v[214:217], v[92:95]
	v_mfma_f32_16x16x32_bf16 v[88:91], v[170:173], v[210:213], v[88:91]
	v_mfma_f32_16x16x32_bf16 v[88:91], v[174:177], v[214:217], v[88:91]
	v_mfma_f32_16x16x32_bf16 v[76:79], v[156:159], v[218:221], v[76:79]
	v_mfma_f32_16x16x32_bf16 v[76:79], v[164:167], v[222:225], v[76:79]
	v_mfma_f32_16x16x32_bf16 v[72:75], v[170:173], v[218:221], v[72:75]
	v_mfma_f32_16x16x32_bf16 v[72:75], v[174:177], v[222:225], v[72:75]
	s_setprio 0
	s_setprio 1
	v_mfma_f32_16x16x32_bf16 v[116:119], v[178:181], v[194:197], v[116:119]
	v_mfma_f32_16x16x32_bf16 v[116:119], v[182:185], v[198:201], v[116:119]
	v_mfma_f32_16x16x32_bf16 v[112:115], v[186:189], v[194:197], v[112:115]
	v_mfma_f32_16x16x32_bf16 v[112:115], v[190:193], v[198:201], v[112:115]
	v_mfma_f32_16x16x32_bf16 v[100:103], v[178:181], v[202:205], v[100:103]
	v_mfma_f32_16x16x32_bf16 v[100:103], v[182:185], v[206:209], v[100:103]
	v_mfma_f32_16x16x32_bf16 v[96:99], v[186:189], v[202:205], v[96:99]
	v_mfma_f32_16x16x32_bf16 v[96:99], v[190:193], v[206:209], v[96:99]
	v_mfma_f32_16x16x32_bf16 v[84:87], v[178:181], v[210:213], v[84:87]
	v_mfma_f32_16x16x32_bf16 v[84:87], v[182:185], v[214:217], v[84:87]
	v_mfma_f32_16x16x32_bf16 v[80:83], v[186:189], v[210:213], v[80:83]
	v_mfma_f32_16x16x32_bf16 v[80:83], v[190:193], v[214:217], v[80:83]
	v_mfma_f32_16x16x32_bf16 v[68:71], v[178:181], v[218:221], v[68:71]
	v_mfma_f32_16x16x32_bf16 v[68:71], v[182:185], v[222:225], v[68:71]
	v_mfma_f32_16x16x32_bf16 v[64:67], v[186:189], v[218:221], v[64:67]
	v_mfma_f32_16x16x32_bf16 v[64:67], v[190:193], v[222:225], v[64:67]
	s_setprio 0
	s_barrier
	s_add_i32 s57, s49, s37
	v_lshl_add_u64 v[226:227], s[22:23], 0, v[130:131]
	s_mov_b32 m0, s57
	ds_read_b128 v[194:197], v162 offset:16384
	ds_read_b128 v[198:201], v162 offset:17408
	ds_read_b128 v[202:205], v162 offset:18432
	ds_read_b128 v[206:209], v162 offset:19456
	ds_read_b128 v[210:213], v162 offset:20480
	ds_read_b128 v[214:217], v162 offset:21504
	ds_read_b128 v[218:221], v162 offset:22528
	ds_read_b128 v[222:225], v162 offset:23552
	global_load_lds_dwordx4 v[226:227], off
	s_add_i32 m0, s57, 0x2000
	s_add_u32 s58, s22, 0x84000
	v_lshl_add_u64 v[228:229], s[22:23], 0, v[134:135]
	s_addc_u32 s59, s23, 0
	s_add_i32 s57, s50, s37
	global_load_lds_dwordx4 v[228:229], off
	v_lshl_add_u64 v[230:231], s[58:59], 0, v[130:131]
	s_mov_b32 m0, s57
	v_lshl_add_u64 v[232:233], s[24:25], 0, v[132:133]
	global_load_lds_dwordx4 v[230:231], off
	v_lshl_add_u64 v[230:231], s[58:59], 0, v[134:135]
	s_add_i32 m0, s57, 0x2000
	s_nop 0
	global_load_lds_dwordx4 v[230:231], off
	v_lshl_add_u64 v[230:231], s[24:25], 0, v[128:129]
	s_mov_b32 m0, s40
	s_nop 0
	global_load_lds_dwordx4 v[230:231], off
	s_mov_b32 m0, s41
	s_nop 0
	global_load_lds_dwordx4 v[232:233], off
	s_waitcnt vmcnt(8)
	s_waitcnt lgkmcnt(0)
	s_barrier
; #define PG8_STAGE(bufoff, gbase, voff) do { _Pragma("unroll") for (int _i = 0; _i < 2; ++_i) \
;         __builtin_amdgcn_global_load_lds((const unsigned*)((const char*)(gbase) + (voff)[_i]), (LAS unsigned*)(lds + (bufoff) + ldsw + _i * 8192), 16, 0, 0); } while (0)
; #define PG8_LDA(dst, b, h) do { _Pragma("unroll") for (int m = 0; m < 4; ++m) _Pragma("unroll") for (int k = 0; k < 2; ++k) dst[m][k] = *(const LAS bf16x8*)(lds + PG8_SA(b, h) + aoff + m * 2048 + k * 1024); } while (0)
; #define PG8_LDB(dst, b, h) do { _Pragma("unroll") for (int n = 0; n < 2; ++n) _Pragma("unroll") for (int k = 0; k < 2; ++k) dst[n][k] = *(const LAS bf16x8*)(lds + PG8_SB(b, h) + boff + n * 2048 + k * 1024); } while (0)
; #define PG8_MMA(ai, bj, At, Bt) do { __builtin_amdgcn_s_setprio(1); _Pragma("unroll") for (int m = 0; m < 4; ++m) _Pragma("unroll") for (int n = 0; n < 2; ++n) _Pragma("unroll") for (int k = 0; k < 2; ++k) \
;         acc[ai][bj][m][n] = __builtin_amdgcn_mfma_f32_16x16x32_bf16(Bt[n][k], At[m][k], acc[ai][bj][m][n], 0, 0, 0); __builtin_amdgcn_s_setprio(0); } while (0)
; #define PG8_WAIT_V(n) asm volatile("s_waitcnt vmcnt(" #n ")" ::: "memory")
; #define PG8_WAIT_L(n) asm volatile("s_waitcnt lgkmcnt(" #n ")" ::: "memory")
; #define PG8_BAR __builtin_amdgcn_s_barrier()
; #define PG8_SCHED __builtin_amdgcn_sched_barrier(0)
; template <class EpiT>
; __device__ __forceinline__ void gemm_phase(LAS unsigned char* lds, const Gemm g, const StaticOrder& S, const EpiT& E) {
;     ...
;             PG8_WAIT_V(8); PG8_WAIT_L(0); PG8_BAR; PG8_MMA(1, 0, At, B0); PG8_MMA(1, 1, At, B1); PG8_BAR; PG8_SCHED;
;             PG8_LDB(B0, 1, 0); PG8_LDB(B1, 1, 1); PG8_SCHED; PG8_LDA(At, 1, 0); PG8_STAGE(PG8_SA(0, 1), a2 + hstepA, voffA);
;             PG8_WAIT_V(8); PG8_WAIT_L(0); PG8_BAR; PG8_MMA(0, 0, At, B0); PG8_MMA(0, 1, At, B1); PG8_BAR; PG8_SCHED;
	s_setprio 1
	s_waitcnt lgkmcnt(0)
	v_mfma_f32_16x16x32_bf16 v[60:63], v[156:159], v[194:197], v[60:63]
	v_mfma_f32_16x16x32_bf16 v[60:63], v[164:167], v[198:201], v[60:63]
	v_mfma_f32_16x16x32_bf16 v[56:59], v[170:173], v[194:197], v[56:59]
	v_mfma_f32_16x16x32_bf16 v[56:59], v[174:177], v[198:201], v[56:59]
	v_mfma_f32_16x16x32_bf16 v[44:47], v[156:159], v[202:205], v[44:47]
	v_mfma_f32_16x16x32_bf16 v[44:47], v[164:167], v[206:209], v[44:47]
	v_mfma_f32_16x16x32_bf16 v[40:43], v[170:173], v[202:205], v[40:43]
	v_mfma_f32_16x16x32_bf16 v[40:43], v[174:177], v[206:209], v[40:43]
	v_mfma_f32_16x16x32_bf16 v[28:31], v[156:159], v[210:213], v[28:31]
	v_mfma_f32_16x16x32_bf16 v[28:31], v[164:167], v[214:217], v[28:31]
	v_mfma_f32_16x16x32_bf16 v[24:27], v[170:173], v[210:213], v[24:27]
	v_mfma_f32_16x16x32_bf16 v[24:27], v[174:177], v[214:217], v[24:27]
	v_mfma_f32_16x16x32_bf16 v[12:15], v[156:159], v[218:221], v[12:15]
	v_mfma_f32_16x16x32_bf16 v[12:15], v[164:167], v[222:225], v[12:15]
	v_mfma_f32_16x16x32_bf16 v[8:11], v[170:173], v[218:221], v[8:11]
	v_mfma_f32_16x16x32_bf16 v[8:11], v[174:177], v[222:225], v[8:11]
	s_setprio 0
	s_setprio 1
	v_mfma_f32_16x16x32_bf16 v[52:55], v[178:181], v[194:197], v[52:55]
	v_mfma_f32_16x16x32_bf16 v[52:55], v[182:185], v[198:201], v[52:55]
	v_mfma_f32_16x16x32_bf16 v[48:51], v[186:189], v[194:197], v[48:51]
	v_mfma_f32_16x16x32_bf16 v[48:51], v[190:193], v[198:201], v[48:51]
	v_mfma_f32_16x16x32_bf16 v[36:39], v[178:181], v[202:205], v[36:39]
	v_mfma_f32_16x16x32_bf16 v[36:39], v[182:185], v[206:209], v[36:39]
	v_mfma_f32_16x16x32_bf16 v[32:35], v[186:189], v[202:205], v[32:35]
	v_mfma_f32_16x16x32_bf16 v[32:35], v[190:193], v[206:209], v[32:35]
	v_mfma_f32_16x16x32_bf16 v[20:23], v[178:181], v[210:213], v[20:23]
	v_mfma_f32_16x16x32_bf16 v[20:23], v[182:185], v[214:217], v[20:23]
	v_mfma_f32_16x16x32_bf16 v[16:19], v[186:189], v[210:213], v[16:19]
	v_mfma_f32_16x16x32_bf16 v[16:19], v[190:193], v[214:217], v[16:19]
	v_mfma_f32_16x16x32_bf16 v[4:7], v[178:181], v[218:221], v[4:7]
	v_mfma_f32_16x16x32_bf16 v[4:7], v[182:185], v[222:225], v[4:7]
	v_mfma_f32_16x16x32_bf16 v[0:3], v[186:189], v[218:221], v[0:3]
	v_mfma_f32_16x16x32_bf16 v[0:3], v[190:193], v[222:225], v[0:3]
	s_setprio 0
	s_barrier
	s_add_i32 s57, 0, 0x18000
	v_add_u32_e32 v136, s57, v149
	s_add_i32 s58, 0, 0x1c000
	ds_read_b128 v[156:159], v136
	ds_read_b128 v[164:167], v136 offset:1024
	ds_read_b128 v[170:173], v136 offset:2048
	ds_read_b128 v[174:177], v136 offset:3072
	v_add_u32_e32 v136, s58, v149
	ds_read_b128 v[178:181], v136
	ds_read_b128 v[182:185], v136 offset:1024
	ds_read_b128 v[186:189], v136 offset:2048
	ds_read_b128 v[190:193], v136 offset:3072
	s_add_u32 s24, s24, 0x84000
	s_addc_u32 s25, s25, 0
	s_mov_b32 m0, s42
	v_lshl_add_u64 v[234:235], s[24:25], 0, v[128:129]
	ds_read_b128 v[194:197], v162 offset:32768
	ds_read_b128 v[198:201], v162 offset:33792
	ds_read_b128 v[202:205], v162 offset:34816
	ds_read_b128 v[206:209], v162 offset:35840
	ds_read_b128 v[210:213], v162 offset:36864
	ds_read_b128 v[214:217], v162 offset:37888
	ds_read_b128 v[218:221], v162 offset:38912
	ds_read_b128 v[222:225], v162 offset:39936
	global_load_lds_dwordx4 v[234:235], off
	v_lshl_add_u64 v[234:235], s[24:25], 0, v[132:133]
	s_mov_b32 m0, s43
	s_nop 0
	global_load_lds_dwordx4 v[234:235], off
	s_waitcnt vmcnt(8)
	s_waitcnt lgkmcnt(0)
	s_barrier
	s_setprio 1
	s_waitcnt lgkmcnt(0)
	v_mfma_f32_16x16x32_bf16 v[124:127], v[156:159], v[194:197], v[124:127]
	v_mfma_f32_16x16x32_bf16 v[124:127], v[164:167], v[198:201], v[124:127]
	v_mfma_f32_16x16x32_bf16 v[120:123], v[170:173], v[194:197], v[120:123]
	v_mfma_f32_16x16x32_bf16 v[120:123], v[174:177], v[198:201], v[120:123]
	v_mfma_f32_16x16x32_bf16 v[108:111], v[156:159], v[202:205], v[108:111]
	v_mfma_f32_16x16x32_bf16 v[108:111], v[164:167], v[206:209], v[108:111]
	v_mfma_f32_16x16x32_bf16 v[104:107], v[170:173], v[202:205], v[104:107]
	v_mfma_f32_16x16x32_bf16 v[104:107], v[174:177], v[206:209], v[104:107]
	v_mfma_f32_16x16x32_bf16 v[92:95], v[156:159], v[210:213], v[92:95]
	v_mfma_f32_16x16x32_bf16 v[92:95], v[164:167], v[214:217], v[92:95]
	v_mfma_f32_16x16x32_bf16 v[88:91], v[170:173], v[210:213], v[88:91]
	v_mfma_f32_16x16x32_bf16 v[88:91], v[174:177], v[214:217], v[88:91]
	v_mfma_f32_16x16x32_bf16 v[76:79], v[156:159], v[218:221], v[76:79]
	v_mfma_f32_16x16x32_bf16 v[76:79], v[164:167], v[222:225], v[76:79]
	v_mfma_f32_16x16x32_bf16 v[72:75], v[170:173], v[218:221], v[72:75]
	v_mfma_f32_16x16x32_bf16 v[72:75], v[174:177], v[222:225], v[72:75]
	s_setprio 0
	s_setprio 1
	v_mfma_f32_16x16x32_bf16 v[116:119], v[178:181], v[194:197], v[116:119]
	v_mfma_f32_16x16x32_bf16 v[116:119], v[182:185], v[198:201], v[116:119]
	v_mfma_f32_16x16x32_bf16 v[112:115], v[186:189], v[194:197], v[112:115]
	v_mfma_f32_16x16x32_bf16 v[112:115], v[190:193], v[198:201], v[112:115]
	v_mfma_f32_16x16x32_bf16 v[100:103], v[178:181], v[202:205], v[100:103]
	v_mfma_f32_16x16x32_bf16 v[100:103], v[182:185], v[206:209], v[100:103]
	v_mfma_f32_16x16x32_bf16 v[96:99], v[186:189], v[202:205], v[96:99]
	v_mfma_f32_16x16x32_bf16 v[96:99], v[190:193], v[206:209], v[96:99]
	v_mfma_f32_16x16x32_bf16 v[84:87], v[178:181], v[210:213], v[84:87]
	v_mfma_f32_16x16x32_bf16 v[84:87], v[182:185], v[214:217], v[84:87]
	v_mfma_f32_16x16x32_bf16 v[80:83], v[186:189], v[210:213], v[80:83]
	v_mfma_f32_16x16x32_bf16 v[80:83], v[190:193], v[214:217], v[80:83]
	v_mfma_f32_16x16x32_bf16 v[68:71], v[178:181], v[218:221], v[68:71]
	v_mfma_f32_16x16x32_bf16 v[68:71], v[182:185], v[222:225], v[68:71]
	v_mfma_f32_16x16x32_bf16 v[64:67], v[186:189], v[218:221], v[64:67]
	v_mfma_f32_16x16x32_bf16 v[64:67], v[190:193], v[222:225], v[64:67]
	s_setprio 0
	s_barrier
; #define PG8_STAGE(bufoff, gbase, voff) do { _Pragma("unroll") for (int _i = 0; _i < 2; ++_i) \
;         __builtin_amdgcn_global_load_lds((const unsigned*)((const char*)(gbase) + (voff)[_i]), (LAS unsigned*)(lds + (bufoff) + ldsw + _i * 8192), 16, 0, 0); } while (0)
; #define PG8_LDA(dst, b, h) do { _Pragma("unroll") for (int m = 0; m < 4; ++m) _Pragma("unroll") for (int k = 0; k < 2; ++k) dst[m][k] = *(const LAS bf16x8*)(lds + PG8_SA(b, h) + aoff + m * 2048 + k * 1024); } while (0)
; #define PG8_MMA(ai, bj, At, Bt) do { __builtin_amdgcn_s_setprio(1); _Pragma("unroll") for (int m = 0; m < 4; ++m) _Pragma("unroll") for (int n = 0; n < 2; ++n) _Pragma("unroll") for (int k = 0; k < 2; ++k) \
;         acc[ai][bj][m][n] = __builtin_amdgcn_mfma_f32_16x16x32_bf16(Bt[n][k], At[m][k], acc[ai][bj][m][n], 0, 0, 0); __builtin_amdgcn_s_setprio(0); } while (0)
; #define PG8_WAIT_V(n) asm volatile("s_waitcnt vmcnt(" #n ")" ::: "memory")
; #define PG8_WAIT_L(n) asm volatile("s_waitcnt lgkmcnt(" #n ")" ::: "memory")
; #define PG8_BAR __builtin_amdgcn_s_barrier()
; #define PG8_SCHED __builtin_amdgcn_sched_barrier(0)
; template <class EpiT>
; __device__ __forceinline__ void gemm_phase(LAS unsigned char* lds, const Gemm g, const StaticOrder& S, const EpiT& E) {
;     ...
;             PG8_LDA(At, 1, 1); PG8_STAGE(PG8_SB(1, 0), b3, voffB); PG8_STAGE(PG8_SB(1, 1), b3 + hstepB, voffB); PG8_STAGE(PG8_SA(1, 0), a3, voffA);
;             PG8_WAIT_V(8); PG8_WAIT_L(0); PG8_BAR; PG8_MMA(1, 0, At, B0); PG8_MMA(1, 1, At, B1); PG8_BAR; PG8_SCHED;
;         }
;         if (wr == 0) PG8_BAR;
	s_add_i32 s24, s57, s37
	v_lshl_add_u64 v[226:227], v[226:227], 0, s[14:15]
	s_mov_b32 m0, s24
	ds_read_b128 v[194:197], v162 offset:49152
	ds_read_b128 v[198:201], v162 offset:50176
	ds_read_b128 v[202:205], v162 offset:51200
	ds_read_b128 v[206:209], v162 offset:52224
	ds_read_b128 v[210:213], v162 offset:53248
	ds_read_b128 v[214:217], v162 offset:54272
	ds_read_b128 v[218:221], v162 offset:55296
	ds_read_b128 v[222:225], v162 offset:56320
	global_load_lds_dwordx4 v[226:227], off
	s_add_i32 m0, s24, 0x2000
	s_add_u32 s22, s22, 0x84080
	v_lshl_add_u64 v[226:227], v[228:229], 0, s[14:15]
	s_addc_u32 s23, s23, 0
	s_add_i32 s24, s58, s37
	global_load_lds_dwordx4 v[226:227], off
	v_lshl_add_u64 v[226:227], s[22:23], 0, v[130:131]
	s_mov_b32 m0, s24
	s_nop 0
	global_load_lds_dwordx4 v[226:227], off
	v_lshl_add_u64 v[226:227], s[22:23], 0, v[134:135]
	s_add_i32 m0, s24, 0x2000
	s_nop 0
	global_load_lds_dwordx4 v[226:227], off
	v_lshl_add_u64 v[226:227], v[230:231], 0, s[14:15]
	s_mov_b32 m0, s44
	s_nop 0
	global_load_lds_dwordx4 v[226:227], off
	v_lshl_add_u64 v[226:227], v[232:233], 0, s[14:15]
	s_mov_b32 m0, s45
	s_nop 0
	global_load_lds_dwordx4 v[226:227], off
	s_waitcnt vmcnt(8)
	s_waitcnt lgkmcnt(0)
	s_barrier
	s_setprio 1
	s_waitcnt lgkmcnt(0)
	v_mfma_f32_16x16x32_bf16 v[60:63], v[156:159], v[194:197], v[60:63]
	v_mfma_f32_16x16x32_bf16 v[60:63], v[164:167], v[198:201], v[60:63]
	v_mfma_f32_16x16x32_bf16 v[56:59], v[170:173], v[194:197], v[56:59]
	v_mfma_f32_16x16x32_bf16 v[56:59], v[174:177], v[198:201], v[56:59]
	v_mfma_f32_16x16x32_bf16 v[44:47], v[156:159], v[202:205], v[44:47]
	v_mfma_f32_16x16x32_bf16 v[44:47], v[164:167], v[206:209], v[44:47]
	v_mfma_f32_16x16x32_bf16 v[40:43], v[170:173], v[202:205], v[40:43]
	v_mfma_f32_16x16x32_bf16 v[40:43], v[174:177], v[206:209], v[40:43]
	v_mfma_f32_16x16x32_bf16 v[28:31], v[156:159], v[210:213], v[28:31]
	v_mfma_f32_16x16x32_bf16 v[28:31], v[164:167], v[214:217], v[28:31]
	v_mfma_f32_16x16x32_bf16 v[24:27], v[170:173], v[210:213], v[24:27]
	v_mfma_f32_16x16x32_bf16 v[24:27], v[174:177], v[214:217], v[24:27]
	v_mfma_f32_16x16x32_bf16 v[12:15], v[156:159], v[218:221], v[12:15]
	v_mfma_f32_16x16x32_bf16 v[12:15], v[164:167], v[222:225], v[12:15]
	v_mfma_f32_16x16x32_bf16 v[8:11], v[170:173], v[218:221], v[8:11]
	v_mfma_f32_16x16x32_bf16 v[8:11], v[174:177], v[222:225], v[8:11]
	s_setprio 0
	s_setprio 1
	v_mfma_f32_16x16x32_bf16 v[52:55], v[178:181], v[194:197], v[52:55]
	v_mfma_f32_16x16x32_bf16 v[52:55], v[182:185], v[198:201], v[52:55]
	v_mfma_f32_16x16x32_bf16 v[48:51], v[186:189], v[194:197], v[48:51]
	v_mfma_f32_16x16x32_bf16 v[48:51], v[190:193], v[198:201], v[48:51]
	v_mfma_f32_16x16x32_bf16 v[36:39], v[178:181], v[202:205], v[36:39]
	v_mfma_f32_16x16x32_bf16 v[36:39], v[182:185], v[206:209], v[36:39]
	v_mfma_f32_16x16x32_bf16 v[32:35], v[186:189], v[202:205], v[32:35]
	v_mfma_f32_16x16x32_bf16 v[32:35], v[190:193], v[206:209], v[32:35]
	v_mfma_f32_16x16x32_bf16 v[20:23], v[178:181], v[210:213], v[20:23]
	v_mfma_f32_16x16x32_bf16 v[20:23], v[182:185], v[214:217], v[20:23]
	v_mfma_f32_16x16x32_bf16 v[16:19], v[186:189], v[210:213], v[16:19]
	v_mfma_f32_16x16x32_bf16 v[16:19], v[190:193], v[214:217], v[16:19]
	v_mfma_f32_16x16x32_bf16 v[4:7], v[178:181], v[218:221], v[4:7]
	v_mfma_f32_16x16x32_bf16 v[4:7], v[182:185], v[222:225], v[4:7]
	v_mfma_f32_16x16x32_bf16 v[0:3], v[186:189], v[218:221], v[0:3]
	v_mfma_f32_16x16x32_bf16 v[0:3], v[190:193], v[222:225], v[0:3]
	s_setprio 0
	s_barrier
	s_add_i32 s56, s56, 2
	s_add_u32 s20, s20, 0x100
	s_addc_u32 s21, s21, 0
	s_add_u32 s8, s8, 0x100
	s_addc_u32 s39, s39, 0
	s_cmp_gt_u32 s56, 29
	s_cbranch_scc0 .LBB0_761
	s_and_b64 vcc, exec, s[16:17]
	s_cbranch_vccz .LBB0_764
	s_barrier

; #define PG8_STAGE(bufoff, gbase, voff) do { _Pragma("unroll") for (int _i = 0; _i < 2; ++_i) \
;         __builtin_amdgcn_global_load_lds((const unsigned*)((const char*)(gbase) + (voff)[_i]), (LAS unsigned*)(lds + (bufoff) + ldsw + _i * 8192), 16, 0, 0); } while (0)
; #define PG8_LDA(dst, b, h) do { _Pragma("unroll") for (int m = 0; m < 4; ++m) _Pragma("unroll") for (int k = 0; k < 2; ++k) dst[m][k] = *(const LAS bf16x8*)(lds + PG8_SA(b, h) + aoff + m * 2048 + k * 1024); } while (0)
; #define PG8_LDB(dst, b, h) do { _Pragma("unroll") for (int n = 0; n < 2; ++n) _Pragma("unroll") for (int k = 0; k < 2; ++k) dst[n][k] = *(const LAS bf16x8*)(lds + PG8_SB(b, h) + boff + n * 2048 + k * 1024); } while (0)
; #define PG8_MMA(ai, bj, At, Bt) do { __builtin_amdgcn_s_setprio(1); _Pragma("unroll") for (int m = 0; m < 4; ++m) _Pragma("unroll") for (int n = 0; n < 2; ++n) _Pragma("unroll") for (int k = 0; k < 2; ++k) \
;         acc[ai][bj][m][n] = __builtin_amdgcn_mfma_f32_16x16x32_bf16(Bt[n][k], At[m][k], acc[ai][bj][m][n], 0, 0, 0); __builtin_amdgcn_s_setprio(0); } while (0)
; #define PG8_WAIT_V(n) asm volatile("s_waitcnt vmcnt(" #n ")" ::: "memory")
; template <class EpiT>
; __device__ __forceinline__ void gemm_phase(LAS unsigned char* lds, const Gemm g, const StaticOrder& S, const EpiT& E) {
;     ...
;         const char* nA = has_next ? (const char*)g.A + (size_t)nxt.pm * tstepA + (size_t)nxt.pn * g.a_koff * 2 : cA; const char* nB = has_next ? (const char*)g.Bt + (size_t)nxt.pn * tstepB : cB;
;         for (int t = 0; t < nt; t += 2) {
;             const bool last = (t == nt - 2);
;             const char* a1 = cA + (size_t)(t + 1) * kstep;
;             const char* a2 = last ? nA : cA + (size_t)(t + 2) * kstep; const char* b2 = last ? nB : cB + (size_t)(t + 2) * kstep;
;             const char* a3 = a2 + kstep; const char* b3 = b2 + kstep;
;             PG8_LDB(B0, 0, 0); PG8_LDB(B1, 0, 1); PG8_SCHED; PG8_LDA(At, 0, 0); PG8_STAGE(PG8_SA(1, 1), a1 + hstepA, voffA);
;             PG8_WAIT_V(8); PG8_WAIT_L(0); PG8_BAR; PG8_MMA(0, 0, At, B0); PG8_MMA(0, 1, At, B1); PG8_BAR; PG8_SCHED;
;             PG8_LDA(At, 0, 1); PG8_STAGE(PG8_SB(0, 0), b2, voffB); PG8_STAGE(PG8_SB(0, 1), b2 + hstepB, voffB); PG8_STAGE(PG8_SA(0, 0), a2, voffA);
;             PG8_WAIT_V(8); PG8_WAIT_L(0); PG8_BAR; PG8_MMA(1, 0, At, B0); PG8_MMA(1, 1, At, B1); PG8_BAR; PG8_SCHED;
.LBB0_1032:
	ds_read_b128 v[154:157], v150
	ds_read_b128 v[158:161], v150 offset:1024
	ds_read_b128 v[162:165], v150 offset:2048
	ds_read_b128 v[170:173], v150 offset:3072
	ds_read_b128 v[174:177], v151
	ds_read_b128 v[178:181], v151 offset:1024
	ds_read_b128 v[182:185], v151 offset:2048
	ds_read_b128 v[186:189], v151 offset:3072
	s_add_u32 s20, s18, 0xfff7c080
	s_addc_u32 s21, s19, -1
	s_cmp_eq_u32 s55, 28
	s_cselect_b32 s23, s5, s21
	s_cselect_b32 s22, s4, s20
	s_cselect_b32 s21, s17, s54
	s_cselect_b32 s20, s16, s53
	v_lshl_add_u64 v[166:167], s[18:19], 0, v[138:139]
	s_add_i32 m0, s37, 0xc000
	ds_read_b128 v[190:193], v152
	ds_read_b128 v[194:197], v152 offset:1024
	ds_read_b128 v[198:201], v152 offset:2048
	ds_read_b128 v[202:205], v152 offset:3072
	ds_read_b128 v[206:209], v152 offset:4096
	ds_read_b128 v[210:213], v152 offset:5120
	ds_read_b128 v[214:217], v152 offset:6144
	ds_read_b128 v[218:221], v152 offset:7168
	global_load_lds_dwordx4 v[166:167], off
	v_lshl_add_u64 v[166:167], s[18:19], 0, v[140:141]
	s_add_i32 m0, s37, 0xe000
	s_nop 0
	global_load_lds_dwordx4 v[166:167], off
	s_waitcnt vmcnt(8)
	s_waitcnt lgkmcnt(0)
	s_barrier
	s_setprio 1
	s_waitcnt lgkmcnt(0)
	v_mfma_f32_16x16x32_bf16 v[124:127], v[154:157], v[190:193], v[124:127]
	v_mfma_f32_16x16x32_bf16 v[124:127], v[158:161], v[194:197], v[124:127]
	v_mfma_f32_16x16x32_bf16 v[120:123], v[162:165], v[190:193], v[120:123]
	v_mfma_f32_16x16x32_bf16 v[120:123], v[170:173], v[194:197], v[120:123]
	v_mfma_f32_16x16x32_bf16 v[108:111], v[154:157], v[198:201], v[108:111]
	v_mfma_f32_16x16x32_bf16 v[108:111], v[158:161], v[202:205], v[108:111]
	v_mfma_f32_16x16x32_bf16 v[104:107], v[162:165], v[198:201], v[104:107]
	v_mfma_f32_16x16x32_bf16 v[104:107], v[170:173], v[202:205], v[104:107]
	v_mfma_f32_16x16x32_bf16 v[92:95], v[154:157], v[206:209], v[92:95]
	v_mfma_f32_16x16x32_bf16 v[92:95], v[158:161], v[210:213], v[92:95]
	v_mfma_f32_16x16x32_bf16 v[88:91], v[162:165], v[206:209], v[88:91]
	v_mfma_f32_16x16x32_bf16 v[88:91], v[170:173], v[210:213], v[88:91]
	v_mfma_f32_16x16x32_bf16 v[76:79], v[154:157], v[214:217], v[76:79]
	v_mfma_f32_16x16x32_bf16 v[76:79], v[158:161], v[218:221], v[76:79]
	v_mfma_f32_16x16x32_bf16 v[72:75], v[162:165], v[214:217], v[72:75]
	v_mfma_f32_16x16x32_bf16 v[72:75], v[170:173], v[218:221], v[72:75]
	s_setprio 0
	s_setprio 1
	v_mfma_f32_16x16x32_bf16 v[116:119], v[174:177], v[190:193], v[116:119]
	v_mfma_f32_16x16x32_bf16 v[116:119], v[178:181], v[194:197], v[116:119]
	v_mfma_f32_16x16x32_bf16 v[112:115], v[182:185], v[190:193], v[112:115]
	v_mfma_f32_16x16x32_bf16 v[112:115], v[186:189], v[194:197], v[112:115]
	v_mfma_f32_16x16x32_bf16 v[100:103], v[174:177], v[198:201], v[100:103]
	v_mfma_f32_16x16x32_bf16 v[100:103], v[178:181], v[202:205], v[100:103]
	v_mfma_f32_16x16x32_bf16 v[96:99], v[182:185], v[198:201], v[96:99]
	v_mfma_f32_16x16x32_bf16 v[96:99], v[186:189], v[202:205], v[96:99]
	v_mfma_f32_16x16x32_bf16 v[84:87], v[174:177], v[206:209], v[84:87]
	v_mfma_f32_16x16x32_bf16 v[84:87], v[178:181], v[210:213], v[84:87]
	v_mfma_f32_16x16x32_bf16 v[80:83], v[182:185], v[206:209], v[80:83]
	v_mfma_f32_16x16x32_bf16 v[80:83], v[186:189], v[210:213], v[80:83]
	v_mfma_f32_16x16x32_bf16 v[68:71], v[174:177], v[214:217], v[68:71]
	v_mfma_f32_16x16x32_bf16 v[68:71], v[178:181], v[218:221], v[68:71]
	v_mfma_f32_16x16x32_bf16 v[64:67], v[182:185], v[214:217], v[64:67]
	v_mfma_f32_16x16x32_bf16 v[64:67], v[186:189], v[218:221], v[64:67]
	s_setprio 0
	s_barrier
	s_add_i32 s56, s46, s36
	v_lshl_add_u64 v[166:167], s[20:21], 0, v[130:131]
	s_mov_b32 m0, s56
	ds_read_b128 v[190:193], v152 offset:16384
	ds_read_b128 v[194:197], v152 offset:17408
	ds_read_b128 v[198:201], v152 offset:18432
	ds_read_b128 v[202:205], v152 offset:19456
	ds_read_b128 v[206:209], v152 offset:20480
	ds_read_b128 v[210:213], v152 offset:21504
	ds_read_b128 v[214:217], v152 offset:22528
	ds_read_b128 v[218:221], v152 offset:23552
	global_load_lds_dwordx4 v[166:167], off
	s_add_i32 m0, s56, 0x2000
	s_add_u32 s56, s20, 0x84000
	v_lshl_add_u64 v[222:223], s[20:21], 0, v[134:135]
	s_addc_u32 s57, s21, 0
	s_add_i32 s58, s47, s36
	global_load_lds_dwordx4 v[222:223], off
	v_lshl_add_u64 v[224:225], s[56:57], 0, v[130:131]
	s_mov_b32 m0, s58
	v_lshl_add_u64 v[226:227], s[22:23], 0, v[132:133]
	global_load_lds_dwordx4 v[224:225], off
	v_lshl_add_u64 v[224:225], s[56:57], 0, v[134:135]
	s_add_i32 m0, s58, 0x2000
	s_nop 0
	global_load_lds_dwordx4 v[224:225], off
	v_lshl_add_u64 v[224:225], s[22:23], 0, v[128:129]
	s_mov_b32 m0, s37
	s_nop 0
	global_load_lds_dwordx4 v[224:225], off
	s_mov_b32 m0, s38
	s_nop 0
	global_load_lds_dwordx4 v[226:227], off
	s_waitcnt vmcnt(8)
	s_waitcnt lgkmcnt(0)
	s_barrier
; #define PG8_STAGE(bufoff, gbase, voff) do { _Pragma("unroll") for (int _i = 0; _i < 2; ++_i) \
;         __builtin_amdgcn_global_load_lds((const unsigned*)((const char*)(gbase) + (voff)[_i]), (LAS unsigned*)(lds + (bufoff) + ldsw + _i * 8192), 16, 0, 0); } while (0)
; #define PG8_LDA(dst, b, h) do { _Pragma("unroll") for (int m = 0; m < 4; ++m) _Pragma("unroll") for (int k = 0; k < 2; ++k) dst[m][k] = *(const LAS bf16x8*)(lds + PG8_SA(b, h) + aoff + m * 2048 + k * 1024); } while (0)
; #define PG8_LDB(dst, b, h) do { _Pragma("unroll") for (int n = 0; n < 2; ++n) _Pragma("unroll") for (int k = 0; k < 2; ++k) dst[n][k] = *(const LAS bf16x8*)(lds + PG8_SB(b, h) + boff + n * 2048 + k * 1024); } while (0)
; #define PG8_MMA(ai, bj, At, Bt) do { __builtin_amdgcn_s_setprio(1); _Pragma("unroll") for (int m = 0; m < 4; ++m) _Pragma("unroll") for (int n = 0; n < 2; ++n) _Pragma("unroll") for (int k = 0; k < 2; ++k) \
;         acc[ai][bj][m][n] = __builtin_amdgcn_mfma_f32_16x16x32_bf16(Bt[n][k], At[m][k], acc[ai][bj][m][n], 0, 0, 0); __builtin_amdgcn_s_setprio(0); } while (0)
; #define PG8_WAIT_V(n) asm volatile("s_waitcnt vmcnt(" #n ")" ::: "memory")
; #define PG8_WAIT_L(n) asm volatile("s_waitcnt lgkmcnt(" #n ")" ::: "memory")
; #define PG8_BAR __builtin_amdgcn_s_barrier()
; #define PG8_SCHED __builtin_amdgcn_sched_barrier(0)
; template <class EpiT>
; __device__ __forceinline__ void gemm_phase(LAS unsigned char* lds, const Gemm g, const StaticOrder& S, const EpiT& E) {
;     ...
;             PG8_WAIT_V(8); PG8_WAIT_L(0); PG8_BAR; PG8_MMA(1, 0, At, B0); PG8_MMA(1, 1, At, B1); PG8_BAR; PG8_SCHED;
;             PG8_LDB(B0, 1, 0); PG8_LDB(B1, 1, 1); PG8_SCHED; PG8_LDA(At, 1, 0); PG8_STAGE(PG8_SA(0, 1), a2 + hstepA, voffA);
;             PG8_WAIT_V(8); PG8_WAIT_L(0); PG8_BAR; PG8_MMA(0, 0, At, B0); PG8_MMA(0, 1, At, B1); PG8_BAR; PG8_SCHED;
	s_setprio 1
	s_waitcnt lgkmcnt(0)
	v_mfma_f32_16x16x32_bf16 v[60:63], v[154:157], v[190:193], v[60:63]
	v_mfma_f32_16x16x32_bf16 v[60:63], v[158:161], v[194:197], v[60:63]
	v_mfma_f32_16x16x32_bf16 v[56:59], v[162:165], v[190:193], v[56:59]
	v_mfma_f32_16x16x32_bf16 v[56:59], v[170:173], v[194:197], v[56:59]
	v_mfma_f32_16x16x32_bf16 v[44:47], v[154:157], v[198:201], v[44:47]
	v_mfma_f32_16x16x32_bf16 v[44:47], v[158:161], v[202:205], v[44:47]
	v_mfma_f32_16x16x32_bf16 v[40:43], v[162:165], v[198:201], v[40:43]
	v_mfma_f32_16x16x32_bf16 v[40:43], v[170:173], v[202:205], v[40:43]
	v_mfma_f32_16x16x32_bf16 v[28:31], v[154:157], v[206:209], v[28:31]
	v_mfma_f32_16x16x32_bf16 v[28:31], v[158:161], v[210:213], v[28:31]
	v_mfma_f32_16x16x32_bf16 v[24:27], v[162:165], v[206:209], v[24:27]
	v_mfma_f32_16x16x32_bf16 v[24:27], v[170:173], v[210:213], v[24:27]
	v_mfma_f32_16x16x32_bf16 v[12:15], v[154:157], v[214:217], v[12:15]
	v_mfma_f32_16x16x32_bf16 v[12:15], v[158:161], v[218:221], v[12:15]
	v_mfma_f32_16x16x32_bf16 v[8:11], v[162:165], v[214:217], v[8:11]
	v_mfma_f32_16x16x32_bf16 v[8:11], v[170:173], v[218:221], v[8:11]
	s_setprio 0
	s_setprio 1
	v_mfma_f32_16x16x32_bf16 v[52:55], v[174:177], v[190:193], v[52:55]
	v_mfma_f32_16x16x32_bf16 v[52:55], v[178:181], v[194:197], v[52:55]
	v_mfma_f32_16x16x32_bf16 v[48:51], v[182:185], v[190:193], v[48:51]
	v_mfma_f32_16x16x32_bf16 v[48:51], v[186:189], v[194:197], v[48:51]
	v_mfma_f32_16x16x32_bf16 v[36:39], v[174:177], v[198:201], v[36:39]
	v_mfma_f32_16x16x32_bf16 v[36:39], v[178:181], v[202:205], v[36:39]
	v_mfma_f32_16x16x32_bf16 v[32:35], v[182:185], v[198:201], v[32:35]
	v_mfma_f32_16x16x32_bf16 v[32:35], v[186:189], v[202:205], v[32:35]
	v_mfma_f32_16x16x32_bf16 v[20:23], v[174:177], v[206:209], v[20:23]
	v_mfma_f32_16x16x32_bf16 v[20:23], v[178:181], v[210:213], v[20:23]
	v_mfma_f32_16x16x32_bf16 v[16:19], v[182:185], v[206:209], v[16:19]
	v_mfma_f32_16x16x32_bf16 v[16:19], v[186:189], v[210:213], v[16:19]
	v_mfma_f32_16x16x32_bf16 v[4:7], v[174:177], v[214:217], v[4:7]
	v_mfma_f32_16x16x32_bf16 v[4:7], v[178:181], v[218:221], v[4:7]
	v_mfma_f32_16x16x32_bf16 v[0:3], v[182:185], v[214:217], v[0:3]
	v_mfma_f32_16x16x32_bf16 v[0:3], v[186:189], v[218:221], v[0:3]
	s_setprio 0
	s_barrier
	s_add_i32 s56, 0, 0x18000
	s_add_i32 s57, 0, 0x1c000
	v_add_u32_e32 v170, s56, v146
	v_add_u32_e32 v186, s57, v146
	ds_read_b128 v[154:157], v170
	ds_read_b128 v[158:161], v170 offset:1024
	ds_read_b128 v[162:165], v170 offset:2048
	ds_read_b128 v[170:173], v170 offset:3072
	ds_read_b128 v[174:177], v186
	ds_read_b128 v[178:181], v186 offset:1024
	ds_read_b128 v[182:185], v186 offset:2048
	ds_read_b128 v[186:189], v186 offset:3072
	s_add_u32 s22, s22, 0x84000
	s_addc_u32 s23, s23, 0
	s_mov_b32 m0, s39
	v_lshl_add_u64 v[228:229], s[22:23], 0, v[128:129]
	ds_read_b128 v[190:193], v152 offset:32768
	ds_read_b128 v[194:197], v152 offset:33792
	ds_read_b128 v[198:201], v152 offset:34816
	ds_read_b128 v[202:205], v152 offset:35840
	ds_read_b128 v[206:209], v152 offset:36864
	ds_read_b128 v[210:213], v152 offset:37888
	ds_read_b128 v[214:217], v152 offset:38912
	ds_read_b128 v[218:221], v152 offset:39936
	global_load_lds_dwordx4 v[228:229], off
	v_lshl_add_u64 v[228:229], s[22:23], 0, v[132:133]
	s_mov_b32 m0, s40
	s_nop 0
	global_load_lds_dwordx4 v[228:229], off
	s_waitcnt vmcnt(8)
	s_waitcnt lgkmcnt(0)
	s_barrier
	s_setprio 1
	s_waitcnt lgkmcnt(0)
	v_mfma_f32_16x16x32_bf16 v[124:127], v[154:157], v[190:193], v[124:127]
	v_mfma_f32_16x16x32_bf16 v[124:127], v[158:161], v[194:197], v[124:127]
	v_mfma_f32_16x16x32_bf16 v[120:123], v[162:165], v[190:193], v[120:123]
	v_mfma_f32_16x16x32_bf16 v[120:123], v[170:173], v[194:197], v[120:123]
	v_mfma_f32_16x16x32_bf16 v[108:111], v[154:157], v[198:201], v[108:111]
	v_mfma_f32_16x16x32_bf16 v[108:111], v[158:161], v[202:205], v[108:111]
	v_mfma_f32_16x16x32_bf16 v[104:107], v[162:165], v[198:201], v[104:107]
	v_mfma_f32_16x16x32_bf16 v[104:107], v[170:173], v[202:205], v[104:107]
	v_mfma_f32_16x16x32_bf16 v[92:95], v[154:157], v[206:209], v[92:95]
	v_mfma_f32_16x16x32_bf16 v[92:95], v[158:161], v[210:213], v[92:95]
	v_mfma_f32_16x16x32_bf16 v[88:91], v[162:165], v[206:209], v[88:91]
	v_mfma_f32_16x16x32_bf16 v[88:91], v[170:173], v[210:213], v[88:91]
	v_mfma_f32_16x16x32_bf16 v[76:79], v[154:157], v[214:217], v[76:79]
	v_mfma_f32_16x16x32_bf16 v[76:79], v[158:161], v[218:221], v[76:79]
	v_mfma_f32_16x16x32_bf16 v[72:75], v[162:165], v[214:217], v[72:75]
	v_mfma_f32_16x16x32_bf16 v[72:75], v[170:173], v[218:221], v[72:75]
	s_setprio 0
	s_setprio 1
	v_mfma_f32_16x16x32_bf16 v[116:119], v[174:177], v[190:193], v[116:119]
	v_mfma_f32_16x16x32_bf16 v[116:119], v[178:181], v[194:197], v[116:119]
	v_mfma_f32_16x16x32_bf16 v[112:115], v[182:185], v[190:193], v[112:115]
	v_mfma_f32_16x16x32_bf16 v[112:115], v[186:189], v[194:197], v[112:115]
	v_mfma_f32_16x16x32_bf16 v[100:103], v[174:177], v[198:201], v[100:103]
	v_mfma_f32_16x16x32_bf16 v[100:103], v[178:181], v[202:205], v[100:103]
	v_mfma_f32_16x16x32_bf16 v[96:99], v[182:185], v[198:201], v[96:99]
	v_mfma_f32_16x16x32_bf16 v[96:99], v[186:189], v[202:205], v[96:99]
	v_mfma_f32_16x16x32_bf16 v[84:87], v[174:177], v[206:209], v[84:87]
	v_mfma_f32_16x16x32_bf16 v[84:87], v[178:181], v[210:213], v[84:87]
	v_mfma_f32_16x16x32_bf16 v[80:83], v[182:185], v[206:209], v[80:83]
	v_mfma_f32_16x16x32_bf16 v[80:83], v[186:189], v[210:213], v[80:83]
	v_mfma_f32_16x16x32_bf16 v[68:71], v[174:177], v[214:217], v[68:71]
	v_mfma_f32_16x16x32_bf16 v[68:71], v[178:181], v[218:221], v[68:71]
	v_mfma_f32_16x16x32_bf16 v[64:67], v[182:185], v[214:217], v[64:67]
	v_mfma_f32_16x16x32_bf16 v[64:67], v[186:189], v[218:221], v[64:67]
	s_setprio 0
	s_barrier
; #define PG8_STAGE(bufoff, gbase, voff) do { _Pragma("unroll") for (int _i = 0; _i < 2; ++_i) \
;         __builtin_amdgcn_global_load_lds((const unsigned*)((const char*)(gbase) + (voff)[_i]), (LAS unsigned*)(lds + (bufoff) + ldsw + _i * 8192), 16, 0, 0); } while (0)
; #define PG8_LDA(dst, b, h) do { _Pragma("unroll") for (int m = 0; m < 4; ++m) _Pragma("unroll") for (int k = 0; k < 2; ++k) dst[m][k] = *(const LAS bf16x8*)(lds + PG8_SA(b, h) + aoff + m * 2048 + k * 1024); } while (0)
; #define PG8_MMA(ai, bj, At, Bt) do { __builtin_amdgcn_s_setprio(1); _Pragma("unroll") for (int m = 0; m < 4; ++m) _Pragma("unroll") for (int n = 0; n < 2; ++n) _Pragma("unroll") for (int k = 0; k < 2; ++k) \
;         acc[ai][bj][m][n] = __builtin_amdgcn_mfma_f32_16x16x32_bf16(Bt[n][k], At[m][k], acc[ai][bj][m][n], 0, 0, 0); __builtin_amdgcn_s_setprio(0); } while (0)
; #define PG8_WAIT_V(n) asm volatile("s_waitcnt vmcnt(" #n ")" ::: "memory")
; #define PG8_WAIT_L(n) asm volatile("s_waitcnt lgkmcnt(" #n ")" ::: "memory")
; #define PG8_BAR __builtin_amdgcn_s_barrier()
; #define PG8_SCHED __builtin_amdgcn_sched_barrier(0)
; template <class EpiT>
; __device__ __forceinline__ void gemm_phase(LAS unsigned char* lds, const Gemm g, const StaticOrder& S, const EpiT& E) {
;     ...
;             PG8_LDA(At, 1, 1); PG8_STAGE(PG8_SB(1, 0), b3, voffB); PG8_STAGE(PG8_SB(1, 1), b3 + hstepB, voffB); PG8_STAGE(PG8_SA(1, 0), a3, voffA);
;             PG8_WAIT_V(8); PG8_WAIT_L(0); PG8_BAR; PG8_MMA(1, 0, At, B0); PG8_MMA(1, 1, At, B1); PG8_BAR; PG8_SCHED;
;         }
;         if (wr == 0) PG8_BAR;
	s_add_i32 s22, s56, s36
	v_lshl_add_u64 v[166:167], v[166:167], 0, s[12:13]
	s_mov_b32 m0, s22
	ds_read_b128 v[190:193], v152 offset:49152
	ds_read_b128 v[194:197], v152 offset:50176
	ds_read_b128 v[198:201], v152 offset:51200
	ds_read_b128 v[202:205], v152 offset:52224
	ds_read_b128 v[206:209], v152 offset:53248
	ds_read_b128 v[210:213], v152 offset:54272
	ds_read_b128 v[214:217], v152 offset:55296
	ds_read_b128 v[218:221], v152 offset:56320
	global_load_lds_dwordx4 v[166:167], off
	s_add_i32 m0, s22, 0x2000
	s_add_u32 s20, s20, 0x84080
	v_lshl_add_u64 v[166:167], v[222:223], 0, s[12:13]
	s_addc_u32 s21, s21, 0
	s_add_i32 s22, s57, s36
	global_load_lds_dwordx4 v[166:167], off
	v_lshl_add_u64 v[166:167], s[20:21], 0, v[130:131]
	s_mov_b32 m0, s22
	s_nop 0
	global_load_lds_dwordx4 v[166:167], off
	v_lshl_add_u64 v[166:167], s[20:21], 0, v[134:135]
	s_add_i32 m0, s22, 0x2000
	s_nop 0
	global_load_lds_dwordx4 v[166:167], off
	v_lshl_add_u64 v[166:167], v[224:225], 0, s[12:13]
	s_mov_b32 m0, s42
	s_nop 0
	global_load_lds_dwordx4 v[166:167], off
	v_lshl_add_u64 v[166:167], v[226:227], 0, s[12:13]
	s_mov_b32 m0, s43
	s_nop 0
	global_load_lds_dwordx4 v[166:167], off
	s_waitcnt vmcnt(8)
	s_waitcnt lgkmcnt(0)
	s_barrier
	s_setprio 1
	s_waitcnt lgkmcnt(0)
	v_mfma_f32_16x16x32_bf16 v[60:63], v[154:157], v[190:193], v[60:63]
	v_mfma_f32_16x16x32_bf16 v[60:63], v[158:161], v[194:197], v[60:63]
	v_mfma_f32_16x16x32_bf16 v[56:59], v[162:165], v[190:193], v[56:59]
	v_mfma_f32_16x16x32_bf16 v[56:59], v[170:173], v[194:197], v[56:59]
	v_mfma_f32_16x16x32_bf16 v[44:47], v[154:157], v[198:201], v[44:47]
	v_mfma_f32_16x16x32_bf16 v[44:47], v[158:161], v[202:205], v[44:47]
	v_mfma_f32_16x16x32_bf16 v[40:43], v[162:165], v[198:201], v[40:43]
	v_mfma_f32_16x16x32_bf16 v[40:43], v[170:173], v[202:205], v[40:43]
	v_mfma_f32_16x16x32_bf16 v[28:31], v[154:157], v[206:209], v[28:31]
	v_mfma_f32_16x16x32_bf16 v[28:31], v[158:161], v[210:213], v[28:31]
	v_mfma_f32_16x16x32_bf16 v[24:27], v[162:165], v[206:209], v[24:27]
	v_mfma_f32_16x16x32_bf16 v[24:27], v[170:173], v[210:213], v[24:27]
	v_mfma_f32_16x16x32_bf16 v[12:15], v[154:157], v[214:217], v[12:15]
	v_mfma_f32_16x16x32_bf16 v[12:15], v[158:161], v[218:221], v[12:15]
	v_mfma_f32_16x16x32_bf16 v[8:11], v[162:165], v[214:217], v[8:11]
	v_mfma_f32_16x16x32_bf16 v[8:11], v[170:173], v[218:221], v[8:11]
	s_setprio 0
	s_setprio 1
	v_mfma_f32_16x16x32_bf16 v[52:55], v[174:177], v[190:193], v[52:55]
	v_mfma_f32_16x16x32_bf16 v[52:55], v[178:181], v[194:197], v[52:55]
	v_mfma_f32_16x16x32_bf16 v[48:51], v[182:185], v[190:193], v[48:51]
	v_mfma_f32_16x16x32_bf16 v[48:51], v[186:189], v[194:197], v[48:51]
	v_mfma_f32_16x16x32_bf16 v[36:39], v[174:177], v[198:201], v[36:39]
	v_mfma_f32_16x16x32_bf16 v[36:39], v[178:181], v[202:205], v[36:39]
	v_mfma_f32_16x16x32_bf16 v[32:35], v[182:185], v[198:201], v[32:35]
	v_mfma_f32_16x16x32_bf16 v[32:35], v[186:189], v[202:205], v[32:35]
	v_mfma_f32_16x16x32_bf16 v[20:23], v[174:177], v[206:209], v[20:23]
	v_mfma_f32_16x16x32_bf16 v[20:23], v[178:181], v[210:213], v[20:23]
	v_mfma_f32_16x16x32_bf16 v[16:19], v[182:185], v[206:209], v[16:19]
	v_mfma_f32_16x16x32_bf16 v[16:19], v[186:189], v[210:213], v[16:19]
	v_mfma_f32_16x16x32_bf16 v[4:7], v[174:177], v[214:217], v[4:7]
	v_mfma_f32_16x16x32_bf16 v[4:7], v[178:181], v[218:221], v[4:7]
	v_mfma_f32_16x16x32_bf16 v[0:3], v[182:185], v[214:217], v[0:3]
	v_mfma_f32_16x16x32_bf16 v[0:3], v[186:189], v[218:221], v[0:3]
	s_setprio 0
	s_barrier
	s_add_i32 s55, s55, 2
	s_add_u32 s18, s18, 0x100
	s_addc_u32 s19, s19, 0
	s_add_u32 s53, s53, 0x100
	s_addc_u32 s54, s54, 0
	s_cmp_gt_u32 s55, 29
	s_cbranch_scc0 .LBB0_1032
	s_and_b64 vcc, exec, s[14:15]
	s_cbranch_vccz .LBB0_1035
	s_barrier

; #define PG8_STAGE(bufoff, gbase, voff) do { _Pragma("unroll") for (int _i = 0; _i < 2; ++_i) \
;         __builtin_amdgcn_global_load_lds((const unsigned*)((const char*)(gbase) + (voff)[_i]), (LAS unsigned*)(lds + (bufoff) + ldsw + _i * 8192), 16, 0, 0); } while (0)
; #define PG8_LDA(dst, b, h) do { _Pragma("unroll") for (int m = 0; m < 4; ++m) _Pragma("unroll") for (int k = 0; k < 2; ++k) dst[m][k] = *(const LAS bf16x8*)(lds + PG8_SA(b, h) + aoff + m * 2048 + k * 1024); } while (0)
; #define PG8_LDB(dst, b, h) do { _Pragma("unroll") for (int n = 0; n < 2; ++n) _Pragma("unroll") for (int k = 0; k < 2; ++k) dst[n][k] = *(const LAS bf16x8*)(lds + PG8_SB(b, h) + boff + n * 2048 + k * 1024); } while (0)
; #define PG8_MMA(ai, bj, At, Bt) do { __builtin_amdgcn_s_setprio(1); _Pragma("unroll") for (int m = 0; m < 4; ++m) _Pragma("unroll") for (int n = 0; n < 2; ++n) _Pragma("unroll") for (int k = 0; k < 2; ++k) \
;         acc[ai][bj][m][n] = __builtin_amdgcn_mfma_f32_16x16x32_bf16(Bt[n][k], At[m][k], acc[ai][bj][m][n], 0, 0, 0); __builtin_amdgcn_s_setprio(0); } while (0)
; #define PG8_WAIT_V(n) asm volatile("s_waitcnt vmcnt(" #n ")" ::: "memory")
; template <class EpiT>
; __device__ __forceinline__ void gemm_phase(LAS unsigned char* lds, const Gemm g, const StaticOrder& S, const EpiT& E) {
;     ...
;         const char* nA = has_next ? (const char*)g.A + (size_t)nxt.pm * tstepA + (size_t)nxt.pn * g.a_koff * 2 : cA; const char* nB = has_next ? (const char*)g.Bt + (size_t)nxt.pn * tstepB : cB;
;         for (int t = 0; t < nt; t += 2) {
;             const bool last = (t == nt - 2);
;             const char* a1 = cA + (size_t)(t + 1) * kstep;
;             const char* a2 = last ? nA : cA + (size_t)(t + 2) * kstep; const char* b2 = last ? nB : cB + (size_t)(t + 2) * kstep;
;             const char* a3 = a2 + kstep; const char* b3 = b2 + kstep;
;             PG8_LDB(B0, 0, 0); PG8_LDB(B1, 0, 1); PG8_SCHED; PG8_LDA(At, 0, 0); PG8_STAGE(PG8_SA(1, 1), a1 + hstepA, voffA);
;             PG8_WAIT_V(8); PG8_WAIT_L(0); PG8_BAR; PG8_MMA(0, 0, At, B0); PG8_MMA(0, 1, At, B1); PG8_BAR; PG8_SCHED;
;             PG8_LDA(At, 0, 1); PG8_STAGE(PG8_SB(0, 0), b2, voffB); PG8_STAGE(PG8_SB(0, 1), b2 + hstepB, voffB); PG8_STAGE(PG8_SA(0, 0), a2, voffA);
;             PG8_WAIT_V(8); PG8_WAIT_L(0); PG8_BAR; PG8_MMA(1, 0, At, B0); PG8_MMA(1, 1, At, B1); PG8_BAR; PG8_SCHED;
.LBB0_1156:
	ds_read_b128 v[154:157], v150
	ds_read_b128 v[158:161], v150 offset:1024
	ds_read_b128 v[162:165], v150 offset:2048
	ds_read_b128 v[170:173], v150 offset:3072
	ds_read_b128 v[174:177], v151
	ds_read_b128 v[178:181], v151 offset:1024
	ds_read_b128 v[182:185], v151 offset:2048
	ds_read_b128 v[186:189], v151 offset:3072
	s_add_u32 s18, s16, 0xfff7c080
	s_addc_u32 s19, s17, -1
	s_cmp_eq_u32 s53, 28
	s_cselect_b32 s21, s3, s19
	s_cselect_b32 s20, s2, s18
	s_cselect_b32 s19, s15, s52
	s_cselect_b32 s18, s14, s51
	v_lshl_add_u64 v[144:145], s[16:17], 0, v[136:137]
	s_add_i32 m0, s36, 0xc000
	ds_read_b128 v[190:193], v152
	ds_read_b128 v[194:197], v152 offset:1024
	ds_read_b128 v[198:201], v152 offset:2048
	ds_read_b128 v[202:205], v152 offset:3072
	ds_read_b128 v[206:209], v152 offset:4096
	ds_read_b128 v[210:213], v152 offset:5120
	ds_read_b128 v[214:217], v152 offset:6144
	ds_read_b128 v[218:221], v152 offset:7168
	global_load_lds_dwordx4 v[144:145], off
	v_lshl_add_u64 v[144:145], s[16:17], 0, v[138:139]
	s_add_i32 m0, s36, 0xe000
	s_nop 0
	global_load_lds_dwordx4 v[144:145], off
	s_waitcnt vmcnt(8)
	s_waitcnt lgkmcnt(0)
	s_barrier
	s_setprio 1
	s_waitcnt lgkmcnt(0)
	v_mfma_f32_16x16x32_bf16 v[124:127], v[154:157], v[190:193], v[124:127]
	v_mfma_f32_16x16x32_bf16 v[124:127], v[158:161], v[194:197], v[124:127]
	v_mfma_f32_16x16x32_bf16 v[120:123], v[162:165], v[190:193], v[120:123]
	v_mfma_f32_16x16x32_bf16 v[120:123], v[170:173], v[194:197], v[120:123]
	v_mfma_f32_16x16x32_bf16 v[108:111], v[154:157], v[198:201], v[108:111]
	v_mfma_f32_16x16x32_bf16 v[108:111], v[158:161], v[202:205], v[108:111]
	v_mfma_f32_16x16x32_bf16 v[104:107], v[162:165], v[198:201], v[104:107]
	v_mfma_f32_16x16x32_bf16 v[104:107], v[170:173], v[202:205], v[104:107]
	v_mfma_f32_16x16x32_bf16 v[92:95], v[154:157], v[206:209], v[92:95]
	v_mfma_f32_16x16x32_bf16 v[92:95], v[158:161], v[210:213], v[92:95]
	v_mfma_f32_16x16x32_bf16 v[88:91], v[162:165], v[206:209], v[88:91]
	v_mfma_f32_16x16x32_bf16 v[88:91], v[170:173], v[210:213], v[88:91]
	v_mfma_f32_16x16x32_bf16 v[76:79], v[154:157], v[214:217], v[76:79]
	v_mfma_f32_16x16x32_bf16 v[76:79], v[158:161], v[218:221], v[76:79]
	v_mfma_f32_16x16x32_bf16 v[72:75], v[162:165], v[214:217], v[72:75]
	v_mfma_f32_16x16x32_bf16 v[72:75], v[170:173], v[218:221], v[72:75]
	s_setprio 0
	s_setprio 1
	v_mfma_f32_16x16x32_bf16 v[116:119], v[174:177], v[190:193], v[116:119]
	v_mfma_f32_16x16x32_bf16 v[116:119], v[178:181], v[194:197], v[116:119]
	v_mfma_f32_16x16x32_bf16 v[112:115], v[182:185], v[190:193], v[112:115]
	v_mfma_f32_16x16x32_bf16 v[112:115], v[186:189], v[194:197], v[112:115]
	v_mfma_f32_16x16x32_bf16 v[100:103], v[174:177], v[198:201], v[100:103]
	v_mfma_f32_16x16x32_bf16 v[100:103], v[178:181], v[202:205], v[100:103]
	v_mfma_f32_16x16x32_bf16 v[96:99], v[182:185], v[198:201], v[96:99]
	v_mfma_f32_16x16x32_bf16 v[96:99], v[186:189], v[202:205], v[96:99]
	v_mfma_f32_16x16x32_bf16 v[84:87], v[174:177], v[206:209], v[84:87]
	v_mfma_f32_16x16x32_bf16 v[84:87], v[178:181], v[210:213], v[84:87]
	v_mfma_f32_16x16x32_bf16 v[80:83], v[182:185], v[206:209], v[80:83]
	v_mfma_f32_16x16x32_bf16 v[80:83], v[186:189], v[210:213], v[80:83]
	v_mfma_f32_16x16x32_bf16 v[68:71], v[174:177], v[214:217], v[68:71]
	v_mfma_f32_16x16x32_bf16 v[68:71], v[178:181], v[218:221], v[68:71]
	v_mfma_f32_16x16x32_bf16 v[64:67], v[182:185], v[214:217], v[64:67]
	v_mfma_f32_16x16x32_bf16 v[64:67], v[186:189], v[218:221], v[64:67]
	s_setprio 0
	s_barrier
	s_add_i32 s54, s44, s27
	v_lshl_add_u64 v[144:145], s[18:19], 0, v[132:133]
	s_mov_b32 m0, s54
	ds_read_b128 v[190:193], v152 offset:16384
	ds_read_b128 v[194:197], v152 offset:17408
	ds_read_b128 v[198:201], v152 offset:18432
	ds_read_b128 v[202:205], v152 offset:19456
	ds_read_b128 v[206:209], v152 offset:20480
	ds_read_b128 v[210:213], v152 offset:21504
	ds_read_b128 v[214:217], v152 offset:22528
	ds_read_b128 v[218:221], v152 offset:23552
	global_load_lds_dwordx4 v[144:145], off
	s_add_i32 m0, s54, 0x2000
	s_add_u32 s54, s18, 0x84000
	v_lshl_add_u64 v[166:167], s[18:19], 0, v[128:129]
	s_addc_u32 s55, s19, 0
	s_add_i32 s56, s45, s27
	global_load_lds_dwordx4 v[166:167], off
	v_lshl_add_u64 v[222:223], s[54:55], 0, v[132:133]
	s_mov_b32 m0, s56
	v_lshl_add_u64 v[224:225], s[20:21], 0, v[130:131]
	global_load_lds_dwordx4 v[222:223], off
	v_lshl_add_u64 v[222:223], s[54:55], 0, v[128:129]
	s_add_i32 m0, s56, 0x2000
	s_nop 0
	global_load_lds_dwordx4 v[222:223], off
	v_lshl_add_u64 v[222:223], s[20:21], 0, v[134:135]
	s_mov_b32 m0, s36
	s_nop 0
	global_load_lds_dwordx4 v[222:223], off
	s_mov_b32 m0, s37
	s_nop 0
	global_load_lds_dwordx4 v[224:225], off
	s_waitcnt vmcnt(8)
	s_waitcnt lgkmcnt(0)
	s_barrier
; #define PG8_STAGE(bufoff, gbase, voff) do { _Pragma("unroll") for (int _i = 0; _i < 2; ++_i) \
;         __builtin_amdgcn_global_load_lds((const unsigned*)((const char*)(gbase) + (voff)[_i]), (LAS unsigned*)(lds + (bufoff) + ldsw + _i * 8192), 16, 0, 0); } while (0)
; #define PG8_LDA(dst, b, h) do { _Pragma("unroll") for (int m = 0; m < 4; ++m) _Pragma("unroll") for (int k = 0; k < 2; ++k) dst[m][k] = *(const LAS bf16x8*)(lds + PG8_SA(b, h) + aoff + m * 2048 + k * 1024); } while (0)
; #define PG8_LDB(dst, b, h) do { _Pragma("unroll") for (int n = 0; n < 2; ++n) _Pragma("unroll") for (int k = 0; k < 2; ++k) dst[n][k] = *(const LAS bf16x8*)(lds + PG8_SB(b, h) + boff + n * 2048 + k * 1024); } while (0)
; #define PG8_MMA(ai, bj, At, Bt) do { __builtin_amdgcn_s_setprio(1); _Pragma("unroll") for (int m = 0; m < 4; ++m) _Pragma("unroll") for (int n = 0; n < 2; ++n) _Pragma("unroll") for (int k = 0; k < 2; ++k) \
;         acc[ai][bj][m][n] = __builtin_amdgcn_mfma_f32_16x16x32_bf16(Bt[n][k], At[m][k], acc[ai][bj][m][n], 0, 0, 0); __builtin_amdgcn_s_setprio(0); } while (0)
; #define PG8_WAIT_V(n) asm volatile("s_waitcnt vmcnt(" #n ")" ::: "memory")
; #define PG8_WAIT_L(n) asm volatile("s_waitcnt lgkmcnt(" #n ")" ::: "memory")
; #define PG8_BAR __builtin_amdgcn_s_barrier()
; #define PG8_SCHED __builtin_amdgcn_sched_barrier(0)
; template <class EpiT>
; __device__ __forceinline__ void gemm_phase(LAS unsigned char* lds, const Gemm g, const StaticOrder& S, const EpiT& E) {
;     ...
;             PG8_WAIT_V(8); PG8_WAIT_L(0); PG8_BAR; PG8_MMA(1, 0, At, B0); PG8_MMA(1, 1, At, B1); PG8_BAR; PG8_SCHED;
;             PG8_LDB(B0, 1, 0); PG8_LDB(B1, 1, 1); PG8_SCHED; PG8_LDA(At, 1, 0); PG8_STAGE(PG8_SA(0, 1), a2 + hstepA, voffA);
;             PG8_WAIT_V(8); PG8_WAIT_L(0); PG8_BAR; PG8_MMA(0, 0, At, B0); PG8_MMA(0, 1, At, B1); PG8_BAR; PG8_SCHED;
	s_setprio 1
	s_waitcnt lgkmcnt(0)
	v_mfma_f32_16x16x32_bf16 v[60:63], v[154:157], v[190:193], v[60:63]
	v_mfma_f32_16x16x32_bf16 v[60:63], v[158:161], v[194:197], v[60:63]
	v_mfma_f32_16x16x32_bf16 v[56:59], v[162:165], v[190:193], v[56:59]
	v_mfma_f32_16x16x32_bf16 v[56:59], v[170:173], v[194:197], v[56:59]
	v_mfma_f32_16x16x32_bf16 v[44:47], v[154:157], v[198:201], v[44:47]
	v_mfma_f32_16x16x32_bf16 v[44:47], v[158:161], v[202:205], v[44:47]
	v_mfma_f32_16x16x32_bf16 v[40:43], v[162:165], v[198:201], v[40:43]
	v_mfma_f32_16x16x32_bf16 v[40:43], v[170:173], v[202:205], v[40:43]
	v_mfma_f32_16x16x32_bf16 v[28:31], v[154:157], v[206:209], v[28:31]
	v_mfma_f32_16x16x32_bf16 v[28:31], v[158:161], v[210:213], v[28:31]
	v_mfma_f32_16x16x32_bf16 v[24:27], v[162:165], v[206:209], v[24:27]
	v_mfma_f32_16x16x32_bf16 v[24:27], v[170:173], v[210:213], v[24:27]
	v_mfma_f32_16x16x32_bf16 v[12:15], v[154:157], v[214:217], v[12:15]
	v_mfma_f32_16x16x32_bf16 v[12:15], v[158:161], v[218:221], v[12:15]
	v_mfma_f32_16x16x32_bf16 v[8:11], v[162:165], v[214:217], v[8:11]
	v_mfma_f32_16x16x32_bf16 v[8:11], v[170:173], v[218:221], v[8:11]
	s_setprio 0
	s_setprio 1
	v_mfma_f32_16x16x32_bf16 v[52:55], v[174:177], v[190:193], v[52:55]
	v_mfma_f32_16x16x32_bf16 v[52:55], v[178:181], v[194:197], v[52:55]
	v_mfma_f32_16x16x32_bf16 v[48:51], v[182:185], v[190:193], v[48:51]
	v_mfma_f32_16x16x32_bf16 v[48:51], v[186:189], v[194:197], v[48:51]
	v_mfma_f32_16x16x32_bf16 v[36:39], v[174:177], v[198:201], v[36:39]
	v_mfma_f32_16x16x32_bf16 v[36:39], v[178:181], v[202:205], v[36:39]
	v_mfma_f32_16x16x32_bf16 v[32:35], v[182:185], v[198:201], v[32:35]
	v_mfma_f32_16x16x32_bf16 v[32:35], v[186:189], v[202:205], v[32:35]
	v_mfma_f32_16x16x32_bf16 v[20:23], v[174:177], v[206:209], v[20:23]
	v_mfma_f32_16x16x32_bf16 v[20:23], v[178:181], v[210:213], v[20:23]
	v_mfma_f32_16x16x32_bf16 v[16:19], v[182:185], v[206:209], v[16:19]
	v_mfma_f32_16x16x32_bf16 v[16:19], v[186:189], v[210:213], v[16:19]
	v_mfma_f32_16x16x32_bf16 v[4:7], v[174:177], v[214:217], v[4:7]
	v_mfma_f32_16x16x32_bf16 v[4:7], v[178:181], v[218:221], v[4:7]
	v_mfma_f32_16x16x32_bf16 v[0:3], v[182:185], v[214:217], v[0:3]
	v_mfma_f32_16x16x32_bf16 v[0:3], v[186:189], v[218:221], v[0:3]
	s_setprio 0
	s_barrier
	s_add_i32 s54, 0, 0x18000
	v_add_u32_e32 v153, s54, v147
	s_add_i32 s55, 0, 0x1c000
	ds_read_b128 v[154:157], v153
	ds_read_b128 v[158:161], v153 offset:1024
	ds_read_b128 v[162:165], v153 offset:2048
	ds_read_b128 v[170:173], v153 offset:3072
	v_add_u32_e32 v153, s55, v147
	ds_read_b128 v[174:177], v153
	ds_read_b128 v[178:181], v153 offset:1024
	ds_read_b128 v[182:185], v153 offset:2048
	ds_read_b128 v[186:189], v153 offset:3072
	s_add_u32 s20, s20, 0x84000
	s_addc_u32 s21, s21, 0
	s_mov_b32 m0, s38
	v_lshl_add_u64 v[226:227], s[20:21], 0, v[134:135]
	ds_read_b128 v[190:193], v152 offset:32768
	ds_read_b128 v[194:197], v152 offset:33792
	ds_read_b128 v[198:201], v152 offset:34816
	ds_read_b128 v[202:205], v152 offset:35840
	ds_read_b128 v[206:209], v152 offset:36864
	ds_read_b128 v[210:213], v152 offset:37888
	ds_read_b128 v[214:217], v152 offset:38912
	ds_read_b128 v[218:221], v152 offset:39936
	global_load_lds_dwordx4 v[226:227], off
	v_lshl_add_u64 v[226:227], s[20:21], 0, v[130:131]
	s_mov_b32 m0, s39
	s_nop 0
	global_load_lds_dwordx4 v[226:227], off
	s_waitcnt vmcnt(8)
	s_waitcnt lgkmcnt(0)
	s_barrier
	s_setprio 1
	s_waitcnt lgkmcnt(0)
	v_mfma_f32_16x16x32_bf16 v[124:127], v[154:157], v[190:193], v[124:127]
	v_mfma_f32_16x16x32_bf16 v[124:127], v[158:161], v[194:197], v[124:127]
	v_mfma_f32_16x16x32_bf16 v[120:123], v[162:165], v[190:193], v[120:123]
	v_mfma_f32_16x16x32_bf16 v[120:123], v[170:173], v[194:197], v[120:123]
	v_mfma_f32_16x16x32_bf16 v[108:111], v[154:157], v[198:201], v[108:111]
	v_mfma_f32_16x16x32_bf16 v[108:111], v[158:161], v[202:205], v[108:111]
	v_mfma_f32_16x16x32_bf16 v[104:107], v[162:165], v[198:201], v[104:107]
	v_mfma_f32_16x16x32_bf16 v[104:107], v[170:173], v[202:205], v[104:107]
	v_mfma_f32_16x16x32_bf16 v[92:95], v[154:157], v[206:209], v[92:95]
	v_mfma_f32_16x16x32_bf16 v[92:95], v[158:161], v[210:213], v[92:95]
	v_mfma_f32_16x16x32_bf16 v[88:91], v[162:165], v[206:209], v[88:91]
	v_mfma_f32_16x16x32_bf16 v[88:91], v[170:173], v[210:213], v[88:91]
	v_mfma_f32_16x16x32_bf16 v[76:79], v[154:157], v[214:217], v[76:79]
	v_mfma_f32_16x16x32_bf16 v[76:79], v[158:161], v[218:221], v[76:79]
	v_mfma_f32_16x16x32_bf16 v[72:75], v[162:165], v[214:217], v[72:75]
	v_mfma_f32_16x16x32_bf16 v[72:75], v[170:173], v[218:221], v[72:75]
	s_setprio 0
	s_setprio 1
	v_mfma_f32_16x16x32_bf16 v[116:119], v[174:177], v[190:193], v[116:119]
	v_mfma_f32_16x16x32_bf16 v[116:119], v[178:181], v[194:197], v[116:119]
	v_mfma_f32_16x16x32_bf16 v[112:115], v[182:185], v[190:193], v[112:115]
	v_mfma_f32_16x16x32_bf16 v[112:115], v[186:189], v[194:197], v[112:115]
	v_mfma_f32_16x16x32_bf16 v[100:103], v[174:177], v[198:201], v[100:103]
	v_mfma_f32_16x16x32_bf16 v[100:103], v[178:181], v[202:205], v[100:103]
	v_mfma_f32_16x16x32_bf16 v[96:99], v[182:185], v[198:201], v[96:99]
	v_mfma_f32_16x16x32_bf16 v[96:99], v[186:189], v[202:205], v[96:99]
	v_mfma_f32_16x16x32_bf16 v[84:87], v[174:177], v[206:209], v[84:87]
	v_mfma_f32_16x16x32_bf16 v[84:87], v[178:181], v[210:213], v[84:87]
	v_mfma_f32_16x16x32_bf16 v[80:83], v[182:185], v[206:209], v[80:83]
	v_mfma_f32_16x16x32_bf16 v[80:83], v[186:189], v[210:213], v[80:83]
	v_mfma_f32_16x16x32_bf16 v[68:71], v[174:177], v[214:217], v[68:71]
	v_mfma_f32_16x16x32_bf16 v[68:71], v[178:181], v[218:221], v[68:71]
	v_mfma_f32_16x16x32_bf16 v[64:67], v[182:185], v[214:217], v[64:67]
	v_mfma_f32_16x16x32_bf16 v[64:67], v[186:189], v[218:221], v[64:67]
	s_setprio 0
	s_barrier
; #define PG8_STAGE(bufoff, gbase, voff) do { _Pragma("unroll") for (int _i = 0; _i < 2; ++_i) \
;         __builtin_amdgcn_global_load_lds((const unsigned*)((const char*)(gbase) + (voff)[_i]), (LAS unsigned*)(lds + (bufoff) + ldsw + _i * 8192), 16, 0, 0); } while (0)
; #define PG8_LDA(dst, b, h) do { _Pragma("unroll") for (int m = 0; m < 4; ++m) _Pragma("unroll") for (int k = 0; k < 2; ++k) dst[m][k] = *(const LAS bf16x8*)(lds + PG8_SA(b, h) + aoff + m * 2048 + k * 1024); } while (0)
; #define PG8_MMA(ai, bj, At, Bt) do { __builtin_amdgcn_s_setprio(1); _Pragma("unroll") for (int m = 0; m < 4; ++m) _Pragma("unroll") for (int n = 0; n < 2; ++n) _Pragma("unroll") for (int k = 0; k < 2; ++k) \
;         acc[ai][bj][m][n] = __builtin_amdgcn_mfma_f32_16x16x32_bf16(Bt[n][k], At[m][k], acc[ai][bj][m][n], 0, 0, 0); __builtin_amdgcn_s_setprio(0); } while (0)
; #define PG8_WAIT_V(n) asm volatile("s_waitcnt vmcnt(" #n ")" ::: "memory")
; #define PG8_WAIT_L(n) asm volatile("s_waitcnt lgkmcnt(" #n ")" ::: "memory")
; #define PG8_BAR __builtin_amdgcn_s_barrier()
; #define PG8_SCHED __builtin_amdgcn_sched_barrier(0)
; template <class EpiT>
; __device__ __forceinline__ void gemm_phase(LAS unsigned char* lds, const Gemm g, const StaticOrder& S, const EpiT& E) {
;     ...
;             PG8_LDA(At, 1, 1); PG8_STAGE(PG8_SB(1, 0), b3, voffB); PG8_STAGE(PG8_SB(1, 1), b3 + hstepB, voffB); PG8_STAGE(PG8_SA(1, 0), a3, voffA);
;             PG8_WAIT_V(8); PG8_WAIT_L(0); PG8_BAR; PG8_MMA(1, 0, At, B0); PG8_MMA(1, 1, At, B1); PG8_BAR; PG8_SCHED;
;         }
;         if (wr == 0) PG8_BAR;
	s_add_i32 s20, s54, s27
	v_lshl_add_u64 v[144:145], v[144:145], 0, s[10:11]
	s_mov_b32 m0, s20
	ds_read_b128 v[190:193], v152 offset:49152
	ds_read_b128 v[194:197], v152 offset:50176
	ds_read_b128 v[198:201], v152 offset:51200
	ds_read_b128 v[202:205], v152 offset:52224
	ds_read_b128 v[206:209], v152 offset:53248
	ds_read_b128 v[210:213], v152 offset:54272
	ds_read_b128 v[214:217], v152 offset:55296
	ds_read_b128 v[218:221], v152 offset:56320
	global_load_lds_dwordx4 v[144:145], off
	s_add_i32 m0, s20, 0x2000
	s_add_u32 s18, s18, 0x84080
	v_lshl_add_u64 v[144:145], v[166:167], 0, s[10:11]
	s_addc_u32 s19, s19, 0
	s_add_i32 s20, s55, s27
	global_load_lds_dwordx4 v[144:145], off
	v_lshl_add_u64 v[144:145], s[18:19], 0, v[132:133]
	s_mov_b32 m0, s20
	s_nop 0
	global_load_lds_dwordx4 v[144:145], off
	v_lshl_add_u64 v[144:145], s[18:19], 0, v[128:129]
	s_add_i32 m0, s20, 0x2000
	s_nop 0
	global_load_lds_dwordx4 v[144:145], off
	v_lshl_add_u64 v[144:145], v[222:223], 0, s[10:11]
	s_mov_b32 m0, s41
	s_nop 0
	global_load_lds_dwordx4 v[144:145], off
	v_lshl_add_u64 v[144:145], v[224:225], 0, s[10:11]
	s_mov_b32 m0, s42
	s_nop 0
	global_load_lds_dwordx4 v[144:145], off
	s_waitcnt vmcnt(8)
	s_waitcnt lgkmcnt(0)
	s_barrier
	s_setprio 1
	s_waitcnt lgkmcnt(0)
	v_mfma_f32_16x16x32_bf16 v[60:63], v[154:157], v[190:193], v[60:63]
	v_mfma_f32_16x16x32_bf16 v[60:63], v[158:161], v[194:197], v[60:63]
	v_mfma_f32_16x16x32_bf16 v[56:59], v[162:165], v[190:193], v[56:59]
	v_mfma_f32_16x16x32_bf16 v[56:59], v[170:173], v[194:197], v[56:59]
	v_mfma_f32_16x16x32_bf16 v[44:47], v[154:157], v[198:201], v[44:47]
	v_mfma_f32_16x16x32_bf16 v[44:47], v[158:161], v[202:205], v[44:47]
	v_mfma_f32_16x16x32_bf16 v[40:43], v[162:165], v[198:201], v[40:43]
	v_mfma_f32_16x16x32_bf16 v[40:43], v[170:173], v[202:205], v[40:43]
	v_mfma_f32_16x16x32_bf16 v[28:31], v[154:157], v[206:209], v[28:31]
	v_mfma_f32_16x16x32_bf16 v[28:31], v[158:161], v[210:213], v[28:31]
	v_mfma_f32_16x16x32_bf16 v[24:27], v[162:165], v[206:209], v[24:27]
	v_mfma_f32_16x16x32_bf16 v[24:27], v[170:173], v[210:213], v[24:27]
	v_mfma_f32_16x16x32_bf16 v[12:15], v[154:157], v[214:217], v[12:15]
	v_mfma_f32_16x16x32_bf16 v[12:15], v[158:161], v[218:221], v[12:15]
	v_mfma_f32_16x16x32_bf16 v[8:11], v[162:165], v[214:217], v[8:11]
	v_mfma_f32_16x16x32_bf16 v[8:11], v[170:173], v[218:221], v[8:11]
	s_setprio 0
	s_setprio 1
	v_mfma_f32_16x16x32_bf16 v[52:55], v[174:177], v[190:193], v[52:55]
	v_mfma_f32_16x16x32_bf16 v[52:55], v[178:181], v[194:197], v[52:55]
	v_mfma_f32_16x16x32_bf16 v[48:51], v[182:185], v[190:193], v[48:51]
	v_mfma_f32_16x16x32_bf16 v[48:51], v[186:189], v[194:197], v[48:51]
	v_mfma_f32_16x16x32_bf16 v[36:39], v[174:177], v[198:201], v[36:39]
	v_mfma_f32_16x16x32_bf16 v[36:39], v[178:181], v[202:205], v[36:39]
	v_mfma_f32_16x16x32_bf16 v[32:35], v[182:185], v[198:201], v[32:35]
	v_mfma_f32_16x16x32_bf16 v[32:35], v[186:189], v[202:205], v[32:35]
	v_mfma_f32_16x16x32_bf16 v[20:23], v[174:177], v[206:209], v[20:23]
	v_mfma_f32_16x16x32_bf16 v[20:23], v[178:181], v[210:213], v[20:23]
	v_mfma_f32_16x16x32_bf16 v[16:19], v[182:185], v[206:209], v[16:19]
	v_mfma_f32_16x16x32_bf16 v[16:19], v[186:189], v[210:213], v[16:19]
	v_mfma_f32_16x16x32_bf16 v[4:7], v[174:177], v[214:217], v[4:7]
	v_mfma_f32_16x16x32_bf16 v[4:7], v[178:181], v[218:221], v[4:7]
	v_mfma_f32_16x16x32_bf16 v[0:3], v[182:185], v[214:217], v[0:3]
	v_mfma_f32_16x16x32_bf16 v[0:3], v[186:189], v[218:221], v[0:3]
	s_setprio 0
	s_barrier
	s_add_i32 s53, s53, 2
	s_add_u32 s16, s16, 0x100
	s_addc_u32 s17, s17, 0
	s_add_u32 s51, s51, 0x100
	s_addc_u32 s52, s52, 0
	s_cmp_gt_u32 s53, 29
	s_cbranch_scc0 .LBB0_1156
	s_and_b64 vcc, exec, s[12:13]
	s_cbranch_vccz .LBB0_1159
	s_barrier

; #define PG8_STAGE(bufoff, gbase, voff) do { _Pragma("unroll") for (int _i = 0; _i < 2; ++_i) \
;         __builtin_amdgcn_global_load_lds((const unsigned*)((const char*)(gbase) + (voff)[_i]), (LAS unsigned*)(lds + (bufoff) + ldsw + _i * 8192), 16, 0, 0); } while (0)
; #define PG8_LDA(dst, b, h) do { _Pragma("unroll") for (int m = 0; m < 4; ++m) _Pragma("unroll") for (int k = 0; k < 2; ++k) dst[m][k] = *(const LAS bf16x8*)(lds + PG8_SA(b, h) + aoff + m * 2048 + k * 1024); } while (0)
; #define PG8_LDB(dst, b, h) do { _Pragma("unroll") for (int n = 0; n < 2; ++n) _Pragma("unroll") for (int k = 0; k < 2; ++k) dst[n][k] = *(const LAS bf16x8*)(lds + PG8_SB(b, h) + boff + n * 2048 + k * 1024); } while (0)
; #define PG8_MMA(ai, bj, At, Bt) do { __builtin_amdgcn_s_setprio(1); _Pragma("unroll") for (int m = 0; m < 4; ++m) _Pragma("unroll") for (int n = 0; n < 2; ++n) _Pragma("unroll") for (int k = 0; k < 2; ++k) \
;         acc[ai][bj][m][n] = __builtin_amdgcn_mfma_f32_16x16x32_bf16(Bt[n][k], At[m][k], acc[ai][bj][m][n], 0, 0, 0); __builtin_amdgcn_s_setprio(0); } while (0)
; #define PG8_WAIT_V(n) asm volatile("s_waitcnt vmcnt(" #n ")" ::: "memory")
; template <class EpiT>
; __device__ __forceinline__ void gemm_phase(LAS unsigned char* lds, const Gemm g, const StaticOrder& S, const EpiT& E) {
;     ...
;         const char* nA = has_next ? (const char*)g.A + (size_t)nxt.pm * tstepA + (size_t)nxt.pn * g.a_koff * 2 : cA; const char* nB = has_next ? (const char*)g.Bt + (size_t)nxt.pn * tstepB : cB;
;         for (int t = 0; t < nt; t += 2) {
;             const bool last = (t == nt - 2);
;             const char* a1 = cA + (size_t)(t + 1) * kstep;
;             const char* a2 = last ? nA : cA + (size_t)(t + 2) * kstep; const char* b2 = last ? nB : cB + (size_t)(t + 2) * kstep;
;             const char* a3 = a2 + kstep; const char* b3 = b2 + kstep;
;             PG8_LDB(B0, 0, 0); PG8_LDB(B1, 0, 1); PG8_SCHED; PG8_LDA(At, 0, 0); PG8_STAGE(PG8_SA(1, 1), a1 + hstepA, voffA);
;             PG8_WAIT_V(8); PG8_WAIT_L(0); PG8_BAR; PG8_MMA(0, 0, At, B0); PG8_MMA(0, 1, At, B1); PG8_BAR; PG8_SCHED;
;             PG8_LDA(At, 0, 1); PG8_STAGE(PG8_SB(0, 0), b2, voffB); PG8_STAGE(PG8_SB(0, 1), b2 + hstepB, voffB); PG8_STAGE(PG8_SA(0, 0), a2, voffA);
;             PG8_WAIT_V(8); PG8_WAIT_L(0); PG8_BAR; PG8_MMA(1, 0, At, B0); PG8_MMA(1, 1, At, B1); PG8_BAR; PG8_SCHED;
.LBB0_1235:
	ds_read_b128 v[154:157], v150
	ds_read_b128 v[158:161], v150 offset:1024
	ds_read_b128 v[162:165], v150 offset:2048
	ds_read_b128 v[170:173], v150 offset:3072
	ds_read_b128 v[174:177], v151
	ds_read_b128 v[178:181], v151 offset:1024
	ds_read_b128 v[182:185], v151 offset:2048
	ds_read_b128 v[186:189], v151 offset:3072
	s_add_u32 s20, s18, 0xffe9c080
	s_addc_u32 s21, s19, -1
	s_cmpk_eq_i32 s55, 0x54
	s_cselect_b32 s23, s5, s21
	s_cselect_b32 s22, s4, s20
	s_cselect_b32 s21, s17, s54
	s_cselect_b32 s20, s16, s53
	v_lshl_add_u64 v[166:167], s[18:19], 0, v[138:139]
	s_add_i32 m0, s37, 0xc000
	ds_read_b128 v[190:193], v152
	ds_read_b128 v[194:197], v152 offset:1024
	ds_read_b128 v[198:201], v152 offset:2048
	ds_read_b128 v[202:205], v152 offset:3072
	ds_read_b128 v[206:209], v152 offset:4096
	ds_read_b128 v[210:213], v152 offset:5120
	ds_read_b128 v[214:217], v152 offset:6144
	ds_read_b128 v[218:221], v152 offset:7168
	global_load_lds_dwordx4 v[166:167], off
	v_lshl_add_u64 v[166:167], s[18:19], 0, v[140:141]
	s_add_i32 m0, s37, 0xe000
	s_nop 0
	global_load_lds_dwordx4 v[166:167], off
	s_waitcnt vmcnt(8)
	s_waitcnt lgkmcnt(0)
	s_barrier
	s_setprio 1
	s_waitcnt lgkmcnt(0)
	v_mfma_f32_16x16x32_bf16 v[124:127], v[154:157], v[190:193], v[124:127]
	v_mfma_f32_16x16x32_bf16 v[124:127], v[158:161], v[194:197], v[124:127]
	v_mfma_f32_16x16x32_bf16 v[120:123], v[162:165], v[190:193], v[120:123]
	v_mfma_f32_16x16x32_bf16 v[120:123], v[170:173], v[194:197], v[120:123]
	v_mfma_f32_16x16x32_bf16 v[108:111], v[154:157], v[198:201], v[108:111]
	v_mfma_f32_16x16x32_bf16 v[108:111], v[158:161], v[202:205], v[108:111]
	v_mfma_f32_16x16x32_bf16 v[104:107], v[162:165], v[198:201], v[104:107]
	v_mfma_f32_16x16x32_bf16 v[104:107], v[170:173], v[202:205], v[104:107]
	v_mfma_f32_16x16x32_bf16 v[92:95], v[154:157], v[206:209], v[92:95]
	v_mfma_f32_16x16x32_bf16 v[92:95], v[158:161], v[210:213], v[92:95]
	v_mfma_f32_16x16x32_bf16 v[88:91], v[162:165], v[206:209], v[88:91]
	v_mfma_f32_16x16x32_bf16 v[88:91], v[170:173], v[210:213], v[88:91]
	v_mfma_f32_16x16x32_bf16 v[76:79], v[154:157], v[214:217], v[76:79]
	v_mfma_f32_16x16x32_bf16 v[76:79], v[158:161], v[218:221], v[76:79]
	v_mfma_f32_16x16x32_bf16 v[72:75], v[162:165], v[214:217], v[72:75]
	v_mfma_f32_16x16x32_bf16 v[72:75], v[170:173], v[218:221], v[72:75]
	s_setprio 0
	s_setprio 1
	v_mfma_f32_16x16x32_bf16 v[116:119], v[174:177], v[190:193], v[116:119]
	v_mfma_f32_16x16x32_bf16 v[116:119], v[178:181], v[194:197], v[116:119]
	v_mfma_f32_16x16x32_bf16 v[112:115], v[182:185], v[190:193], v[112:115]
	v_mfma_f32_16x16x32_bf16 v[112:115], v[186:189], v[194:197], v[112:115]
	v_mfma_f32_16x16x32_bf16 v[100:103], v[174:177], v[198:201], v[100:103]
	v_mfma_f32_16x16x32_bf16 v[100:103], v[178:181], v[202:205], v[100:103]
	v_mfma_f32_16x16x32_bf16 v[96:99], v[182:185], v[198:201], v[96:99]
	v_mfma_f32_16x16x32_bf16 v[96:99], v[186:189], v[202:205], v[96:99]
	v_mfma_f32_16x16x32_bf16 v[84:87], v[174:177], v[206:209], v[84:87]
	v_mfma_f32_16x16x32_bf16 v[84:87], v[178:181], v[210:213], v[84:87]
	v_mfma_f32_16x16x32_bf16 v[80:83], v[182:185], v[206:209], v[80:83]
	v_mfma_f32_16x16x32_bf16 v[80:83], v[186:189], v[210:213], v[80:83]
	v_mfma_f32_16x16x32_bf16 v[68:71], v[174:177], v[214:217], v[68:71]
	v_mfma_f32_16x16x32_bf16 v[68:71], v[178:181], v[218:221], v[68:71]
	v_mfma_f32_16x16x32_bf16 v[64:67], v[182:185], v[214:217], v[64:67]
	v_mfma_f32_16x16x32_bf16 v[64:67], v[186:189], v[218:221], v[64:67]
	s_setprio 0
	s_barrier
	s_add_i32 s56, s46, s36
	v_lshl_add_u64 v[166:167], s[20:21], 0, v[130:131]
	s_mov_b32 m0, s56
	ds_read_b128 v[190:193], v152 offset:16384
	ds_read_b128 v[194:197], v152 offset:17408
	ds_read_b128 v[198:201], v152 offset:18432
	ds_read_b128 v[202:205], v152 offset:19456
	ds_read_b128 v[206:209], v152 offset:20480
	ds_read_b128 v[210:213], v152 offset:21504
	ds_read_b128 v[214:217], v152 offset:22528
	ds_read_b128 v[218:221], v152 offset:23552
	global_load_lds_dwordx4 v[166:167], off
	s_add_i32 m0, s56, 0x2000
	s_add_u32 s56, s20, 0x164000
	v_lshl_add_u64 v[222:223], s[20:21], 0, v[134:135]
	s_addc_u32 s57, s21, 0
	s_add_i32 s58, s47, s36
	global_load_lds_dwordx4 v[222:223], off
	v_lshl_add_u64 v[224:225], s[56:57], 0, v[130:131]
	s_mov_b32 m0, s58
	v_lshl_add_u64 v[226:227], s[22:23], 0, v[132:133]
	global_load_lds_dwordx4 v[224:225], off
	v_lshl_add_u64 v[224:225], s[56:57], 0, v[134:135]
	s_add_i32 m0, s58, 0x2000
	s_nop 0
	global_load_lds_dwordx4 v[224:225], off
	v_lshl_add_u64 v[224:225], s[22:23], 0, v[128:129]
	s_mov_b32 m0, s37
	s_nop 0
	global_load_lds_dwordx4 v[224:225], off
	s_mov_b32 m0, s38
	s_nop 0
	global_load_lds_dwordx4 v[226:227], off
	s_waitcnt vmcnt(8)
	s_waitcnt lgkmcnt(0)
	s_barrier
; #define PG8_STAGE(bufoff, gbase, voff) do { _Pragma("unroll") for (int _i = 0; _i < 2; ++_i) \
;         __builtin_amdgcn_global_load_lds((const unsigned*)((const char*)(gbase) + (voff)[_i]), (LAS unsigned*)(lds + (bufoff) + ldsw + _i * 8192), 16, 0, 0); } while (0)
; #define PG8_LDA(dst, b, h) do { _Pragma("unroll") for (int m = 0; m < 4; ++m) _Pragma("unroll") for (int k = 0; k < 2; ++k) dst[m][k] = *(const LAS bf16x8*)(lds + PG8_SA(b, h) + aoff + m * 2048 + k * 1024); } while (0)
; #define PG8_LDB(dst, b, h) do { _Pragma("unroll") for (int n = 0; n < 2; ++n) _Pragma("unroll") for (int k = 0; k < 2; ++k) dst[n][k] = *(const LAS bf16x8*)(lds + PG8_SB(b, h) + boff + n * 2048 + k * 1024); } while (0)
; #define PG8_MMA(ai, bj, At, Bt) do { __builtin_amdgcn_s_setprio(1); _Pragma("unroll") for (int m = 0; m < 4; ++m) _Pragma("unroll") for (int n = 0; n < 2; ++n) _Pragma("unroll") for (int k = 0; k < 2; ++k) \
;         acc[ai][bj][m][n] = __builtin_amdgcn_mfma_f32_16x16x32_bf16(Bt[n][k], At[m][k], acc[ai][bj][m][n], 0, 0, 0); __builtin_amdgcn_s_setprio(0); } while (0)
; #define PG8_WAIT_V(n) asm volatile("s_waitcnt vmcnt(" #n ")" ::: "memory")
; #define PG8_WAIT_L(n) asm volatile("s_waitcnt lgkmcnt(" #n ")" ::: "memory")
; #define PG8_BAR __builtin_amdgcn_s_barrier()
; #define PG8_SCHED __builtin_amdgcn_sched_barrier(0)
; template <class EpiT>
; __device__ __forceinline__ void gemm_phase(LAS unsigned char* lds, const Gemm g, const StaticOrder& S, const EpiT& E) {
;     ...
;             PG8_WAIT_V(8); PG8_WAIT_L(0); PG8_BAR; PG8_MMA(1, 0, At, B0); PG8_MMA(1, 1, At, B1); PG8_BAR; PG8_SCHED;
;             PG8_LDB(B0, 1, 0); PG8_LDB(B1, 1, 1); PG8_SCHED; PG8_LDA(At, 1, 0); PG8_STAGE(PG8_SA(0, 1), a2 + hstepA, voffA);
;             PG8_WAIT_V(8); PG8_WAIT_L(0); PG8_BAR; PG8_MMA(0, 0, At, B0); PG8_MMA(0, 1, At, B1); PG8_BAR; PG8_SCHED;
	s_setprio 1
	s_waitcnt lgkmcnt(0)
	v_mfma_f32_16x16x32_bf16 v[60:63], v[154:157], v[190:193], v[60:63]
	v_mfma_f32_16x16x32_bf16 v[60:63], v[158:161], v[194:197], v[60:63]
	v_mfma_f32_16x16x32_bf16 v[56:59], v[162:165], v[190:193], v[56:59]
	v_mfma_f32_16x16x32_bf16 v[56:59], v[170:173], v[194:197], v[56:59]
	v_mfma_f32_16x16x32_bf16 v[44:47], v[154:157], v[198:201], v[44:47]
	v_mfma_f32_16x16x32_bf16 v[44:47], v[158:161], v[202:205], v[44:47]
	v_mfma_f32_16x16x32_bf16 v[40:43], v[162:165], v[198:201], v[40:43]
	v_mfma_f32_16x16x32_bf16 v[40:43], v[170:173], v[202:205], v[40:43]
	v_mfma_f32_16x16x32_bf16 v[28:31], v[154:157], v[206:209], v[28:31]
	v_mfma_f32_16x16x32_bf16 v[28:31], v[158:161], v[210:213], v[28:31]
	v_mfma_f32_16x16x32_bf16 v[24:27], v[162:165], v[206:209], v[24:27]
	v_mfma_f32_16x16x32_bf16 v[24:27], v[170:173], v[210:213], v[24:27]
	v_mfma_f32_16x16x32_bf16 v[12:15], v[154:157], v[214:217], v[12:15]
	v_mfma_f32_16x16x32_bf16 v[12:15], v[158:161], v[218:221], v[12:15]
	v_mfma_f32_16x16x32_bf16 v[8:11], v[162:165], v[214:217], v[8:11]
	v_mfma_f32_16x16x32_bf16 v[8:11], v[170:173], v[218:221], v[8:11]
	s_setprio 0
	s_setprio 1
	v_mfma_f32_16x16x32_bf16 v[52:55], v[174:177], v[190:193], v[52:55]
	v_mfma_f32_16x16x32_bf16 v[52:55], v[178:181], v[194:197], v[52:55]
	v_mfma_f32_16x16x32_bf16 v[48:51], v[182:185], v[190:193], v[48:51]
	v_mfma_f32_16x16x32_bf16 v[48:51], v[186:189], v[194:197], v[48:51]
	v_mfma_f32_16x16x32_bf16 v[36:39], v[174:177], v[198:201], v[36:39]
	v_mfma_f32_16x16x32_bf16 v[36:39], v[178:181], v[202:205], v[36:39]
	v_mfma_f32_16x16x32_bf16 v[32:35], v[182:185], v[198:201], v[32:35]
	v_mfma_f32_16x16x32_bf16 v[32:35], v[186:189], v[202:205], v[32:35]
	v_mfma_f32_16x16x32_bf16 v[20:23], v[174:177], v[206:209], v[20:23]
	v_mfma_f32_16x16x32_bf16 v[20:23], v[178:181], v[210:213], v[20:23]
	v_mfma_f32_16x16x32_bf16 v[16:19], v[182:185], v[206:209], v[16:19]
	v_mfma_f32_16x16x32_bf16 v[16:19], v[186:189], v[210:213], v[16:19]
	v_mfma_f32_16x16x32_bf16 v[4:7], v[174:177], v[214:217], v[4:7]
	v_mfma_f32_16x16x32_bf16 v[4:7], v[178:181], v[218:221], v[4:7]
	v_mfma_f32_16x16x32_bf16 v[0:3], v[182:185], v[214:217], v[0:3]
	v_mfma_f32_16x16x32_bf16 v[0:3], v[186:189], v[218:221], v[0:3]
	s_setprio 0
	s_barrier
	s_add_i32 s56, 0, 0x18000
	s_add_i32 s57, 0, 0x1c000
	v_add_u32_e32 v170, s56, v146
	v_add_u32_e32 v186, s57, v146
	ds_read_b128 v[154:157], v170
	ds_read_b128 v[158:161], v170 offset:1024
	ds_read_b128 v[162:165], v170 offset:2048
	ds_read_b128 v[170:173], v170 offset:3072
	ds_read_b128 v[174:177], v186
	ds_read_b128 v[178:181], v186 offset:1024
	ds_read_b128 v[182:185], v186 offset:2048
	ds_read_b128 v[186:189], v186 offset:3072
	s_add_u32 s22, s22, 0x164000
	s_addc_u32 s23, s23, 0
	s_mov_b32 m0, s39
	v_lshl_add_u64 v[228:229], s[22:23], 0, v[128:129]
	ds_read_b128 v[190:193], v152 offset:32768
	ds_read_b128 v[194:197], v152 offset:33792
	ds_read_b128 v[198:201], v152 offset:34816
	ds_read_b128 v[202:205], v152 offset:35840
	ds_read_b128 v[206:209], v152 offset:36864
	ds_read_b128 v[210:213], v152 offset:37888
	ds_read_b128 v[214:217], v152 offset:38912
	ds_read_b128 v[218:221], v152 offset:39936
	global_load_lds_dwordx4 v[228:229], off
	v_lshl_add_u64 v[228:229], s[22:23], 0, v[132:133]
	s_mov_b32 m0, s40
	s_nop 0
	global_load_lds_dwordx4 v[228:229], off
	s_waitcnt vmcnt(8)
	s_waitcnt lgkmcnt(0)
	s_barrier
	s_setprio 1
	s_waitcnt lgkmcnt(0)
	v_mfma_f32_16x16x32_bf16 v[124:127], v[154:157], v[190:193], v[124:127]
	v_mfma_f32_16x16x32_bf16 v[124:127], v[158:161], v[194:197], v[124:127]
	v_mfma_f32_16x16x32_bf16 v[120:123], v[162:165], v[190:193], v[120:123]
	v_mfma_f32_16x16x32_bf16 v[120:123], v[170:173], v[194:197], v[120:123]
	v_mfma_f32_16x16x32_bf16 v[108:111], v[154:157], v[198:201], v[108:111]
	v_mfma_f32_16x16x32_bf16 v[108:111], v[158:161], v[202:205], v[108:111]
	v_mfma_f32_16x16x32_bf16 v[104:107], v[162:165], v[198:201], v[104:107]
	v_mfma_f32_16x16x32_bf16 v[104:107], v[170:173], v[202:205], v[104:107]
	v_mfma_f32_16x16x32_bf16 v[92:95], v[154:157], v[206:209], v[92:95]
	v_mfma_f32_16x16x32_bf16 v[92:95], v[158:161], v[210:213], v[92:95]
	v_mfma_f32_16x16x32_bf16 v[88:91], v[162:165], v[206:209], v[88:91]
	v_mfma_f32_16x16x32_bf16 v[88:91], v[170:173], v[210:213], v[88:91]
	v_mfma_f32_16x16x32_bf16 v[76:79], v[154:157], v[214:217], v[76:79]
	v_mfma_f32_16x16x32_bf16 v[76:79], v[158:161], v[218:221], v[76:79]
	v_mfma_f32_16x16x32_bf16 v[72:75], v[162:165], v[214:217], v[72:75]
	v_mfma_f32_16x16x32_bf16 v[72:75], v[170:173], v[218:221], v[72:75]
	s_setprio 0
	s_setprio 1
	v_mfma_f32_16x16x32_bf16 v[116:119], v[174:177], v[190:193], v[116:119]
	v_mfma_f32_16x16x32_bf16 v[116:119], v[178:181], v[194:197], v[116:119]
	v_mfma_f32_16x16x32_bf16 v[112:115], v[182:185], v[190:193], v[112:115]
	v_mfma_f32_16x16x32_bf16 v[112:115], v[186:189], v[194:197], v[112:115]
	v_mfma_f32_16x16x32_bf16 v[100:103], v[174:177], v[198:201], v[100:103]
	v_mfma_f32_16x16x32_bf16 v[100:103], v[178:181], v[202:205], v[100:103]
	v_mfma_f32_16x16x32_bf16 v[96:99], v[182:185], v[198:201], v[96:99]
	v_mfma_f32_16x16x32_bf16 v[96:99], v[186:189], v[202:205], v[96:99]
	v_mfma_f32_16x16x32_bf16 v[84:87], v[174:177], v[206:209], v[84:87]
	v_mfma_f32_16x16x32_bf16 v[84:87], v[178:181], v[210:213], v[84:87]
	v_mfma_f32_16x16x32_bf16 v[80:83], v[182:185], v[206:209], v[80:83]
	v_mfma_f32_16x16x32_bf16 v[80:83], v[186:189], v[210:213], v[80:83]
	v_mfma_f32_16x16x32_bf16 v[68:71], v[174:177], v[214:217], v[68:71]
	v_mfma_f32_16x16x32_bf16 v[68:71], v[178:181], v[218:221], v[68:71]
	v_mfma_f32_16x16x32_bf16 v[64:67], v[182:185], v[214:217], v[64:67]
	v_mfma_f32_16x16x32_bf16 v[64:67], v[186:189], v[218:221], v[64:67]
	s_setprio 0
	s_barrier
; #define PG8_STAGE(bufoff, gbase, voff) do { _Pragma("unroll") for (int _i = 0; _i < 2; ++_i) \
;         __builtin_amdgcn_global_load_lds((const unsigned*)((const char*)(gbase) + (voff)[_i]), (LAS unsigned*)(lds + (bufoff) + ldsw + _i * 8192), 16, 0, 0); } while (0)
; #define PG8_LDA(dst, b, h) do { _Pragma("unroll") for (int m = 0; m < 4; ++m) _Pragma("unroll") for (int k = 0; k < 2; ++k) dst[m][k] = *(const LAS bf16x8*)(lds + PG8_SA(b, h) + aoff + m * 2048 + k * 1024); } while (0)
; #define PG8_MMA(ai, bj, At, Bt) do { __builtin_amdgcn_s_setprio(1); _Pragma("unroll") for (int m = 0; m < 4; ++m) _Pragma("unroll") for (int n = 0; n < 2; ++n) _Pragma("unroll") for (int k = 0; k < 2; ++k) \
;         acc[ai][bj][m][n] = __builtin_amdgcn_mfma_f32_16x16x32_bf16(Bt[n][k], At[m][k], acc[ai][bj][m][n], 0, 0, 0); __builtin_amdgcn_s_setprio(0); } while (0)
; #define PG8_WAIT_V(n) asm volatile("s_waitcnt vmcnt(" #n ")" ::: "memory")
; #define PG8_WAIT_L(n) asm volatile("s_waitcnt lgkmcnt(" #n ")" ::: "memory")
; #define PG8_BAR __builtin_amdgcn_s_barrier()
; #define PG8_SCHED __builtin_amdgcn_sched_barrier(0)
; template <class EpiT>
; __device__ __forceinline__ void gemm_phase(LAS unsigned char* lds, const Gemm g, const StaticOrder& S, const EpiT& E) {
;     ...
;             PG8_LDA(At, 1, 1); PG8_STAGE(PG8_SB(1, 0), b3, voffB); PG8_STAGE(PG8_SB(1, 1), b3 + hstepB, voffB); PG8_STAGE(PG8_SA(1, 0), a3, voffA);
;             PG8_WAIT_V(8); PG8_WAIT_L(0); PG8_BAR; PG8_MMA(1, 0, At, B0); PG8_MMA(1, 1, At, B1); PG8_BAR; PG8_SCHED;
;         }
;         if (wr == 0) PG8_BAR;
	s_add_i32 s22, s56, s36
	v_lshl_add_u64 v[166:167], v[166:167], 0, s[12:13]
	s_mov_b32 m0, s22
	ds_read_b128 v[190:193], v152 offset:49152
	ds_read_b128 v[194:197], v152 offset:50176
	ds_read_b128 v[198:201], v152 offset:51200
	ds_read_b128 v[202:205], v152 offset:52224
	ds_read_b128 v[206:209], v152 offset:53248
	ds_read_b128 v[210:213], v152 offset:54272
	ds_read_b128 v[214:217], v152 offset:55296
	ds_read_b128 v[218:221], v152 offset:56320
	global_load_lds_dwordx4 v[166:167], off
	s_add_i32 m0, s22, 0x2000
	s_add_u32 s20, s20, 0x164080
	v_lshl_add_u64 v[166:167], v[222:223], 0, s[12:13]
	s_addc_u32 s21, s21, 0
	s_add_i32 s22, s57, s36
	global_load_lds_dwordx4 v[166:167], off
	v_lshl_add_u64 v[166:167], s[20:21], 0, v[130:131]
	s_mov_b32 m0, s22
	s_nop 0
	global_load_lds_dwordx4 v[166:167], off
	v_lshl_add_u64 v[166:167], s[20:21], 0, v[134:135]
	s_add_i32 m0, s22, 0x2000
	s_nop 0
	global_load_lds_dwordx4 v[166:167], off
	v_lshl_add_u64 v[166:167], v[224:225], 0, s[12:13]
	s_mov_b32 m0, s42
	s_nop 0
	global_load_lds_dwordx4 v[166:167], off
	v_lshl_add_u64 v[166:167], v[226:227], 0, s[12:13]
	s_mov_b32 m0, s43
	s_nop 0
	global_load_lds_dwordx4 v[166:167], off
	s_waitcnt vmcnt(8)
	s_waitcnt lgkmcnt(0)
	s_barrier
	s_setprio 1
	s_waitcnt lgkmcnt(0)
	v_mfma_f32_16x16x32_bf16 v[60:63], v[154:157], v[190:193], v[60:63]
	v_mfma_f32_16x16x32_bf16 v[60:63], v[158:161], v[194:197], v[60:63]
	v_mfma_f32_16x16x32_bf16 v[56:59], v[162:165], v[190:193], v[56:59]
	v_mfma_f32_16x16x32_bf16 v[56:59], v[170:173], v[194:197], v[56:59]
	v_mfma_f32_16x16x32_bf16 v[44:47], v[154:157], v[198:201], v[44:47]
	v_mfma_f32_16x16x32_bf16 v[44:47], v[158:161], v[202:205], v[44:47]
	v_mfma_f32_16x16x32_bf16 v[40:43], v[162:165], v[198:201], v[40:43]
	v_mfma_f32_16x16x32_bf16 v[40:43], v[170:173], v[202:205], v[40:43]
	v_mfma_f32_16x16x32_bf16 v[28:31], v[154:157], v[206:209], v[28:31]
	v_mfma_f32_16x16x32_bf16 v[28:31], v[158:161], v[210:213], v[28:31]
	v_mfma_f32_16x16x32_bf16 v[24:27], v[162:165], v[206:209], v[24:27]
	v_mfma_f32_16x16x32_bf16 v[24:27], v[170:173], v[210:213], v[24:27]
	v_mfma_f32_16x16x32_bf16 v[12:15], v[154:157], v[214:217], v[12:15]
	v_mfma_f32_16x16x32_bf16 v[12:15], v[158:161], v[218:221], v[12:15]
	v_mfma_f32_16x16x32_bf16 v[8:11], v[162:165], v[214:217], v[8:11]
	v_mfma_f32_16x16x32_bf16 v[8:11], v[170:173], v[218:221], v[8:11]
	s_setprio 0
	s_setprio 1
	v_mfma_f32_16x16x32_bf16 v[52:55], v[174:177], v[190:193], v[52:55]
	v_mfma_f32_16x16x32_bf16 v[52:55], v[178:181], v[194:197], v[52:55]
	v_mfma_f32_16x16x32_bf16 v[48:51], v[182:185], v[190:193], v[48:51]
	v_mfma_f32_16x16x32_bf16 v[48:51], v[186:189], v[194:197], v[48:51]
	v_mfma_f32_16x16x32_bf16 v[36:39], v[174:177], v[198:201], v[36:39]
	v_mfma_f32_16x16x32_bf16 v[36:39], v[178:181], v[202:205], v[36:39]
	v_mfma_f32_16x16x32_bf16 v[32:35], v[182:185], v[198:201], v[32:35]
	v_mfma_f32_16x16x32_bf16 v[32:35], v[186:189], v[202:205], v[32:35]
	v_mfma_f32_16x16x32_bf16 v[20:23], v[174:177], v[206:209], v[20:23]
	v_mfma_f32_16x16x32_bf16 v[20:23], v[178:181], v[210:213], v[20:23]
	v_mfma_f32_16x16x32_bf16 v[16:19], v[182:185], v[206:209], v[16:19]
	v_mfma_f32_16x16x32_bf16 v[16:19], v[186:189], v[210:213], v[16:19]
	v_mfma_f32_16x16x32_bf16 v[4:7], v[174:177], v[214:217], v[4:7]
	v_mfma_f32_16x16x32_bf16 v[4:7], v[178:181], v[218:221], v[4:7]
	v_mfma_f32_16x16x32_bf16 v[0:3], v[182:185], v[214:217], v[0:3]
	v_mfma_f32_16x16x32_bf16 v[0:3], v[186:189], v[218:221], v[0:3]
	s_setprio 0
	s_barrier
	s_add_i32 s55, s55, 2
	s_add_u32 s18, s18, 0x100
	s_addc_u32 s19, s19, 0
	s_add_u32 s53, s53, 0x100
	s_addc_u32 s54, s54, 0
	s_cmpk_gt_u32 s55, 0x55
	s_cbranch_scc0 .LBB0_1235
	s_and_b64 vcc, exec, s[14:15]
	s_cbranch_vccz .LBB0_1238
	s_barrier
